# s_setprio strategy step (b): per-segment priority flips deleted from the four hand-written K-loops
# baseline (speedup 1.0000x reference)
.LBB0_127:
	s_add_i32 s42, s16, s46
	s_cmpk_gt_i32 s42, 0xb27
	s_mov_b64 s[40:41], -1
	s_cbranch_scc1 .LBB0_126
	s_mul_hi_i32 s40, s42, 0x30c30c31
	s_lshr_b32 s41, s40, 31
	s_ashr_i32 s40, s40, 7
	s_add_i32 s54, s40, s41
	s_mul_i32 s40, s54, 0xfffffd60
	s_lshl_b32 s43, s54, 3
	s_add_i32 s41, s40, s42
	s_sub_i32 s40, 34, s43
	s_cmpk_gt_i32 s42, 0xa7f
	s_cselect_b32 s42, s40, 8
	s_abs_i32 s40, s42
	v_cvt_f32_u32_e32 v0, s40
	s_sub_i32 s50, 0, s40
	s_abs_i32 s44, s41
	s_xor_b32 s45, s41, s42
	v_rcp_iflag_f32_e32 v0, v0
	s_ashr_i32 s45, s45, 31
	v_mov_b32_e32 v8, v204
	v_mul_f32_e32 v0, 0x4f7ffffe, v0
	v_cvt_u32_f32_e32 v0, v0
	v_bfe_u32 v2, v8, 2, 4
	v_ashrrev_i32_e32 v1, 6, v8
	v_lshlrev_b32_e32 v3, 16, v1
	v_readfirstlane_b32 s51, v0
	s_mul_i32 s50, s50, s51
	s_mul_hi_u32 s50, s51, s50
	s_add_i32 s51, s51, s50
	s_mul_hi_u32 s50, s44, s51
	s_mul_i32 s51, s50, s40
	s_sub_i32 s44, s44, s51
	s_add_i32 s52, s50, 1
	s_sub_i32 s51, s44, s40
	s_cmp_ge_u32 s44, s40
	s_cselect_b32 s50, s52, s50
	s_cselect_b32 s44, s51, s44
	s_add_i32 s51, s50, 1
	s_cmp_ge_u32 s44, s40
	s_cselect_b32 s40, s51, s50
	s_xor_b32 s40, s40, s45
	s_sub_i32 s40, s40, s45
	s_mul_i32 s55, s42, s40
	s_add_i32 s41, s41, s43
	s_sub_i32 s42, s41, s55
	s_ashr_i32 s43, s42, 31
	s_lshl_b64 s[44:45], s[42:43], 20
	s_add_u32 s50, s23, s44
	s_addc_u32 s51, s28, s45
	s_ashr_i32 s41, s40, 31
	v_bfe_u32 v0, v8, 4, 2
	s_lshl_b64 s[44:45], s[40:41], 19
	v_bitop3_b32 v0, v0, v8, 3 bitop3:0x78
	s_mov_b32 s41, 0x1fffc0
	v_lshlrev_b32_e32 v9, 3, v0
	v_and_or_b32 v0, v8, s41, v2
	v_lshl_or_b32 v0, v0, 11, v9
	v_lshl_add_u32 v165, v1, 12, 32
	v_lshlrev_b32_e32 v1, 11, v1
	v_sub_u32_e32 v166, v165, v1
	v_ashrrev_i32_e32 v1, 31, v0
	v_readfirstlane_b32 s41, v165
	v_add_u32_e32 v12, 0x400, v165
	v_lshlrev_b32_e32 v10, 11, v2
	v_lshl_add_u64 v[0:1], v[0:1], 1, s[50:51]
	s_mov_b32 m0, s41
	v_readfirstlane_b32 s41, v12
	v_add_u32_e32 v12, 0x800, v165
	v_or3_b32 v2, v10, v3, v9
	global_load_lds_dwordx4 v[0:1], off
	v_lshl_add_u64 v[6:7], v[0:1], 0, s[6:7]
	s_mov_b32 m0, s41
	s_mov_b64 s[50:51], 0x20000
	v_readfirstlane_b32 s41, v12
	v_add_u32_e32 v12, 0xc00, v165
	s_add_u32 s52, s29, s44
	v_add_u32_e32 v11, 0x4000, v166
	v_ashrrev_i32_e32 v3, 31, v2
	global_load_lds_dwordx4 v[6:7], off
	v_lshl_add_u64 v[6:7], v[0:1], 0, s[50:51]
	s_mov_b32 m0, s41
	s_mov_b64 s[50:51], 0x30000
	v_readfirstlane_b32 s41, v12
	s_addc_u32 s53, s30, s45
	v_lshlrev_b64 v[2:3], 1, v[2:3]
	v_lshrrev_b32_e32 v240, 4, v10
	v_add_u32_e32 v2, v2, v240
	global_load_lds_dwordx4 v[6:7], off
	v_lshl_add_u64 v[6:7], v[0:1], 0, s[50:51]
	s_mov_b32 m0, s41
	v_readfirstlane_b32 s41, v11
	v_add_u32_e32 v11, 0x4400, v166
	v_lshl_add_u64 v[4:5], s[52:53], 0, v[2:3]
	global_load_lds_dwordx4 v[6:7], off
	s_mov_b32 m0, s41
	v_readfirstlane_b32 s41, v11
	v_add_u32_e32 v11, 0x6000, v165
	global_load_lds_dwordx4 v[4:5], off
	s_mov_b64 s[50:51], 0x10800
	v_lshl_add_u64 v[6:7], v[4:5], 0, s[50:51]
	s_mov_b32 m0, s41
	v_readfirstlane_b32 s41, v11
	v_add_u32_e32 v11, 0x6400, v165
	global_load_lds_dwordx4 v[6:7], off
	v_lshl_add_u64 v[6:7], v[0:1], 0, 64
	s_mov_b32 m0, s41
	v_readfirstlane_b32 s41, v11
	v_add_u32_e32 v11, 0x6800, v165
	global_load_lds_dwordx4 v[6:7], off
	v_lshl_add_u64 v[6:7], v[0:1], 0, s[8:9]
	s_mov_b32 m0, s41
	s_mov_b64 s[50:51], 0x20040
	v_readfirstlane_b32 s41, v11
	global_load_lds_dwordx4 v[6:7], off
	v_lshl_add_u64 v[6:7], v[0:1], 0, s[50:51]
	s_mov_b32 m0, s41
	s_mov_b64 s[50:51], 0x30040
	global_load_lds_dwordx4 v[6:7], off
	v_add_u32_e32 v6, 0x6c00, v165
	v_lshl_add_u64 v[0:1], v[0:1], 0, s[50:51]
	v_readfirstlane_b32 s41, v6
	v_add_u32_e32 v6, 0xa000, v166
	s_mov_b32 m0, s41
	v_readfirstlane_b32 s41, v6
	global_load_lds_dwordx4 v[0:1], off
	v_lshl_add_u64 v[0:1], v[4:5], 0, 64
	s_mov_b32 m0, s41
	s_add_u32 s44, s94, s44
	global_load_lds_dwordx4 v[0:1], off
	s_mov_b64 s[50:51], 0x10840
	v_lshl_add_u64 v[0:1], v[4:5], 0, s[50:51]
	v_add_u32_e32 v4, 0xa400, v166
	s_addc_u32 s45, s95, s45
	v_readfirstlane_b32 s41, v4
	s_mov_b32 m0, s41
	v_bfe_u32 v4, v8, 2, 2
	global_load_lds_dwordx4 v[0:1], off
	v_bfe_u32 v0, v8, 5, 1
	v_lshrrev_b32_e32 v1, 2, v8
	s_sub_i32 s41, s47, s55
	s_mulk_i32 s54, 0x298
	v_bitop3_b32 v1, v0, v1, 3 bitop3:0x78
	v_bitop3_b32 v0, v0, v4, 2 bitop3:0x36
	v_lshl_add_u64 v[130:131], s[44:45], 0, v[2:3]
	s_sub_i32 s44, s41, s54
	v_lshlrev_b32_e32 v128, 4, v0
	s_ashr_i32 s45, s44, 31
	v_lshlrev_b32_e32 v0, 11, v8
	s_lshl_b64 s[44:45], s[44:45], 20
	v_and_b32_e32 v0, 0xfffe0000, v0
	v_or3_b32 v0, v0, v10, v9
	s_add_u32 s44, s94, s44
	v_lshlrev_b32_e32 v167, 4, v1
	v_ashrrev_i32_e32 v1, 31, v0
	s_addc_u32 s45, s95, s45
	v_lshlrev_b32_e32 v5, 6, v8
	v_lshl_add_u64 v[132:133], v[0:1], 1, s[44:45]
	v_mov_b32_e32 v0, 0
	s_mov_b32 s49, 0
	v_and_b32_e32 v168, 0xffffe7c0, v5
	v_and_b32_e32 v169, 0x17c0, v5
	s_mov_b64 s[44:45], 0
	v_mov_b32_e32 v1, v0
	v_mov_b32_e32 v2, v0
	v_mov_b32_e32 v3, v0
	v_mov_b32_e32 v4, v0
	v_mov_b32_e32 v5, v0
	v_mov_b32_e32 v6, v0
	v_mov_b32_e32 v7, v0
	v_mov_b32_e32 v8, v0
	v_mov_b32_e32 v9, v0
	v_mov_b32_e32 v10, v0
	v_mov_b32_e32 v11, v0
	v_mov_b32_e32 v12, v0
	v_mov_b32_e32 v13, v0
	v_mov_b32_e32 v14, v0
	v_mov_b32_e32 v15, v0
	v_mov_b32_e32 v16, v0
	v_mov_b32_e32 v17, v0
	v_mov_b32_e32 v18, v0
	v_mov_b32_e32 v19, v0
	v_mov_b32_e32 v20, v0
	v_mov_b32_e32 v21, v0
	v_mov_b32_e32 v22, v0
	v_mov_b32_e32 v23, v0
	v_mov_b32_e32 v24, v0
	v_mov_b32_e32 v25, v0
	v_mov_b32_e32 v26, v0
	v_mov_b32_e32 v27, v0
	v_mov_b32_e32 v28, v0
	v_mov_b32_e32 v29, v0
	v_mov_b32_e32 v30, v0
	v_mov_b32_e32 v31, v0
	v_mov_b32_e32 v32, v0
	v_mov_b32_e32 v33, v0
	v_mov_b32_e32 v34, v0
	v_mov_b32_e32 v35, v0
	v_mov_b32_e32 v36, v0
	v_mov_b32_e32 v37, v0
	v_mov_b32_e32 v38, v0
	v_mov_b32_e32 v39, v0
	v_mov_b32_e32 v40, v0
	v_mov_b32_e32 v41, v0
	v_mov_b32_e32 v42, v0
	v_mov_b32_e32 v43, v0
	v_mov_b32_e32 v44, v0
	v_mov_b32_e32 v45, v0
	v_mov_b32_e32 v46, v0
	v_mov_b32_e32 v47, v0
	v_mov_b32_e32 v48, v0
	v_mov_b32_e32 v49, v0
	v_mov_b32_e32 v50, v0
	v_mov_b32_e32 v51, v0
	v_mov_b32_e32 v52, v0
	v_mov_b32_e32 v53, v0
	v_mov_b32_e32 v54, v0
	v_mov_b32_e32 v55, v0
	v_mov_b32_e32 v56, v0
	v_mov_b32_e32 v57, v0
	v_mov_b32_e32 v58, v0
	v_mov_b32_e32 v59, v0
	v_mov_b32_e32 v60, v0
	v_mov_b32_e32 v61, v0
	v_mov_b32_e32 v62, v0
	v_mov_b32_e32 v63, v0
	v_mov_b32_e32 v64, v0
	v_mov_b32_e32 v65, v0
	v_mov_b32_e32 v66, v0
	v_mov_b32_e32 v67, v0
	v_mov_b32_e32 v68, v0
	v_mov_b32_e32 v69, v0
	v_mov_b32_e32 v70, v0
	v_mov_b32_e32 v71, v0
	v_mov_b32_e32 v72, v0
	v_mov_b32_e32 v73, v0
	v_mov_b32_e32 v74, v0
	v_mov_b32_e32 v75, v0
	v_mov_b32_e32 v76, v0
	v_mov_b32_e32 v77, v0
	v_mov_b32_e32 v78, v0
	v_mov_b32_e32 v79, v0
	v_mov_b32_e32 v80, v0
	v_mov_b32_e32 v81, v0
	v_mov_b32_e32 v82, v0
	v_mov_b32_e32 v83, v0
	v_mov_b32_e32 v84, v0
	v_mov_b32_e32 v85, v0
	v_mov_b32_e32 v86, v0
	v_mov_b32_e32 v87, v0
	v_mov_b32_e32 v88, v0
	v_mov_b32_e32 v89, v0
	v_mov_b32_e32 v90, v0
	v_mov_b32_e32 v91, v0
	v_mov_b32_e32 v92, v0
	v_mov_b32_e32 v93, v0
	v_mov_b32_e32 v94, v0
	v_mov_b32_e32 v95, v0
	v_mov_b32_e32 v96, v0
	v_mov_b32_e32 v97, v0
	v_mov_b32_e32 v98, v0
	v_mov_b32_e32 v99, v0
	v_mov_b32_e32 v100, v0
	v_mov_b32_e32 v101, v0
	v_mov_b32_e32 v102, v0
	v_mov_b32_e32 v103, v0
	v_mov_b32_e32 v104, v0
	v_mov_b32_e32 v105, v0
	v_mov_b32_e32 v106, v0
	v_mov_b32_e32 v107, v0
	v_mov_b32_e32 v108, v0
	v_mov_b32_e32 v109, v0
	v_mov_b32_e32 v110, v0
	v_mov_b32_e32 v111, v0
	v_mov_b32_e32 v112, v0
	v_mov_b32_e32 v113, v0
	v_mov_b32_e32 v114, v0
	v_mov_b32_e32 v115, v0
	v_mov_b32_e32 v116, v0
	v_mov_b32_e32 v117, v0
	v_mov_b32_e32 v118, v0
	v_mov_b32_e32 v119, v0
	v_mov_b32_e32 v120, v0
	v_mov_b32_e32 v121, v0
	v_mov_b32_e32 v122, v0
	v_mov_b32_e32 v123, v0
	v_mov_b32_e32 v124, v0
	v_mov_b32_e32 v125, v0
	v_mov_b32_e32 v126, v0
	v_mov_b32_e32 v127, v0
	v_add3_u32 v230, v168, v167, 32
	v_add3_u32 v231, v168, v128, 32
	v_add_u32_e32 v232, 0x4020, v169
	v_add_u32_e32 v233, v232, v128
	v_add_u32_e32 v232, v232, v167
	v_subrev_u32_e32 v234, s94, v132
	v_subrev_u32_e32 v238, s94, v130
	v_add_u32_e32 v234, 0x15c88080, v234
	v_sub_u32_e32 v238, v238, v240
	v_add_u32_e32 v238, 0x13288000, v238
	v_add_u32_e32 v235, 0x10000, v234
	v_add_u32_e32 v236, 0x20000, v234
	v_add_u32_e32 v237, 0x30000, v234
	v_add_u32_e32 v239, 0x10000, v238
	v_readfirstlane_b32 s101, v165
	v_readfirstlane_b32 s49, v166
	s_mov_b64 s[98:99], s[94:95]
	s_add_u32 s44, s94, 64
	s_addc_u32 s45, s95, 0
	s_add_u32 s49, s49, 0x4000
	s_movk_i32 s36, 0x80
	s_movk_i32 s37, 0x880
	s_waitcnt vmcnt(6)
	s_barrier
	ds_read_b128 v[170:173], v232 offset:0
	ds_read_b128 v[174:177], v232 offset:2048
	ds_read_b128 v[178:181], v230 offset:0
	ds_read_b128 v[182:185], v230 offset:2048
	ds_read_b128 v[186:189], v230 offset:4096
	ds_read_b128 v[190:193], v230 offset:6144
	s_waitcnt lgkmcnt(2)
	v_mfma_f32_32x32x16_bf16 v[112:127], v[178:181], v[170:173], v[112:127]
	v_mfma_f32_32x32x16_bf16 v[96:111], v[178:181], v[174:177], v[96:111]
	v_mfma_f32_32x32x16_bf16 v[80:95], v[182:185], v[170:173], v[80:95]
	v_mfma_f32_32x32x16_bf16 v[64:79], v[182:185], v[174:177], v[64:79]
	ds_read_b128 v[206:209], v233 offset:0
	ds_read_b128 v[210:213], v233 offset:2048
	ds_read_b128 v[214:217], v231 offset:0
	ds_read_b128 v[218:221], v231 offset:2048
	s_waitcnt lgkmcnt(4)
	v_mfma_f32_32x32x16_bf16 v[48:63], v[186:189], v[170:173], v[48:63]
	v_mfma_f32_32x32x16_bf16 v[32:47], v[186:189], v[174:177], v[32:47]
	v_mfma_f32_32x32x16_bf16 v[16:31], v[190:193], v[170:173], v[16:31]
	v_mfma_f32_32x32x16_bf16 v[0:15], v[190:193], v[174:177], v[0:15]
	ds_read_b128 v[222:225], v231 offset:4096
	ds_read_b128 v[226:229], v231 offset:6144
	s_waitcnt lgkmcnt(2)
	v_mfma_f32_32x32x16_bf16 v[112:127], v[214:217], v[206:209], v[112:127]
	v_mfma_f32_32x32x16_bf16 v[96:111], v[214:217], v[210:213], v[96:111]
	v_mfma_f32_32x32x16_bf16 v[80:95], v[218:221], v[206:209], v[80:95]
	v_mfma_f32_32x32x16_bf16 v[64:79], v[218:221], v[210:213], v[64:79]
	s_mov_b32 s100, 10
.Lp1m_kloop:
	s_waitcnt vmcnt(0) lgkmcnt(0)
	s_barrier
	ds_read_b128 v[170:173], v232 offset:24576
	ds_read_b128 v[174:177], v232 offset:26624
	ds_read_b128 v[178:181], v230 offset:24576
	ds_read_b128 v[182:185], v230 offset:26624
	ds_read_b128 v[186:189], v230 offset:28672
	ds_read_b128 v[190:193], v230 offset:30720
	v_mfma_f32_32x32x16_bf16 v[48:63], v[222:225], v[206:209], v[48:63]
	v_mfma_f32_32x32x16_bf16 v[32:47], v[222:225], v[210:213], v[32:47]
	v_mfma_f32_32x32x16_bf16 v[16:31], v[226:229], v[206:209], v[16:31]
	v_mfma_f32_32x32x16_bf16 v[0:15], v[226:229], v[210:213], v[0:15]
	s_add_u32 m0, s101, 0xc000
	s_nop 0
	global_load_lds_dwordx4 v234, s[98:99]
	s_add_u32 m0, s101, 0x0
	s_nop 0
	global_load_lds_dwordx4 v234, s[44:45]
	s_add_u32 m0, s101, 0xc400
	s_nop 0
	global_load_lds_dwordx4 v235, s[98:99]
	s_add_u32 m0, s101, 0x400
	s_nop 0
	global_load_lds_dwordx4 v235, s[44:45]
	s_waitcnt lgkmcnt(2)
	v_mfma_f32_32x32x16_bf16 v[112:127], v[178:181], v[170:173], v[112:127]
	v_mfma_f32_32x32x16_bf16 v[96:111], v[178:181], v[174:177], v[96:111]
	v_mfma_f32_32x32x16_bf16 v[80:95], v[182:185], v[170:173], v[80:95]
	v_mfma_f32_32x32x16_bf16 v[64:79], v[182:185], v[174:177], v[64:79]
	ds_read_b128 v[206:209], v233 offset:24576
	ds_read_b128 v[210:213], v233 offset:26624
	ds_read_b128 v[214:217], v231 offset:24576
	ds_read_b128 v[218:221], v231 offset:26624
	s_add_u32 m0, s101, 0xc800
	s_nop 0
	global_load_lds_dwordx4 v236, s[98:99]
	s_add_u32 m0, s101, 0x800
	s_nop 0
	global_load_lds_dwordx4 v236, s[44:45]
	s_add_u32 m0, s101, 0xcc00
	s_nop 0
	global_load_lds_dwordx4 v237, s[98:99]
	s_add_u32 m0, s101, 0xc00
	s_nop 0
	global_load_lds_dwordx4 v237, s[44:45]
	s_waitcnt lgkmcnt(4)
	v_mfma_f32_32x32x16_bf16 v[48:63], v[186:189], v[170:173], v[48:63]
	v_mfma_f32_32x32x16_bf16 v[32:47], v[186:189], v[174:177], v[32:47]
	v_mfma_f32_32x32x16_bf16 v[16:31], v[190:193], v[170:173], v[16:31]
	v_mfma_f32_32x32x16_bf16 v[0:15], v[190:193], v[174:177], v[0:15]
	ds_read_b128 v[222:225], v231 offset:28672
	ds_read_b128 v[226:229], v231 offset:30720
	v_xad_u32 v241, s36, v240, v238
	v_xad_u32 v242, s37, v240, v239
	s_add_u32 m0, s49, 0xc000
	s_nop 0
	global_load_lds_dwordx4 v241, s[94:95]
	s_add_u32 m0, s49, 0xffffffc0
	s_nop 0
	global_load_lds_dwordx4 v241, s[94:95] offset:64
	s_add_u32 m0, s49, 0xc400
	s_nop 0
	global_load_lds_dwordx4 v242, s[94:95]
	s_add_u32 m0, s49, 0x3c0
	s_nop 0
	global_load_lds_dwordx4 v242, s[94:95] offset:64
	s_add_u32 s36, s36, 0x80
	s_xor_b32 s37, s36, 0x800
	s_add_u32 s98, s98, 128
	s_addc_u32 s99, s99, 0
	s_add_u32 s44, s44, 128
	s_addc_u32 s45, s45, 0
	s_waitcnt lgkmcnt(2)
	v_mfma_f32_32x32x16_bf16 v[112:127], v[214:217], v[206:209], v[112:127]
	v_mfma_f32_32x32x16_bf16 v[96:111], v[214:217], v[210:213], v[96:111]
	v_mfma_f32_32x32x16_bf16 v[80:95], v[218:221], v[206:209], v[80:95]
	v_mfma_f32_32x32x16_bf16 v[64:79], v[218:221], v[210:213], v[64:79]
	s_waitcnt vmcnt(0) lgkmcnt(0)
	s_barrier
	ds_read_b128 v[170:173], v232 offset:49152
	ds_read_b128 v[174:177], v232 offset:51200
	ds_read_b128 v[178:181], v230 offset:49152
	ds_read_b128 v[182:185], v230 offset:51200
	ds_read_b128 v[186:189], v230 offset:53248
	ds_read_b128 v[190:193], v230 offset:55296
	v_mfma_f32_32x32x16_bf16 v[48:63], v[222:225], v[206:209], v[48:63]
	v_mfma_f32_32x32x16_bf16 v[32:47], v[222:225], v[210:213], v[32:47]
	v_mfma_f32_32x32x16_bf16 v[16:31], v[226:229], v[206:209], v[16:31]
	v_mfma_f32_32x32x16_bf16 v[0:15], v[226:229], v[210:213], v[0:15]
	s_waitcnt lgkmcnt(2)
	v_mfma_f32_32x32x16_bf16 v[112:127], v[178:181], v[170:173], v[112:127]
	v_mfma_f32_32x32x16_bf16 v[96:111], v[178:181], v[174:177], v[96:111]
	v_mfma_f32_32x32x16_bf16 v[80:95], v[182:185], v[170:173], v[80:95]
	v_mfma_f32_32x32x16_bf16 v[64:79], v[182:185], v[174:177], v[64:79]
	ds_read_b128 v[206:209], v233 offset:49152
	ds_read_b128 v[210:213], v233 offset:51200
	ds_read_b128 v[214:217], v231 offset:49152
	ds_read_b128 v[218:221], v231 offset:51200
	s_waitcnt lgkmcnt(4)
	v_mfma_f32_32x32x16_bf16 v[48:63], v[186:189], v[170:173], v[48:63]
	v_mfma_f32_32x32x16_bf16 v[32:47], v[186:189], v[174:177], v[32:47]
	v_mfma_f32_32x32x16_bf16 v[16:31], v[190:193], v[170:173], v[16:31]
	v_mfma_f32_32x32x16_bf16 v[0:15], v[190:193], v[174:177], v[0:15]
	ds_read_b128 v[222:225], v231 offset:53248
	ds_read_b128 v[226:229], v231 offset:55296
	s_waitcnt lgkmcnt(2)
	v_mfma_f32_32x32x16_bf16 v[112:127], v[214:217], v[206:209], v[112:127]
	v_mfma_f32_32x32x16_bf16 v[96:111], v[214:217], v[210:213], v[96:111]
	v_mfma_f32_32x32x16_bf16 v[80:95], v[218:221], v[206:209], v[80:95]
	v_mfma_f32_32x32x16_bf16 v[64:79], v[218:221], v[210:213], v[64:79]
	s_waitcnt vmcnt(0) lgkmcnt(0)
	s_barrier
	ds_read_b128 v[170:173], v232 offset:0
	ds_read_b128 v[174:177], v232 offset:2048
	ds_read_b128 v[178:181], v230 offset:0
	ds_read_b128 v[182:185], v230 offset:2048
	ds_read_b128 v[186:189], v230 offset:4096
	ds_read_b128 v[190:193], v230 offset:6144
	v_mfma_f32_32x32x16_bf16 v[48:63], v[222:225], v[206:209], v[48:63]
	v_mfma_f32_32x32x16_bf16 v[32:47], v[222:225], v[210:213], v[32:47]
	v_mfma_f32_32x32x16_bf16 v[16:31], v[226:229], v[206:209], v[16:31]
	v_mfma_f32_32x32x16_bf16 v[0:15], v[226:229], v[210:213], v[0:15]
	s_add_u32 m0, s101, 0x6000
	s_nop 0
	global_load_lds_dwordx4 v234, s[98:99]
	s_add_u32 m0, s101, 0xc000
	s_nop 0
	global_load_lds_dwordx4 v234, s[44:45]
	s_add_u32 m0, s101, 0x6400
	s_nop 0
	global_load_lds_dwordx4 v235, s[98:99]
	s_add_u32 m0, s101, 0xc400
	s_nop 0
	global_load_lds_dwordx4 v235, s[44:45]
	s_waitcnt lgkmcnt(2)
	v_mfma_f32_32x32x16_bf16 v[112:127], v[178:181], v[170:173], v[112:127]
	v_mfma_f32_32x32x16_bf16 v[96:111], v[178:181], v[174:177], v[96:111]
	v_mfma_f32_32x32x16_bf16 v[80:95], v[182:185], v[170:173], v[80:95]
	v_mfma_f32_32x32x16_bf16 v[64:79], v[182:185], v[174:177], v[64:79]
	ds_read_b128 v[206:209], v233 offset:0
	ds_read_b128 v[210:213], v233 offset:2048
	ds_read_b128 v[214:217], v231 offset:0
	ds_read_b128 v[218:221], v231 offset:2048
	s_add_u32 m0, s101, 0x6800
	s_nop 0
	global_load_lds_dwordx4 v236, s[98:99]
	s_add_u32 m0, s101, 0xc800
	s_nop 0
	global_load_lds_dwordx4 v236, s[44:45]
	s_add_u32 m0, s101, 0x6c00
	s_nop 0
	global_load_lds_dwordx4 v237, s[98:99]
	s_add_u32 m0, s101, 0xcc00
	s_nop 0
	global_load_lds_dwordx4 v237, s[44:45]
	s_waitcnt lgkmcnt(4)
	v_mfma_f32_32x32x16_bf16 v[48:63], v[186:189], v[170:173], v[48:63]
	v_mfma_f32_32x32x16_bf16 v[32:47], v[186:189], v[174:177], v[32:47]
	v_mfma_f32_32x32x16_bf16 v[16:31], v[190:193], v[170:173], v[16:31]
	v_mfma_f32_32x32x16_bf16 v[0:15], v[190:193], v[174:177], v[0:15]
	ds_read_b128 v[222:225], v231 offset:4096
	ds_read_b128 v[226:229], v231 offset:6144
	v_xad_u32 v241, s36, v240, v238
	v_xad_u32 v242, s37, v240, v239
	s_add_u32 m0, s49, 0x6000
	s_nop 0
	global_load_lds_dwordx4 v241, s[94:95]
	s_add_u32 m0, s49, 0xbfc0
	s_nop 0
	global_load_lds_dwordx4 v241, s[94:95] offset:64
	s_add_u32 m0, s49, 0x6400
	s_nop 0
	global_load_lds_dwordx4 v242, s[94:95]
	s_add_u32 m0, s49, 0xc3c0
	s_nop 0
	global_load_lds_dwordx4 v242, s[94:95] offset:64
	s_add_u32 s36, s36, 0x80
	s_xor_b32 s37, s36, 0x800
	s_add_u32 s98, s98, 128
	s_addc_u32 s99, s99, 0
	s_add_u32 s44, s44, 128
	s_addc_u32 s45, s45, 0
	s_waitcnt lgkmcnt(2)
	v_mfma_f32_32x32x16_bf16 v[112:127], v[214:217], v[206:209], v[112:127]
	v_mfma_f32_32x32x16_bf16 v[96:111], v[214:217], v[210:213], v[96:111]
	v_mfma_f32_32x32x16_bf16 v[80:95], v[218:221], v[206:209], v[80:95]
	v_mfma_f32_32x32x16_bf16 v[64:79], v[218:221], v[210:213], v[64:79]
	s_waitcnt vmcnt(0) lgkmcnt(0)
	s_barrier
	ds_read_b128 v[170:173], v232 offset:24576
	ds_read_b128 v[174:177], v232 offset:26624
	ds_read_b128 v[178:181], v230 offset:24576
	ds_read_b128 v[182:185], v230 offset:26624
	ds_read_b128 v[186:189], v230 offset:28672
	ds_read_b128 v[190:193], v230 offset:30720
	v_mfma_f32_32x32x16_bf16 v[48:63], v[222:225], v[206:209], v[48:63]
	v_mfma_f32_32x32x16_bf16 v[32:47], v[222:225], v[210:213], v[32:47]
	v_mfma_f32_32x32x16_bf16 v[16:31], v[226:229], v[206:209], v[16:31]
	v_mfma_f32_32x32x16_bf16 v[0:15], v[226:229], v[210:213], v[0:15]
	s_waitcnt lgkmcnt(2)
	v_mfma_f32_32x32x16_bf16 v[112:127], v[178:181], v[170:173], v[112:127]
	v_mfma_f32_32x32x16_bf16 v[96:111], v[178:181], v[174:177], v[96:111]
	v_mfma_f32_32x32x16_bf16 v[80:95], v[182:185], v[170:173], v[80:95]
	v_mfma_f32_32x32x16_bf16 v[64:79], v[182:185], v[174:177], v[64:79]
	ds_read_b128 v[206:209], v233 offset:24576
	ds_read_b128 v[210:213], v233 offset:26624
	ds_read_b128 v[214:217], v231 offset:24576
	ds_read_b128 v[218:221], v231 offset:26624
	s_waitcnt lgkmcnt(4)
	v_mfma_f32_32x32x16_bf16 v[48:63], v[186:189], v[170:173], v[48:63]
	v_mfma_f32_32x32x16_bf16 v[32:47], v[186:189], v[174:177], v[32:47]
	v_mfma_f32_32x32x16_bf16 v[16:31], v[190:193], v[170:173], v[16:31]
	v_mfma_f32_32x32x16_bf16 v[0:15], v[190:193], v[174:177], v[0:15]
	ds_read_b128 v[222:225], v231 offset:28672
	ds_read_b128 v[226:229], v231 offset:30720
	s_waitcnt lgkmcnt(2)
	v_mfma_f32_32x32x16_bf16 v[112:127], v[214:217], v[206:209], v[112:127]
	v_mfma_f32_32x32x16_bf16 v[96:111], v[214:217], v[210:213], v[96:111]
	v_mfma_f32_32x32x16_bf16 v[80:95], v[218:221], v[206:209], v[80:95]
	v_mfma_f32_32x32x16_bf16 v[64:79], v[218:221], v[210:213], v[64:79]
	s_waitcnt vmcnt(0) lgkmcnt(0)
	s_barrier
	ds_read_b128 v[170:173], v232 offset:49152
	ds_read_b128 v[174:177], v232 offset:51200
	ds_read_b128 v[178:181], v230 offset:49152
	ds_read_b128 v[182:185], v230 offset:51200
	ds_read_b128 v[186:189], v230 offset:53248
	ds_read_b128 v[190:193], v230 offset:55296
	v_mfma_f32_32x32x16_bf16 v[48:63], v[222:225], v[206:209], v[48:63]
	v_mfma_f32_32x32x16_bf16 v[32:47], v[222:225], v[210:213], v[32:47]
	v_mfma_f32_32x32x16_bf16 v[16:31], v[226:229], v[206:209], v[16:31]
	v_mfma_f32_32x32x16_bf16 v[0:15], v[226:229], v[210:213], v[0:15]
	s_add_u32 m0, s101, 0x0
	s_nop 0
	global_load_lds_dwordx4 v234, s[98:99]
	s_add_u32 m0, s101, 0x6000
	s_nop 0
	global_load_lds_dwordx4 v234, s[44:45]
	s_add_u32 m0, s101, 0x400
	s_nop 0
	global_load_lds_dwordx4 v235, s[98:99]
	s_add_u32 m0, s101, 0x6400
	s_nop 0
	global_load_lds_dwordx4 v235, s[44:45]
	s_waitcnt lgkmcnt(2)
	v_mfma_f32_32x32x16_bf16 v[112:127], v[178:181], v[170:173], v[112:127]
	v_mfma_f32_32x32x16_bf16 v[96:111], v[178:181], v[174:177], v[96:111]
	v_mfma_f32_32x32x16_bf16 v[80:95], v[182:185], v[170:173], v[80:95]
	v_mfma_f32_32x32x16_bf16 v[64:79], v[182:185], v[174:177], v[64:79]
	ds_read_b128 v[206:209], v233 offset:49152
	ds_read_b128 v[210:213], v233 offset:51200
	ds_read_b128 v[214:217], v231 offset:49152
	ds_read_b128 v[218:221], v231 offset:51200
	s_add_u32 m0, s101, 0x800
	s_nop 0
	global_load_lds_dwordx4 v236, s[98:99]
	s_add_u32 m0, s101, 0x6800
	s_nop 0
	global_load_lds_dwordx4 v236, s[44:45]
	s_add_u32 m0, s101, 0xc00
	s_nop 0
	global_load_lds_dwordx4 v237, s[98:99]
	s_add_u32 m0, s101, 0x6c00
	s_nop 0
	global_load_lds_dwordx4 v237, s[44:45]
	s_waitcnt lgkmcnt(4)
	v_mfma_f32_32x32x16_bf16 v[48:63], v[186:189], v[170:173], v[48:63]
	v_mfma_f32_32x32x16_bf16 v[32:47], v[186:189], v[174:177], v[32:47]
	v_mfma_f32_32x32x16_bf16 v[16:31], v[190:193], v[170:173], v[16:31]
	v_mfma_f32_32x32x16_bf16 v[0:15], v[190:193], v[174:177], v[0:15]
	ds_read_b128 v[222:225], v231 offset:53248
	ds_read_b128 v[226:229], v231 offset:55296
	v_xad_u32 v241, s36, v240, v238
	v_xad_u32 v242, s37, v240, v239
	s_add_u32 m0, s49, 0x0
	s_nop 0
	global_load_lds_dwordx4 v241, s[94:95]
	s_add_u32 m0, s49, 0x5fc0
	s_nop 0
	global_load_lds_dwordx4 v241, s[94:95] offset:64
	s_add_u32 m0, s49, 0x400
	s_nop 0
	global_load_lds_dwordx4 v242, s[94:95]
	s_add_u32 m0, s49, 0x63c0
	s_nop 0
	global_load_lds_dwordx4 v242, s[94:95] offset:64
	s_add_u32 s36, s36, 0x80
	s_xor_b32 s37, s36, 0x800
	s_add_u32 s98, s98, 128
	s_addc_u32 s99, s99, 0
	s_add_u32 s44, s44, 128
	s_addc_u32 s45, s45, 0
	s_waitcnt lgkmcnt(2)
	v_mfma_f32_32x32x16_bf16 v[112:127], v[214:217], v[206:209], v[112:127]
	v_mfma_f32_32x32x16_bf16 v[96:111], v[214:217], v[210:213], v[96:111]
	v_mfma_f32_32x32x16_bf16 v[80:95], v[218:221], v[206:209], v[80:95]
	v_mfma_f32_32x32x16_bf16 v[64:79], v[218:221], v[210:213], v[64:79]
	s_waitcnt vmcnt(0) lgkmcnt(0)
	s_barrier
	ds_read_b128 v[170:173], v232 offset:0
	ds_read_b128 v[174:177], v232 offset:2048
	ds_read_b128 v[178:181], v230 offset:0
	ds_read_b128 v[182:185], v230 offset:2048
	ds_read_b128 v[186:189], v230 offset:4096
	ds_read_b128 v[190:193], v230 offset:6144
	v_mfma_f32_32x32x16_bf16 v[48:63], v[222:225], v[206:209], v[48:63]
	v_mfma_f32_32x32x16_bf16 v[32:47], v[222:225], v[210:213], v[32:47]
	v_mfma_f32_32x32x16_bf16 v[16:31], v[226:229], v[206:209], v[16:31]
	v_mfma_f32_32x32x16_bf16 v[0:15], v[226:229], v[210:213], v[0:15]
	s_waitcnt lgkmcnt(2)
	v_mfma_f32_32x32x16_bf16 v[112:127], v[178:181], v[170:173], v[112:127]
	v_mfma_f32_32x32x16_bf16 v[96:111], v[178:181], v[174:177], v[96:111]
	v_mfma_f32_32x32x16_bf16 v[80:95], v[182:185], v[170:173], v[80:95]
	v_mfma_f32_32x32x16_bf16 v[64:79], v[182:185], v[174:177], v[64:79]
	ds_read_b128 v[206:209], v233 offset:0
	ds_read_b128 v[210:213], v233 offset:2048
	ds_read_b128 v[214:217], v231 offset:0
	ds_read_b128 v[218:221], v231 offset:2048
	s_waitcnt lgkmcnt(4)
	v_mfma_f32_32x32x16_bf16 v[48:63], v[186:189], v[170:173], v[48:63]
	v_mfma_f32_32x32x16_bf16 v[32:47], v[186:189], v[174:177], v[32:47]
	v_mfma_f32_32x32x16_bf16 v[16:31], v[190:193], v[170:173], v[16:31]
	v_mfma_f32_32x32x16_bf16 v[0:15], v[190:193], v[174:177], v[0:15]
	ds_read_b128 v[222:225], v231 offset:4096
	ds_read_b128 v[226:229], v231 offset:6144
	s_waitcnt lgkmcnt(2)
	v_mfma_f32_32x32x16_bf16 v[112:127], v[214:217], v[206:209], v[112:127]
	v_mfma_f32_32x32x16_bf16 v[96:111], v[214:217], v[210:213], v[96:111]
	v_mfma_f32_32x32x16_bf16 v[80:95], v[218:221], v[206:209], v[80:95]
	v_mfma_f32_32x32x16_bf16 v[64:79], v[218:221], v[210:213], v[64:79]
	s_sub_u32 s100, s100, 1
	s_cmp_lg_u32 s100, 0
	s_cbranch_scc1 .Lp1m_kloop
	s_waitcnt vmcnt(0) lgkmcnt(0)
	s_barrier
	ds_read_b128 v[170:173], v232 offset:24576
	ds_read_b128 v[174:177], v232 offset:26624
	ds_read_b128 v[178:181], v230 offset:24576
	ds_read_b128 v[182:185], v230 offset:26624
	ds_read_b128 v[186:189], v230 offset:28672
	ds_read_b128 v[190:193], v230 offset:30720
	v_mfma_f32_32x32x16_bf16 v[48:63], v[222:225], v[206:209], v[48:63]
	v_mfma_f32_32x32x16_bf16 v[32:47], v[222:225], v[210:213], v[32:47]
	v_mfma_f32_32x32x16_bf16 v[16:31], v[226:229], v[206:209], v[16:31]
	v_mfma_f32_32x32x16_bf16 v[0:15], v[226:229], v[210:213], v[0:15]
	s_add_u32 m0, s101, 0xc000
	s_nop 0
	global_load_lds_dwordx4 v234, s[98:99]
	s_add_u32 m0, s101, 0x0
	s_nop 0
	global_load_lds_dwordx4 v234, s[44:45]
	s_add_u32 m0, s101, 0xc400
	s_nop 0
	global_load_lds_dwordx4 v235, s[98:99]
	s_add_u32 m0, s101, 0x400
	s_nop 0
	global_load_lds_dwordx4 v235, s[44:45]
	s_waitcnt lgkmcnt(2)
	v_mfma_f32_32x32x16_bf16 v[112:127], v[178:181], v[170:173], v[112:127]
	v_mfma_f32_32x32x16_bf16 v[96:111], v[178:181], v[174:177], v[96:111]
	v_mfma_f32_32x32x16_bf16 v[80:95], v[182:185], v[170:173], v[80:95]
	v_mfma_f32_32x32x16_bf16 v[64:79], v[182:185], v[174:177], v[64:79]
	ds_read_b128 v[206:209], v233 offset:24576
	ds_read_b128 v[210:213], v233 offset:26624
	ds_read_b128 v[214:217], v231 offset:24576
	ds_read_b128 v[218:221], v231 offset:26624
	s_add_u32 m0, s101, 0xc800
	s_nop 0
	global_load_lds_dwordx4 v236, s[98:99]
	s_add_u32 m0, s101, 0x800
	s_nop 0
	global_load_lds_dwordx4 v236, s[44:45]
	s_add_u32 m0, s101, 0xcc00
	s_nop 0
	global_load_lds_dwordx4 v237, s[98:99]
	s_add_u32 m0, s101, 0xc00
	s_nop 0
	global_load_lds_dwordx4 v237, s[44:45]
	s_waitcnt lgkmcnt(4)
	v_mfma_f32_32x32x16_bf16 v[48:63], v[186:189], v[170:173], v[48:63]
	v_mfma_f32_32x32x16_bf16 v[32:47], v[186:189], v[174:177], v[32:47]
	v_mfma_f32_32x32x16_bf16 v[16:31], v[190:193], v[170:173], v[16:31]
	v_mfma_f32_32x32x16_bf16 v[0:15], v[190:193], v[174:177], v[0:15]
	ds_read_b128 v[222:225], v231 offset:28672
	ds_read_b128 v[226:229], v231 offset:30720
	v_xad_u32 v241, s36, v240, v238
	v_xad_u32 v242, s37, v240, v239
	s_add_u32 m0, s49, 0xc000
	s_nop 0
	global_load_lds_dwordx4 v241, s[94:95]
	s_add_u32 m0, s49, 0xffffffc0
	s_nop 0
	global_load_lds_dwordx4 v241, s[94:95] offset:64
	s_add_u32 m0, s49, 0xc400
	s_nop 0
	global_load_lds_dwordx4 v242, s[94:95]
	s_add_u32 m0, s49, 0x3c0
	s_nop 0
	global_load_lds_dwordx4 v242, s[94:95] offset:64
	s_add_u32 s36, s36, 0x80
	s_xor_b32 s37, s36, 0x800
	s_add_u32 s98, s98, 128
	s_addc_u32 s99, s99, 0
	s_add_u32 s44, s44, 128
	s_addc_u32 s45, s45, 0
	s_waitcnt lgkmcnt(2)
	v_mfma_f32_32x32x16_bf16 v[112:127], v[214:217], v[206:209], v[112:127]
	v_mfma_f32_32x32x16_bf16 v[96:111], v[214:217], v[210:213], v[96:111]
	v_mfma_f32_32x32x16_bf16 v[80:95], v[218:221], v[206:209], v[80:95]
	v_mfma_f32_32x32x16_bf16 v[64:79], v[218:221], v[210:213], v[64:79]
	s_waitcnt vmcnt(0) lgkmcnt(0)
	s_barrier
	ds_read_b128 v[170:173], v232 offset:49152
	ds_read_b128 v[174:177], v232 offset:51200
	ds_read_b128 v[178:181], v230 offset:49152
	ds_read_b128 v[182:185], v230 offset:51200
	ds_read_b128 v[186:189], v230 offset:53248
	ds_read_b128 v[190:193], v230 offset:55296
	v_mfma_f32_32x32x16_bf16 v[48:63], v[222:225], v[206:209], v[48:63]
	v_mfma_f32_32x32x16_bf16 v[32:47], v[222:225], v[210:213], v[32:47]
	v_mfma_f32_32x32x16_bf16 v[16:31], v[226:229], v[206:209], v[16:31]
	v_mfma_f32_32x32x16_bf16 v[0:15], v[226:229], v[210:213], v[0:15]
	s_waitcnt lgkmcnt(2)
	v_mfma_f32_32x32x16_bf16 v[112:127], v[178:181], v[170:173], v[112:127]
	v_mfma_f32_32x32x16_bf16 v[96:111], v[178:181], v[174:177], v[96:111]
	v_mfma_f32_32x32x16_bf16 v[80:95], v[182:185], v[170:173], v[80:95]
	v_mfma_f32_32x32x16_bf16 v[64:79], v[182:185], v[174:177], v[64:79]
	ds_read_b128 v[206:209], v233 offset:49152
	ds_read_b128 v[210:213], v233 offset:51200
	ds_read_b128 v[214:217], v231 offset:49152
	ds_read_b128 v[218:221], v231 offset:51200
	s_waitcnt lgkmcnt(4)
	v_mfma_f32_32x32x16_bf16 v[48:63], v[186:189], v[170:173], v[48:63]
	v_mfma_f32_32x32x16_bf16 v[32:47], v[186:189], v[174:177], v[32:47]
	v_mfma_f32_32x32x16_bf16 v[16:31], v[190:193], v[170:173], v[16:31]
	v_mfma_f32_32x32x16_bf16 v[0:15], v[190:193], v[174:177], v[0:15]
	ds_read_b128 v[222:225], v231 offset:53248
	ds_read_b128 v[226:229], v231 offset:55296
	s_waitcnt lgkmcnt(2)
	v_mfma_f32_32x32x16_bf16 v[112:127], v[214:217], v[206:209], v[112:127]
	v_mfma_f32_32x32x16_bf16 v[96:111], v[214:217], v[210:213], v[96:111]
	v_mfma_f32_32x32x16_bf16 v[80:95], v[218:221], v[206:209], v[80:95]
	v_mfma_f32_32x32x16_bf16 v[64:79], v[218:221], v[210:213], v[64:79]
	s_waitcnt vmcnt(0) lgkmcnt(0)
	s_barrier
	ds_read_b128 v[170:173], v232 offset:0
	ds_read_b128 v[174:177], v232 offset:2048
	ds_read_b128 v[178:181], v230 offset:0
	ds_read_b128 v[182:185], v230 offset:2048
	ds_read_b128 v[186:189], v230 offset:4096
	ds_read_b128 v[190:193], v230 offset:6144
	v_mfma_f32_32x32x16_bf16 v[48:63], v[222:225], v[206:209], v[48:63]
	v_mfma_f32_32x32x16_bf16 v[32:47], v[222:225], v[210:213], v[32:47]
	v_mfma_f32_32x32x16_bf16 v[16:31], v[226:229], v[206:209], v[16:31]
	v_mfma_f32_32x32x16_bf16 v[0:15], v[226:229], v[210:213], v[0:15]
	s_waitcnt lgkmcnt(2)
	v_mfma_f32_32x32x16_bf16 v[112:127], v[178:181], v[170:173], v[112:127]
	v_mfma_f32_32x32x16_bf16 v[96:111], v[178:181], v[174:177], v[96:111]
	v_mfma_f32_32x32x16_bf16 v[80:95], v[182:185], v[170:173], v[80:95]
	v_mfma_f32_32x32x16_bf16 v[64:79], v[182:185], v[174:177], v[64:79]
	ds_read_b128 v[206:209], v233 offset:0
	ds_read_b128 v[210:213], v233 offset:2048
	ds_read_b128 v[214:217], v231 offset:0
	ds_read_b128 v[218:221], v231 offset:2048
	s_waitcnt lgkmcnt(4)
	v_mfma_f32_32x32x16_bf16 v[48:63], v[186:189], v[170:173], v[48:63]
	v_mfma_f32_32x32x16_bf16 v[32:47], v[186:189], v[174:177], v[32:47]
	v_mfma_f32_32x32x16_bf16 v[16:31], v[190:193], v[170:173], v[16:31]
	v_mfma_f32_32x32x16_bf16 v[0:15], v[190:193], v[174:177], v[0:15]
	ds_read_b128 v[222:225], v231 offset:4096
	ds_read_b128 v[226:229], v231 offset:6144
	s_waitcnt lgkmcnt(2)
	v_mfma_f32_32x32x16_bf16 v[112:127], v[214:217], v[206:209], v[112:127]
	v_mfma_f32_32x32x16_bf16 v[96:111], v[214:217], v[210:213], v[96:111]
	v_mfma_f32_32x32x16_bf16 v[80:95], v[218:221], v[206:209], v[80:95]
	v_mfma_f32_32x32x16_bf16 v[64:79], v[218:221], v[210:213], v[64:79]
	s_waitcnt lgkmcnt(0)
	v_mfma_f32_32x32x16_bf16 v[48:63], v[222:225], v[206:209], v[48:63]
	v_mfma_f32_32x32x16_bf16 v[32:47], v[222:225], v[210:213], v[32:47]
	v_mfma_f32_32x32x16_bf16 v[16:31], v[226:229], v[206:209], v[16:31]
	v_mfma_f32_32x32x16_bf16 v[0:15], v[226:229], v[210:213], v[0:15]
	s_mul_hi_i32 s41, s42, 0x540000
	s_mul_i32 s42, s42, 0x540000
	s_add_u32 s42, s31, s42
	s_addc_u32 s43, s33, s41
	s_lshl_b32 s40, s40, 8
	s_add_u32 s42, s42, s40
	s_addc_u32 s43, s43, 0
	s_add_i32 s16, s16, s17
	s_add_i32 s47, s47, s17
	v_lshrrev_b32_e32 v170, 6, v204
	v_and_b32_e32 v171, 31, v204
	v_bfe_u32 v172, v204, 5, 1
	v_mul_u32_u24_e32 v173, 0x4400, v170
	v_mul_u32_u24_e32 v174, 544, v172
	v_lshl_add_u32 v174, v171, 2, v174
	v_add3_u32 v174, v174, v173, 32
	v_and_b32_e32 v175, 7, v204
	v_bfe_u32 v176, v204, 3, 3
	v_mul_u32_u24_e32 v177, 272, v176
	v_lshl_add_u32 v177, v175, 5, v177
	v_add3_u32 v177, v177, v173, 32
	v_lshrrev_b32_e32 v178, 1, v170
	v_and_b32_e32 v179, 1, v170
	v_lshlrev_b32_e32 v178, 7, v178
	v_lshl_add_u32 v178, v176, 1, v178
	v_mul_u32_u24_e32 v178, 0x5400, v178
	v_lshl_add_u32 v178, v179, 7, v178
	v_lshl_add_u32 v178, v175, 4, v178
	v_add_u32_e32 v179, 0x5400, v178
	v_mov_b32_e32 v180, 0x05040100
	v_mov_b32_e32 v181, 0x07060302
	s_waitcnt vmcnt(0)
	s_barrier
	v_cvt_pk_bf16_f32 v112, v112, v113
	ds_write_b32 v174, v112 offset:0
	v_cvt_pk_bf16_f32 v114, v114, v115
	ds_write_b32 v174, v114 offset:272
	v_cvt_pk_bf16_f32 v116, v116, v117
	ds_write_b32 v174, v116 offset:1088
	v_cvt_pk_bf16_f32 v118, v118, v119
	ds_write_b32 v174, v118 offset:1360
	v_cvt_pk_bf16_f32 v120, v120, v121
	ds_write_b32 v174, v120 offset:2176
	v_cvt_pk_bf16_f32 v122, v122, v123
	ds_write_b32 v174, v122 offset:2448
	v_cvt_pk_bf16_f32 v124, v124, v125
	ds_write_b32 v174, v124 offset:3264
	v_cvt_pk_bf16_f32 v126, v126, v127
	ds_write_b32 v174, v126 offset:3536
	v_cvt_pk_bf16_f32 v96, v96, v97
	ds_write_b32 v174, v96 offset:128
	v_cvt_pk_bf16_f32 v98, v98, v99
	ds_write_b32 v174, v98 offset:400
	v_cvt_pk_bf16_f32 v100, v100, v101
	ds_write_b32 v174, v100 offset:1216
	v_cvt_pk_bf16_f32 v102, v102, v103
	ds_write_b32 v174, v102 offset:1488
	v_cvt_pk_bf16_f32 v104, v104, v105
	ds_write_b32 v174, v104 offset:2304
	v_cvt_pk_bf16_f32 v106, v106, v107
	ds_write_b32 v174, v106 offset:2576
	v_cvt_pk_bf16_f32 v108, v108, v109
	ds_write_b32 v174, v108 offset:3392
	v_cvt_pk_bf16_f32 v110, v110, v111
	ds_write_b32 v174, v110 offset:3664
	v_cvt_pk_bf16_f32 v80, v80, v81
	ds_write_b32 v174, v80 offset:4352
	v_cvt_pk_bf16_f32 v82, v82, v83
	ds_write_b32 v174, v82 offset:4624
	v_cvt_pk_bf16_f32 v84, v84, v85
	ds_write_b32 v174, v84 offset:5440
	v_cvt_pk_bf16_f32 v86, v86, v87
	ds_write_b32 v174, v86 offset:5712
	v_cvt_pk_bf16_f32 v88, v88, v89
	ds_write_b32 v174, v88 offset:6528
	v_cvt_pk_bf16_f32 v90, v90, v91
	ds_write_b32 v174, v90 offset:6800
	v_cvt_pk_bf16_f32 v92, v92, v93
	ds_write_b32 v174, v92 offset:7616
	v_cvt_pk_bf16_f32 v94, v94, v95
	ds_write_b32 v174, v94 offset:7888
	v_cvt_pk_bf16_f32 v64, v64, v65
	ds_write_b32 v174, v64 offset:4480
	v_cvt_pk_bf16_f32 v66, v66, v67
	ds_write_b32 v174, v66 offset:4752
	v_cvt_pk_bf16_f32 v68, v68, v69
	ds_write_b32 v174, v68 offset:5568
	v_cvt_pk_bf16_f32 v70, v70, v71
	ds_write_b32 v174, v70 offset:5840
	v_cvt_pk_bf16_f32 v72, v72, v73
	ds_write_b32 v174, v72 offset:6656
	v_cvt_pk_bf16_f32 v74, v74, v75
	ds_write_b32 v174, v74 offset:6928
	v_cvt_pk_bf16_f32 v76, v76, v77
	ds_write_b32 v174, v76 offset:7744
	v_cvt_pk_bf16_f32 v78, v78, v79
	ds_write_b32 v174, v78 offset:8016
	v_cvt_pk_bf16_f32 v48, v48, v49
	ds_write_b32 v174, v48 offset:8704
	v_cvt_pk_bf16_f32 v50, v50, v51
	ds_write_b32 v174, v50 offset:8976
	v_cvt_pk_bf16_f32 v52, v52, v53
	ds_write_b32 v174, v52 offset:9792
	v_cvt_pk_bf16_f32 v54, v54, v55
	ds_write_b32 v174, v54 offset:10064
	v_cvt_pk_bf16_f32 v56, v56, v57
	ds_write_b32 v174, v56 offset:10880
	v_cvt_pk_bf16_f32 v58, v58, v59
	ds_write_b32 v174, v58 offset:11152
	v_cvt_pk_bf16_f32 v60, v60, v61
	ds_write_b32 v174, v60 offset:11968
	v_cvt_pk_bf16_f32 v62, v62, v63
	ds_write_b32 v174, v62 offset:12240
	v_cvt_pk_bf16_f32 v32, v32, v33
	ds_write_b32 v174, v32 offset:8832
	v_cvt_pk_bf16_f32 v34, v34, v35
	ds_write_b32 v174, v34 offset:9104
	v_cvt_pk_bf16_f32 v36, v36, v37
	ds_write_b32 v174, v36 offset:9920
	v_cvt_pk_bf16_f32 v38, v38, v39
	ds_write_b32 v174, v38 offset:10192
	v_cvt_pk_bf16_f32 v40, v40, v41
	ds_write_b32 v174, v40 offset:11008
	v_cvt_pk_bf16_f32 v42, v42, v43
	ds_write_b32 v174, v42 offset:11280
	v_cvt_pk_bf16_f32 v44, v44, v45
	ds_write_b32 v174, v44 offset:12096
	v_cvt_pk_bf16_f32 v46, v46, v47
	ds_write_b32 v174, v46 offset:12368
	v_cvt_pk_bf16_f32 v16, v16, v17
	ds_write_b32 v174, v16 offset:13056
	v_cvt_pk_bf16_f32 v18, v18, v19
	ds_write_b32 v174, v18 offset:13328
	v_cvt_pk_bf16_f32 v20, v20, v21
	ds_write_b32 v174, v20 offset:14144
	v_cvt_pk_bf16_f32 v22, v22, v23
	ds_write_b32 v174, v22 offset:14416
	v_cvt_pk_bf16_f32 v24, v24, v25
	ds_write_b32 v174, v24 offset:15232
	v_cvt_pk_bf16_f32 v26, v26, v27
	ds_write_b32 v174, v26 offset:15504
	v_cvt_pk_bf16_f32 v28, v28, v29
	ds_write_b32 v174, v28 offset:16320
	v_cvt_pk_bf16_f32 v30, v30, v31
	ds_write_b32 v174, v30 offset:16592
	v_cvt_pk_bf16_f32 v0, v0, v1
	ds_write_b32 v174, v0 offset:13184
	v_cvt_pk_bf16_f32 v2, v2, v3
	ds_write_b32 v174, v2 offset:13456
	v_cvt_pk_bf16_f32 v4, v4, v5
	ds_write_b32 v174, v4 offset:14272
	v_cvt_pk_bf16_f32 v6, v6, v7
	ds_write_b32 v174, v6 offset:14544
	v_cvt_pk_bf16_f32 v8, v8, v9
	ds_write_b32 v174, v8 offset:15360
	v_cvt_pk_bf16_f32 v10, v10, v11
	ds_write_b32 v174, v10 offset:15632
	v_cvt_pk_bf16_f32 v12, v12, v13
	ds_write_b32 v174, v12 offset:16448
	v_cvt_pk_bf16_f32 v14, v14, v15
	ds_write_b32 v174, v14 offset:16720
	s_cmp_ge_i32 s16, s22
	s_cselect_b64 s[40:41], -1, 0
	s_waitcnt lgkmcnt(0)
	ds_read_b128 v[182:185], v177 offset:0
	ds_read_b128 v[186:189], v177 offset:16
	ds_read_b128 v[190:193], v177 offset:2176
	ds_read_b128 v[194:197], v177 offset:2192
	s_waitcnt lgkmcnt(2)
	v_perm_b32 v198, v183, v182, v180
	v_perm_b32 v199, v185, v184, v180
	v_perm_b32 v200, v187, v186, v180
	v_perm_b32 v201, v189, v188, v180
	v_perm_b32 v206, v183, v182, v181
	v_perm_b32 v207, v185, v184, v181
	v_perm_b32 v208, v187, v186, v181
	v_perm_b32 v209, v189, v188, v181
	global_store_dwordx4 v178, v[198:201], s[42:43]
	global_store_dwordx4 v179, v[206:209], s[42:43]
	s_add_u32 s42, s42, 0x54000
	s_addc_u32 s43, s43, 0
	s_nop 1
	ds_read_b128 v[182:185], v177 offset:4352
	ds_read_b128 v[186:189], v177 offset:4368
	s_waitcnt lgkmcnt(2)
	v_perm_b32 v198, v191, v190, v180
	v_perm_b32 v199, v193, v192, v180
	v_perm_b32 v200, v195, v194, v180
	v_perm_b32 v201, v197, v196, v180
	v_perm_b32 v206, v191, v190, v181
	v_perm_b32 v207, v193, v192, v181
	v_perm_b32 v208, v195, v194, v181
	v_perm_b32 v209, v197, v196, v181
	global_store_dwordx4 v178, v[198:201], s[42:43]
	global_store_dwordx4 v179, v[206:209], s[42:43]
	s_add_u32 s42, s42, 0x54000
	s_addc_u32 s43, s43, 0
	s_nop 1
	ds_read_b128 v[190:193], v177 offset:6528
	ds_read_b128 v[194:197], v177 offset:6544
	s_waitcnt lgkmcnt(2)
	v_perm_b32 v198, v183, v182, v180
	v_perm_b32 v199, v185, v184, v180
	v_perm_b32 v200, v187, v186, v180
	v_perm_b32 v201, v189, v188, v180
	v_perm_b32 v206, v183, v182, v181
	v_perm_b32 v207, v185, v184, v181
	v_perm_b32 v208, v187, v186, v181
	v_perm_b32 v209, v189, v188, v181
	global_store_dwordx4 v178, v[198:201], s[42:43]
	global_store_dwordx4 v179, v[206:209], s[42:43]
	s_add_u32 s42, s42, 0x54000
	s_addc_u32 s43, s43, 0
	s_nop 1
	ds_read_b128 v[182:185], v177 offset:8704
	ds_read_b128 v[186:189], v177 offset:8720
	s_waitcnt lgkmcnt(2)
	v_perm_b32 v198, v191, v190, v180
	v_perm_b32 v199, v193, v192, v180
	v_perm_b32 v200, v195, v194, v180
	v_perm_b32 v201, v197, v196, v180
	v_perm_b32 v206, v191, v190, v181
	v_perm_b32 v207, v193, v192, v181
	v_perm_b32 v208, v195, v194, v181
	v_perm_b32 v209, v197, v196, v181
	global_store_dwordx4 v178, v[198:201], s[42:43]
	global_store_dwordx4 v179, v[206:209], s[42:43]
	s_add_u32 s42, s42, 0x54000
	s_addc_u32 s43, s43, 0
	s_nop 1
	ds_read_b128 v[190:193], v177 offset:10880
	ds_read_b128 v[194:197], v177 offset:10896
	s_waitcnt lgkmcnt(2)
	v_perm_b32 v198, v183, v182, v180
	v_perm_b32 v199, v185, v184, v180
	v_perm_b32 v200, v187, v186, v180
	v_perm_b32 v201, v189, v188, v180
	v_perm_b32 v206, v183, v182, v181
	v_perm_b32 v207, v185, v184, v181
	v_perm_b32 v208, v187, v186, v181
	v_perm_b32 v209, v189, v188, v181
	global_store_dwordx4 v178, v[198:201], s[42:43]
	global_store_dwordx4 v179, v[206:209], s[42:43]
	s_add_u32 s42, s42, 0x54000
	s_addc_u32 s43, s43, 0
	s_nop 1
	ds_read_b128 v[182:185], v177 offset:13056
	ds_read_b128 v[186:189], v177 offset:13072
	s_waitcnt lgkmcnt(2)
	v_perm_b32 v198, v191, v190, v180
	v_perm_b32 v199, v193, v192, v180
	v_perm_b32 v200, v195, v194, v180
	v_perm_b32 v201, v197, v196, v180
	v_perm_b32 v206, v191, v190, v181
	v_perm_b32 v207, v193, v192, v181
	v_perm_b32 v208, v195, v194, v181
	v_perm_b32 v209, v197, v196, v181
	global_store_dwordx4 v178, v[198:201], s[42:43]
	global_store_dwordx4 v179, v[206:209], s[42:43]
	s_add_u32 s42, s42, 0x54000
	s_addc_u32 s43, s43, 0
	s_nop 1
	ds_read_b128 v[190:193], v177 offset:15232
	ds_read_b128 v[194:197], v177 offset:15248
	s_waitcnt lgkmcnt(2)
	v_perm_b32 v198, v183, v182, v180
	v_perm_b32 v199, v185, v184, v180
	v_perm_b32 v200, v187, v186, v180
	v_perm_b32 v201, v189, v188, v180
	v_perm_b32 v206, v183, v182, v181
	v_perm_b32 v207, v185, v184, v181
	v_perm_b32 v208, v187, v186, v181
	v_perm_b32 v209, v189, v188, v181
	global_store_dwordx4 v178, v[198:201], s[42:43]
	global_store_dwordx4 v179, v[206:209], s[42:43]
	s_add_u32 s42, s42, 0x54000
	s_addc_u32 s43, s43, 0
	s_nop 1
	s_waitcnt lgkmcnt(0)
	s_barrier
	v_perm_b32 v198, v191, v190, v180
	v_perm_b32 v199, v193, v192, v180
	v_perm_b32 v200, v195, v194, v180
	v_perm_b32 v201, v197, v196, v180
	v_perm_b32 v206, v191, v190, v181
	v_perm_b32 v207, v193, v192, v181
	v_perm_b32 v208, v195, v194, v181
	v_perm_b32 v209, v197, v196, v181
	global_store_dwordx4 v178, v[198:201], s[42:43]
	global_store_dwordx4 v179, v[206:209], s[42:43]
	s_branch .LBB0_126

.LBB0_707:
	v_add_u32_e32 v0, v206, v207
	s_movk_i32 s22, 0x1ff
	v_cmp_lt_i32_e32 vcc, s22, v0
	s_cbranch_vccnz .LBB0_706
	v_readfirstlane_b32 s22, v0
	s_ashr_i32 s23, s22, 31
	s_lshr_b32 s23, s23, 25
	s_add_i32 s23, s22, s23
	s_ashr_i32 s33, s23, 7
	s_lshl_b32 s41, s33, 3
	s_and_b32 s23, s23, 0xffffff80
	s_sub_i32 s40, 32, s41
	s_cmpk_gt_i32 s22, 0x1ff
	s_cselect_b32 s42, s40, 8
	s_abs_i32 s40, s42
	v_cvt_f32_u32_e32 v1, s40
	v_subrev_u32_e32 v0, s23, v0
	s_sub_i32 s23, 0, s40
	v_sub_u32_e32 v2, 0, v0
	v_rcp_iflag_f32_e32 v1, v1
	v_max_i32_e32 v2, v0, v2
	v_xor_b32_e32 v3, s42, v0
	v_ashrrev_i32_e32 v3, 31, v3
	v_mul_f32_e32 v1, 0x4f7ffffe, v1
	v_cvt_u32_f32_e32 v1, v1
	v_mov_b32_e32 v8, v204
	s_mulk_i32 s33, 0x78
	v_mul_lo_u32 v4, s23, v1
	v_mul_hi_u32 v4, v1, v4
	v_add_u32_e32 v1, v1, v4
	v_mul_hi_u32 v1, v2, v1
	v_mul_lo_u32 v4, v1, s40
	v_sub_u32_e32 v2, v2, v4
	v_add_u32_e32 v5, 1, v1
	v_subrev_u32_e32 v4, s40, v2
	v_cmp_le_u32_e32 vcc, s40, v2
	s_mov_b32 s22, 0
	s_nop 0
	v_cndmask_b32_e32 v1, v1, v5, vcc
	v_cndmask_b32_e32 v2, v2, v4, vcc
	v_add_u32_e32 v4, 1, v1
	v_cmp_le_u32_e32 vcc, s40, v2
	v_bfe_u32 v2, v8, 4, 2
	v_bitop3_b32 v2, v2, v8, 3 bitop3:0x78
	v_cndmask_b32_e32 v1, v1, v4, vcc
	v_xor_b32_e32 v1, v1, v3
	v_sub_u32_e32 v1, v1, v3
	v_ashrrev_i32_e32 v3, 6, v8
	v_readfirstlane_b32 s40, v1
	s_mul_i32 s23, s42, s40
	v_subrev_u32_e32 v0, s23, v0
	s_waitcnt vmcnt(1)
	v_add_u32_e32 v138, s41, v0
	s_ashr_i32 s41, s40, 31
	v_lshlrev_b32_e32 v132, 8, v138
	s_lshl_b64 s[42:43], s[40:41], 19
	v_bfe_u32 v4, v8, 2, 4
	s_mov_b32 s41, 0x1fffc0
	v_ashrrev_i32_e32 v133, 31, v132
	v_lshlrev_b32_e32 v9, 3, v2
	v_and_or_b32 v2, v8, s41, v4
	v_lshlrev_b32_e32 v5, 16, v3
	v_lshlrev_b32_e32 v10, 11, v4
	v_lshlrev_b64 v[130:131], 11, v[132:133]
	v_lshlrev_b64 v[0:1], 12, v[132:133]
	v_lshl_or_b32 v2, v2, 11, v9
	v_or3_b32 v4, v10, v5, v9
	v_lshl_add_u32 v133, v3, 12, 32
	v_lshlrev_b32_e32 v3, 11, v3
	v_lshl_add_u64 v[0:1], s[6:7], 0, v[0:1]
	s_add_u32 s90, s52, s42
	v_sub_u32_e32 v139, v133, v3
	v_ashrrev_i32_e32 v3, 31, v2
	v_ashrrev_i32_e32 v5, 31, v4
	v_readfirstlane_b32 s41, v133
	v_add_u32_e32 v12, 0x400, v133
	s_addc_u32 s91, s53, s43
	v_lshl_add_u64 v[0:1], v[2:3], 1, v[0:1]
	v_lshlrev_b64 v[2:3], 1, v[4:5]
	v_lshrrev_b32_e32 v241, 4, v10
	v_add_u32_e32 v2, v2, v241
	s_mov_b32 m0, s41
	v_readfirstlane_b32 s41, v12
	v_add_u32_e32 v12, 0x800, v133
	v_lshl_add_u64 v[4:5], s[90:91], 0, v[2:3]
	global_load_lds_dwordx4 v[0:1], off
	v_lshl_add_u64 v[6:7], v[0:1], 0, s[10:11]
	s_mov_b32 m0, s41
	s_mov_b64 s[90:91], 0x20000
	v_readfirstlane_b32 s41, v12
	v_add_u32_e32 v12, 0xc00, v133
	v_add_u32_e32 v11, 0x4000, v139
	global_load_lds_dwordx4 v[6:7], off
	v_lshl_add_u64 v[6:7], v[0:1], 0, s[90:91]
	s_mov_b32 m0, s41
	s_mov_b64 s[90:91], 0x30000
	v_readfirstlane_b32 s41, v12
	global_load_lds_dwordx4 v[6:7], off
	v_lshl_add_u64 v[6:7], v[0:1], 0, s[90:91]
	s_mov_b32 m0, s41
	v_readfirstlane_b32 s41, v11
	v_add_u32_e32 v11, 0x4400, v139
	global_load_lds_dwordx4 v[6:7], off
	s_mov_b32 m0, s41
	v_readfirstlane_b32 s41, v11
	v_add_u32_e32 v11, 0x6000, v133
	global_load_lds_dwordx4 v[4:5], off
	s_mov_b64 s[90:91], 0x10800
	v_lshl_add_u64 v[6:7], v[4:5], 0, s[90:91]
	s_mov_b32 m0, s41
	v_readfirstlane_b32 s41, v11
	v_add_u32_e32 v11, 0x6400, v133
	global_load_lds_dwordx4 v[6:7], off
	v_lshl_add_u64 v[6:7], v[0:1], 0, 64
	s_mov_b32 m0, s41
	v_readfirstlane_b32 s41, v11
	v_add_u32_e32 v11, 0x6800, v133
	global_load_lds_dwordx4 v[6:7], off
	v_lshl_add_u64 v[6:7], v[0:1], 0, s[12:13]
	s_mov_b32 m0, s41
	s_mov_b64 s[90:91], 0x20040
	v_readfirstlane_b32 s41, v11
	global_load_lds_dwordx4 v[6:7], off
	v_lshl_add_u64 v[6:7], v[0:1], 0, s[90:91]
	s_mov_b32 m0, s41
	s_mov_b64 s[90:91], 0x30040
	global_load_lds_dwordx4 v[6:7], off
	v_add_u32_e32 v6, 0x6c00, v133
	v_lshl_add_u64 v[0:1], v[0:1], 0, s[90:91]
	v_readfirstlane_b32 s41, v6
	v_add_u32_e32 v6, 0xa000, v139
	s_mov_b32 m0, s41
	v_readfirstlane_b32 s41, v6
	global_load_lds_dwordx4 v[0:1], off
	v_lshl_add_u64 v[0:1], v[4:5], 0, 64
	s_mov_b32 m0, s41
	s_add_u32 s42, s94, s42
	global_load_lds_dwordx4 v[0:1], off
	s_mov_b64 s[90:91], 0x10840
	v_lshl_add_u64 v[0:1], v[4:5], 0, s[90:91]
	v_add_u32_e32 v4, 0xa400, v139
	s_addc_u32 s43, s95, s43
	v_readfirstlane_b32 s41, v4
	s_mov_b32 m0, s41
	v_bfe_u32 v4, v8, 2, 2
	global_load_lds_dwordx4 v[0:1], off
	v_bfe_u32 v0, v8, 5, 1
	v_lshrrev_b32_e32 v1, 2, v8
	v_bitop3_b32 v1, v0, v1, 3 bitop3:0x78
	v_bitop3_b32 v0, v0, v4, 2 bitop3:0x36
	v_lshlrev_b32_e32 v128, 4, v0
	v_subrev_u32_e32 v0, s23, v208
	v_subrev_u32_e32 v0, s33, v0
	v_lshl_add_u64 v[134:135], s[42:43], 0, v[2:3]
	v_lshlrev_b32_e32 v0, 8, v0
	v_lshlrev_b32_e32 v2, 11, v8
	v_lshlrev_b32_e32 v140, 4, v1
	v_ashrrev_i32_e32 v1, 31, v0
	v_and_b32_e32 v2, 0xfffe0000, v2
	v_lshlrev_b64 v[0:1], 12, v[0:1]
	v_or3_b32 v2, v2, v10, v9
	v_ashrrev_i32_e32 v3, 31, v2
	v_lshl_add_u64 v[0:1], s[94:95], 0, v[0:1]
	v_lshlrev_b32_e32 v5, 6, v8
	v_lshl_add_u64 v[136:137], v[2:3], 1, v[0:1]
	v_mov_b32_e32 v0, 0
	v_and_b32_e32 v141, 0xffffe7c0, v5
	s_waitcnt vmcnt(0)
	v_and_b32_e32 v142, 0x17c0, v5
	s_mov_b64 s[42:43], 0
	v_mov_b32_e32 v1, v0
	v_mov_b32_e32 v2, v0
	v_mov_b32_e32 v3, v0
	v_mov_b32_e32 v4, v0
	v_mov_b32_e32 v5, v0
	v_mov_b32_e32 v6, v0
	v_mov_b32_e32 v7, v0
	v_mov_b32_e32 v8, v0
	v_mov_b32_e32 v9, v0
	v_mov_b32_e32 v10, v0
	v_mov_b32_e32 v11, v0
	v_mov_b32_e32 v12, v0
	v_mov_b32_e32 v13, v0
	v_mov_b32_e32 v14, v0
	v_mov_b32_e32 v15, v0
	v_mov_b32_e32 v16, v0
	v_mov_b32_e32 v17, v0
	v_mov_b32_e32 v18, v0
	v_mov_b32_e32 v19, v0
	v_mov_b32_e32 v20, v0
	v_mov_b32_e32 v21, v0
	v_mov_b32_e32 v22, v0
	v_mov_b32_e32 v23, v0
	v_mov_b32_e32 v24, v0
	v_mov_b32_e32 v25, v0
	v_mov_b32_e32 v26, v0
	v_mov_b32_e32 v27, v0
	v_mov_b32_e32 v28, v0
	v_mov_b32_e32 v29, v0
	v_mov_b32_e32 v30, v0
	v_mov_b32_e32 v31, v0
	v_mov_b32_e32 v32, v0
	v_mov_b32_e32 v33, v0
	v_mov_b32_e32 v34, v0
	v_mov_b32_e32 v35, v0
	v_mov_b32_e32 v36, v0
	v_mov_b32_e32 v37, v0
	v_mov_b32_e32 v38, v0
	v_mov_b32_e32 v39, v0
	v_mov_b32_e32 v40, v0
	v_mov_b32_e32 v41, v0
	v_mov_b32_e32 v42, v0
	v_mov_b32_e32 v43, v0
	v_mov_b32_e32 v44, v0
	v_mov_b32_e32 v45, v0
	v_mov_b32_e32 v46, v0
	v_mov_b32_e32 v47, v0
	v_mov_b32_e32 v48, v0
	v_mov_b32_e32 v49, v0
	v_mov_b32_e32 v50, v0
	v_mov_b32_e32 v51, v0
	v_mov_b32_e32 v52, v0
	v_mov_b32_e32 v53, v0
	v_mov_b32_e32 v54, v0
	v_mov_b32_e32 v55, v0
	v_mov_b32_e32 v56, v0
	v_mov_b32_e32 v57, v0
	v_mov_b32_e32 v58, v0
	v_mov_b32_e32 v59, v0
	v_mov_b32_e32 v60, v0
	v_mov_b32_e32 v61, v0
	v_mov_b32_e32 v62, v0
	v_mov_b32_e32 v63, v0
	v_mov_b32_e32 v64, v0
	v_mov_b32_e32 v65, v0
	v_mov_b32_e32 v66, v0
	v_mov_b32_e32 v67, v0
	v_mov_b32_e32 v68, v0
	v_mov_b32_e32 v69, v0
	v_mov_b32_e32 v70, v0
	v_mov_b32_e32 v71, v0
	v_mov_b32_e32 v72, v0
	v_mov_b32_e32 v73, v0
	v_mov_b32_e32 v74, v0
	v_mov_b32_e32 v75, v0
	v_mov_b32_e32 v76, v0
	v_mov_b32_e32 v77, v0
	v_mov_b32_e32 v78, v0
	v_mov_b32_e32 v79, v0
	v_mov_b32_e32 v80, v0
	v_mov_b32_e32 v81, v0
	v_mov_b32_e32 v82, v0
	v_mov_b32_e32 v83, v0
	v_mov_b32_e32 v84, v0
	v_mov_b32_e32 v85, v0
	v_mov_b32_e32 v86, v0
	v_mov_b32_e32 v87, v0
	v_mov_b32_e32 v88, v0
	v_mov_b32_e32 v89, v0
	v_mov_b32_e32 v90, v0
	v_mov_b32_e32 v91, v0
	v_mov_b32_e32 v92, v0
	v_mov_b32_e32 v93, v0
	v_mov_b32_e32 v94, v0
	v_mov_b32_e32 v95, v0
	v_mov_b32_e32 v96, v0
	v_mov_b32_e32 v97, v0
	v_mov_b32_e32 v98, v0
	v_mov_b32_e32 v99, v0
	v_mov_b32_e32 v100, v0
	v_mov_b32_e32 v101, v0
	v_mov_b32_e32 v102, v0
	v_mov_b32_e32 v103, v0
	v_mov_b32_e32 v104, v0
	v_mov_b32_e32 v105, v0
	v_mov_b32_e32 v106, v0
	v_mov_b32_e32 v107, v0
	v_mov_b32_e32 v108, v0
	v_mov_b32_e32 v109, v0
	v_mov_b32_e32 v110, v0
	v_mov_b32_e32 v111, v0
	v_mov_b32_e32 v112, v0
	v_mov_b32_e32 v113, v0
	v_mov_b32_e32 v114, v0
	v_mov_b32_e32 v115, v0
	v_mov_b32_e32 v116, v0
	v_mov_b32_e32 v117, v0
	v_mov_b32_e32 v118, v0
	v_mov_b32_e32 v119, v0
	v_mov_b32_e32 v120, v0
	v_mov_b32_e32 v121, v0
	v_mov_b32_e32 v122, v0
	v_mov_b32_e32 v123, v0
	v_mov_b32_e32 v124, v0
	v_mov_b32_e32 v125, v0
	v_mov_b32_e32 v126, v0
	v_mov_b32_e32 v127, v0
	v_add3_u32 v192, v141, v140, 32
	v_add3_u32 v193, v141, v128, 32
	v_add_u32_e32 v194, 0x4020, v142
	v_add_u32_e32 v195, v194, v128
	v_add_u32_e32 v194, v194, v140
	v_subrev_u32_e32 v196, s94, v136
	v_subrev_u32_e32 v200, s94, v134
	v_add_u32_e32 v196, 0x15c88080, v196
	v_sub_u32_e32 v200, v200, v241
	v_add_u32_e32 v200, 0x18a88000, v200
	v_add_u32_e32 v197, 0x10000, v196
	v_add_u32_e32 v198, 0x20000, v196
	v_add_u32_e32 v199, 0x30000, v196
	v_add_u32_e32 v201, 0x10000, v200
	v_readfirstlane_b32 s22, v133
	v_readfirstlane_b32 s23, v139
	s_mov_b64 s[98:99], s[94:95]
	s_add_u32 s100, s94, 64
	s_addc_u32 s101, s95, 0
	s_add_u32 s23, s23, 0x4000
	v_or_b32_e32 v245, 0x800, v241
	s_movk_i32 s32, 0x80
	s_waitcnt vmcnt(6)
	s_barrier
	ds_read_b128 v[144:147], v194 offset:0
	ds_read_b128 v[148:151], v194 offset:2048
	ds_read_b128 v[152:155], v192 offset:0
	ds_read_b128 v[156:159], v192 offset:2048
	ds_read_b128 v[160:163], v192 offset:4096
	ds_read_b128 v[164:167], v192 offset:6144
	s_waitcnt lgkmcnt(2)
	v_mfma_f32_32x32x16_bf16 v[112:127], v[152:155], v[144:147], v[112:127]
	v_mfma_f32_32x32x16_bf16 v[96:111], v[152:155], v[148:151], v[96:111]
	v_mfma_f32_32x32x16_bf16 v[80:95], v[156:159], v[144:147], v[80:95]
	v_mfma_f32_32x32x16_bf16 v[64:79], v[156:159], v[148:151], v[64:79]
	ds_read_b128 v[168:171], v195 offset:0
	ds_read_b128 v[172:175], v195 offset:2048
	ds_read_b128 v[176:179], v193 offset:0
	ds_read_b128 v[180:183], v193 offset:2048
	s_waitcnt lgkmcnt(4)
	v_mfma_f32_32x32x16_bf16 v[48:63], v[160:163], v[144:147], v[48:63]
	v_mfma_f32_32x32x16_bf16 v[32:47], v[160:163], v[148:151], v[32:47]
	v_mfma_f32_32x32x16_bf16 v[16:31], v[164:167], v[144:147], v[16:31]
	v_mfma_f32_32x32x16_bf16 v[0:15], v[164:167], v[148:151], v[0:15]
	ds_read_b128 v[184:187], v193 offset:4096
	ds_read_b128 v[188:191], v193 offset:6144
	s_waitcnt lgkmcnt(2)
	v_mfma_f32_32x32x16_bf16 v[112:127], v[176:179], v[168:171], v[112:127]
	v_mfma_f32_32x32x16_bf16 v[96:111], v[176:179], v[172:175], v[96:111]
	v_mfma_f32_32x32x16_bf16 v[80:95], v[180:183], v[168:171], v[80:95]
	v_mfma_f32_32x32x16_bf16 v[64:79], v[180:183], v[172:175], v[64:79]
	s_mov_b32 s33, 10
.Lp5m_kloop:
	s_waitcnt vmcnt(0) lgkmcnt(0)
	s_barrier
	ds_read_b128 v[144:147], v194 offset:24576
	ds_read_b128 v[148:151], v194 offset:26624
	ds_read_b128 v[152:155], v192 offset:24576
	ds_read_b128 v[156:159], v192 offset:26624
	ds_read_b128 v[160:163], v192 offset:28672
	ds_read_b128 v[164:167], v192 offset:30720
	v_mfma_f32_32x32x16_bf16 v[48:63], v[184:187], v[168:171], v[48:63]
	v_mfma_f32_32x32x16_bf16 v[32:47], v[184:187], v[172:175], v[32:47]
	v_mfma_f32_32x32x16_bf16 v[16:31], v[188:191], v[168:171], v[16:31]
	v_mfma_f32_32x32x16_bf16 v[0:15], v[188:191], v[172:175], v[0:15]
	s_add_u32 m0, s22, 0xc000
	s_nop 0
	global_load_lds_dwordx4 v196, s[98:99]
	s_add_u32 m0, s22, 0x0
	s_nop 0
	global_load_lds_dwordx4 v196, s[100:101]
	s_add_u32 m0, s22, 0xc400
	s_nop 0
	global_load_lds_dwordx4 v197, s[98:99]
	s_add_u32 m0, s22, 0x400
	s_nop 0
	global_load_lds_dwordx4 v197, s[100:101]
	s_waitcnt lgkmcnt(2)
	v_mfma_f32_32x32x16_bf16 v[112:127], v[152:155], v[144:147], v[112:127]
	v_mfma_f32_32x32x16_bf16 v[96:111], v[152:155], v[148:151], v[96:111]
	v_mfma_f32_32x32x16_bf16 v[80:95], v[156:159], v[144:147], v[80:95]
	v_mfma_f32_32x32x16_bf16 v[64:79], v[156:159], v[148:151], v[64:79]
	ds_read_b128 v[168:171], v195 offset:24576
	ds_read_b128 v[172:175], v195 offset:26624
	ds_read_b128 v[176:179], v193 offset:24576
	ds_read_b128 v[180:183], v193 offset:26624
	s_add_u32 m0, s22, 0xc800
	s_nop 0
	global_load_lds_dwordx4 v198, s[98:99]
	s_add_u32 m0, s22, 0x800
	s_nop 0
	global_load_lds_dwordx4 v198, s[100:101]
	s_add_u32 m0, s22, 0xcc00
	s_nop 0
	global_load_lds_dwordx4 v199, s[98:99]
	s_add_u32 m0, s22, 0xc00
	s_nop 0
	global_load_lds_dwordx4 v199, s[100:101]
	s_waitcnt lgkmcnt(4)
	v_mfma_f32_32x32x16_bf16 v[48:63], v[160:163], v[144:147], v[48:63]
	v_mfma_f32_32x32x16_bf16 v[32:47], v[160:163], v[148:151], v[32:47]
	v_mfma_f32_32x32x16_bf16 v[16:31], v[164:167], v[144:147], v[16:31]
	v_mfma_f32_32x32x16_bf16 v[0:15], v[164:167], v[148:151], v[0:15]
	ds_read_b128 v[184:187], v193 offset:28672
	ds_read_b128 v[188:191], v193 offset:30720
	v_xad_u32 v246, s32, v241, v200
	v_xad_u32 v247, s32, v245, v201
	s_add_u32 m0, s23, 0xc000
	s_nop 0
	global_load_lds_dwordx4 v246, s[94:95]
	s_add_u32 m0, s23, 0xffffffc0
	s_nop 0
	global_load_lds_dwordx4 v246, s[94:95] offset:64
	s_add_u32 m0, s23, 0xc400
	s_nop 0
	global_load_lds_dwordx4 v247, s[94:95]
	s_add_u32 m0, s23, 0x3c0
	s_nop 0
	global_load_lds_dwordx4 v247, s[94:95] offset:64
	s_add_u32 s32, s32, 0x80
	s_add_u32 s98, s98, 128
	s_addc_u32 s99, s99, 0
	s_add_u32 s100, s100, 128
	s_addc_u32 s101, s101, 0
	s_waitcnt lgkmcnt(2)
	v_mfma_f32_32x32x16_bf16 v[112:127], v[176:179], v[168:171], v[112:127]
	v_mfma_f32_32x32x16_bf16 v[96:111], v[176:179], v[172:175], v[96:111]
	v_mfma_f32_32x32x16_bf16 v[80:95], v[180:183], v[168:171], v[80:95]
	v_mfma_f32_32x32x16_bf16 v[64:79], v[180:183], v[172:175], v[64:79]
	s_waitcnt vmcnt(0) lgkmcnt(0)
	s_barrier
	ds_read_b128 v[144:147], v194 offset:49152
	ds_read_b128 v[148:151], v194 offset:51200
	ds_read_b128 v[152:155], v192 offset:49152
	ds_read_b128 v[156:159], v192 offset:51200
	ds_read_b128 v[160:163], v192 offset:53248
	ds_read_b128 v[164:167], v192 offset:55296
	v_mfma_f32_32x32x16_bf16 v[48:63], v[184:187], v[168:171], v[48:63]
	v_mfma_f32_32x32x16_bf16 v[32:47], v[184:187], v[172:175], v[32:47]
	v_mfma_f32_32x32x16_bf16 v[16:31], v[188:191], v[168:171], v[16:31]
	v_mfma_f32_32x32x16_bf16 v[0:15], v[188:191], v[172:175], v[0:15]
	s_waitcnt lgkmcnt(2)
	v_mfma_f32_32x32x16_bf16 v[112:127], v[152:155], v[144:147], v[112:127]
	v_mfma_f32_32x32x16_bf16 v[96:111], v[152:155], v[148:151], v[96:111]
	v_mfma_f32_32x32x16_bf16 v[80:95], v[156:159], v[144:147], v[80:95]
	v_mfma_f32_32x32x16_bf16 v[64:79], v[156:159], v[148:151], v[64:79]
	ds_read_b128 v[168:171], v195 offset:49152
	ds_read_b128 v[172:175], v195 offset:51200
	ds_read_b128 v[176:179], v193 offset:49152
	ds_read_b128 v[180:183], v193 offset:51200
	s_waitcnt lgkmcnt(4)
	v_mfma_f32_32x32x16_bf16 v[48:63], v[160:163], v[144:147], v[48:63]
	v_mfma_f32_32x32x16_bf16 v[32:47], v[160:163], v[148:151], v[32:47]
	v_mfma_f32_32x32x16_bf16 v[16:31], v[164:167], v[144:147], v[16:31]
	v_mfma_f32_32x32x16_bf16 v[0:15], v[164:167], v[148:151], v[0:15]
	ds_read_b128 v[184:187], v193 offset:53248
	ds_read_b128 v[188:191], v193 offset:55296
	s_waitcnt lgkmcnt(2)
	v_mfma_f32_32x32x16_bf16 v[112:127], v[176:179], v[168:171], v[112:127]
	v_mfma_f32_32x32x16_bf16 v[96:111], v[176:179], v[172:175], v[96:111]
	v_mfma_f32_32x32x16_bf16 v[80:95], v[180:183], v[168:171], v[80:95]
	v_mfma_f32_32x32x16_bf16 v[64:79], v[180:183], v[172:175], v[64:79]
	s_waitcnt vmcnt(0) lgkmcnt(0)
	s_barrier
	ds_read_b128 v[144:147], v194 offset:0
	ds_read_b128 v[148:151], v194 offset:2048
	ds_read_b128 v[152:155], v192 offset:0
	ds_read_b128 v[156:159], v192 offset:2048
	ds_read_b128 v[160:163], v192 offset:4096
	ds_read_b128 v[164:167], v192 offset:6144
	v_mfma_f32_32x32x16_bf16 v[48:63], v[184:187], v[168:171], v[48:63]
	v_mfma_f32_32x32x16_bf16 v[32:47], v[184:187], v[172:175], v[32:47]
	v_mfma_f32_32x32x16_bf16 v[16:31], v[188:191], v[168:171], v[16:31]
	v_mfma_f32_32x32x16_bf16 v[0:15], v[188:191], v[172:175], v[0:15]
	s_add_u32 m0, s22, 0x6000
	s_nop 0
	global_load_lds_dwordx4 v196, s[98:99]
	s_add_u32 m0, s22, 0xc000
	s_nop 0
	global_load_lds_dwordx4 v196, s[100:101]
	s_add_u32 m0, s22, 0x6400
	s_nop 0
	global_load_lds_dwordx4 v197, s[98:99]
	s_add_u32 m0, s22, 0xc400
	s_nop 0
	global_load_lds_dwordx4 v197, s[100:101]
	s_waitcnt lgkmcnt(2)
	v_mfma_f32_32x32x16_bf16 v[112:127], v[152:155], v[144:147], v[112:127]
	v_mfma_f32_32x32x16_bf16 v[96:111], v[152:155], v[148:151], v[96:111]
	v_mfma_f32_32x32x16_bf16 v[80:95], v[156:159], v[144:147], v[80:95]
	v_mfma_f32_32x32x16_bf16 v[64:79], v[156:159], v[148:151], v[64:79]
	ds_read_b128 v[168:171], v195 offset:0
	ds_read_b128 v[172:175], v195 offset:2048
	ds_read_b128 v[176:179], v193 offset:0
	ds_read_b128 v[180:183], v193 offset:2048
	s_add_u32 m0, s22, 0x6800
	s_nop 0
	global_load_lds_dwordx4 v198, s[98:99]
	s_add_u32 m0, s22, 0xc800
	s_nop 0
	global_load_lds_dwordx4 v198, s[100:101]
	s_add_u32 m0, s22, 0x6c00
	s_nop 0
	global_load_lds_dwordx4 v199, s[98:99]
	s_add_u32 m0, s22, 0xcc00
	s_nop 0
	global_load_lds_dwordx4 v199, s[100:101]
	s_waitcnt lgkmcnt(4)
	v_mfma_f32_32x32x16_bf16 v[48:63], v[160:163], v[144:147], v[48:63]
	v_mfma_f32_32x32x16_bf16 v[32:47], v[160:163], v[148:151], v[32:47]
	v_mfma_f32_32x32x16_bf16 v[16:31], v[164:167], v[144:147], v[16:31]
	v_mfma_f32_32x32x16_bf16 v[0:15], v[164:167], v[148:151], v[0:15]
	ds_read_b128 v[184:187], v193 offset:4096
	ds_read_b128 v[188:191], v193 offset:6144
	v_xad_u32 v246, s32, v241, v200
	v_xad_u32 v247, s32, v245, v201
	s_add_u32 m0, s23, 0x6000
	s_nop 0
	global_load_lds_dwordx4 v246, s[94:95]
	s_add_u32 m0, s23, 0xbfc0
	s_nop 0
	global_load_lds_dwordx4 v246, s[94:95] offset:64
	s_add_u32 m0, s23, 0x6400
	s_nop 0
	global_load_lds_dwordx4 v247, s[94:95]
	s_add_u32 m0, s23, 0xc3c0
	s_nop 0
	global_load_lds_dwordx4 v247, s[94:95] offset:64
	s_add_u32 s32, s32, 0x80
	s_add_u32 s98, s98, 128
	s_addc_u32 s99, s99, 0
	s_add_u32 s100, s100, 128
	s_addc_u32 s101, s101, 0
	s_waitcnt lgkmcnt(2)
	v_mfma_f32_32x32x16_bf16 v[112:127], v[176:179], v[168:171], v[112:127]
	v_mfma_f32_32x32x16_bf16 v[96:111], v[176:179], v[172:175], v[96:111]
	v_mfma_f32_32x32x16_bf16 v[80:95], v[180:183], v[168:171], v[80:95]
	v_mfma_f32_32x32x16_bf16 v[64:79], v[180:183], v[172:175], v[64:79]
	s_waitcnt vmcnt(0) lgkmcnt(0)
	s_barrier
	ds_read_b128 v[144:147], v194 offset:24576
	ds_read_b128 v[148:151], v194 offset:26624
	ds_read_b128 v[152:155], v192 offset:24576
	ds_read_b128 v[156:159], v192 offset:26624
	ds_read_b128 v[160:163], v192 offset:28672
	ds_read_b128 v[164:167], v192 offset:30720
	v_mfma_f32_32x32x16_bf16 v[48:63], v[184:187], v[168:171], v[48:63]
	v_mfma_f32_32x32x16_bf16 v[32:47], v[184:187], v[172:175], v[32:47]
	v_mfma_f32_32x32x16_bf16 v[16:31], v[188:191], v[168:171], v[16:31]
	v_mfma_f32_32x32x16_bf16 v[0:15], v[188:191], v[172:175], v[0:15]
	s_waitcnt lgkmcnt(2)
	v_mfma_f32_32x32x16_bf16 v[112:127], v[152:155], v[144:147], v[112:127]
	v_mfma_f32_32x32x16_bf16 v[96:111], v[152:155], v[148:151], v[96:111]
	v_mfma_f32_32x32x16_bf16 v[80:95], v[156:159], v[144:147], v[80:95]
	v_mfma_f32_32x32x16_bf16 v[64:79], v[156:159], v[148:151], v[64:79]
	ds_read_b128 v[168:171], v195 offset:24576
	ds_read_b128 v[172:175], v195 offset:26624
	ds_read_b128 v[176:179], v193 offset:24576
	ds_read_b128 v[180:183], v193 offset:26624
	s_waitcnt lgkmcnt(4)
	v_mfma_f32_32x32x16_bf16 v[48:63], v[160:163], v[144:147], v[48:63]
	v_mfma_f32_32x32x16_bf16 v[32:47], v[160:163], v[148:151], v[32:47]
	v_mfma_f32_32x32x16_bf16 v[16:31], v[164:167], v[144:147], v[16:31]
	v_mfma_f32_32x32x16_bf16 v[0:15], v[164:167], v[148:151], v[0:15]
	ds_read_b128 v[184:187], v193 offset:28672
	ds_read_b128 v[188:191], v193 offset:30720
	s_waitcnt lgkmcnt(2)
	v_mfma_f32_32x32x16_bf16 v[112:127], v[176:179], v[168:171], v[112:127]
	v_mfma_f32_32x32x16_bf16 v[96:111], v[176:179], v[172:175], v[96:111]
	v_mfma_f32_32x32x16_bf16 v[80:95], v[180:183], v[168:171], v[80:95]
	v_mfma_f32_32x32x16_bf16 v[64:79], v[180:183], v[172:175], v[64:79]
	s_waitcnt vmcnt(0) lgkmcnt(0)
	s_barrier
	ds_read_b128 v[144:147], v194 offset:49152
	ds_read_b128 v[148:151], v194 offset:51200
	ds_read_b128 v[152:155], v192 offset:49152
	ds_read_b128 v[156:159], v192 offset:51200
	ds_read_b128 v[160:163], v192 offset:53248
	ds_read_b128 v[164:167], v192 offset:55296
	v_mfma_f32_32x32x16_bf16 v[48:63], v[184:187], v[168:171], v[48:63]
	v_mfma_f32_32x32x16_bf16 v[32:47], v[184:187], v[172:175], v[32:47]
	v_mfma_f32_32x32x16_bf16 v[16:31], v[188:191], v[168:171], v[16:31]
	v_mfma_f32_32x32x16_bf16 v[0:15], v[188:191], v[172:175], v[0:15]
	s_add_u32 m0, s22, 0x0
	s_nop 0
	global_load_lds_dwordx4 v196, s[98:99]
	s_add_u32 m0, s22, 0x6000
	s_nop 0
	global_load_lds_dwordx4 v196, s[100:101]
	s_add_u32 m0, s22, 0x400
	s_nop 0
	global_load_lds_dwordx4 v197, s[98:99]
	s_add_u32 m0, s22, 0x6400
	s_nop 0
	global_load_lds_dwordx4 v197, s[100:101]
	s_waitcnt lgkmcnt(2)
	v_mfma_f32_32x32x16_bf16 v[112:127], v[152:155], v[144:147], v[112:127]
	v_mfma_f32_32x32x16_bf16 v[96:111], v[152:155], v[148:151], v[96:111]
	v_mfma_f32_32x32x16_bf16 v[80:95], v[156:159], v[144:147], v[80:95]
	v_mfma_f32_32x32x16_bf16 v[64:79], v[156:159], v[148:151], v[64:79]
	ds_read_b128 v[168:171], v195 offset:49152
	ds_read_b128 v[172:175], v195 offset:51200
	ds_read_b128 v[176:179], v193 offset:49152
	ds_read_b128 v[180:183], v193 offset:51200
	s_add_u32 m0, s22, 0x800
	s_nop 0
	global_load_lds_dwordx4 v198, s[98:99]
	s_add_u32 m0, s22, 0x6800
	s_nop 0
	global_load_lds_dwordx4 v198, s[100:101]
	s_add_u32 m0, s22, 0xc00
	s_nop 0
	global_load_lds_dwordx4 v199, s[98:99]
	s_add_u32 m0, s22, 0x6c00
	s_nop 0
	global_load_lds_dwordx4 v199, s[100:101]
	s_waitcnt lgkmcnt(4)
	v_mfma_f32_32x32x16_bf16 v[48:63], v[160:163], v[144:147], v[48:63]
	v_mfma_f32_32x32x16_bf16 v[32:47], v[160:163], v[148:151], v[32:47]
	v_mfma_f32_32x32x16_bf16 v[16:31], v[164:167], v[144:147], v[16:31]
	v_mfma_f32_32x32x16_bf16 v[0:15], v[164:167], v[148:151], v[0:15]
	ds_read_b128 v[184:187], v193 offset:53248
	ds_read_b128 v[188:191], v193 offset:55296
	v_xad_u32 v246, s32, v241, v200
	v_xad_u32 v247, s32, v245, v201
	s_add_u32 m0, s23, 0x0
	s_nop 0
	global_load_lds_dwordx4 v246, s[94:95]
	s_add_u32 m0, s23, 0x5fc0
	s_nop 0
	global_load_lds_dwordx4 v246, s[94:95] offset:64
	s_add_u32 m0, s23, 0x400
	s_nop 0
	global_load_lds_dwordx4 v247, s[94:95]
	s_add_u32 m0, s23, 0x63c0
	s_nop 0
	global_load_lds_dwordx4 v247, s[94:95] offset:64
	s_add_u32 s32, s32, 0x80
	s_add_u32 s98, s98, 128
	s_addc_u32 s99, s99, 0
	s_add_u32 s100, s100, 128
	s_addc_u32 s101, s101, 0
	s_waitcnt lgkmcnt(2)
	v_mfma_f32_32x32x16_bf16 v[112:127], v[176:179], v[168:171], v[112:127]
	v_mfma_f32_32x32x16_bf16 v[96:111], v[176:179], v[172:175], v[96:111]
	v_mfma_f32_32x32x16_bf16 v[80:95], v[180:183], v[168:171], v[80:95]
	v_mfma_f32_32x32x16_bf16 v[64:79], v[180:183], v[172:175], v[64:79]
	s_waitcnt vmcnt(0) lgkmcnt(0)
	s_barrier
	ds_read_b128 v[144:147], v194 offset:0
	ds_read_b128 v[148:151], v194 offset:2048
	ds_read_b128 v[152:155], v192 offset:0
	ds_read_b128 v[156:159], v192 offset:2048
	ds_read_b128 v[160:163], v192 offset:4096
	ds_read_b128 v[164:167], v192 offset:6144
	v_mfma_f32_32x32x16_bf16 v[48:63], v[184:187], v[168:171], v[48:63]
	v_mfma_f32_32x32x16_bf16 v[32:47], v[184:187], v[172:175], v[32:47]
	v_mfma_f32_32x32x16_bf16 v[16:31], v[188:191], v[168:171], v[16:31]
	v_mfma_f32_32x32x16_bf16 v[0:15], v[188:191], v[172:175], v[0:15]
	s_waitcnt lgkmcnt(2)
	v_mfma_f32_32x32x16_bf16 v[112:127], v[152:155], v[144:147], v[112:127]
	v_mfma_f32_32x32x16_bf16 v[96:111], v[152:155], v[148:151], v[96:111]
	v_mfma_f32_32x32x16_bf16 v[80:95], v[156:159], v[144:147], v[80:95]
	v_mfma_f32_32x32x16_bf16 v[64:79], v[156:159], v[148:151], v[64:79]
	ds_read_b128 v[168:171], v195 offset:0
	ds_read_b128 v[172:175], v195 offset:2048
	ds_read_b128 v[176:179], v193 offset:0
	ds_read_b128 v[180:183], v193 offset:2048
	s_waitcnt lgkmcnt(4)
	v_mfma_f32_32x32x16_bf16 v[48:63], v[160:163], v[144:147], v[48:63]
	v_mfma_f32_32x32x16_bf16 v[32:47], v[160:163], v[148:151], v[32:47]
	v_mfma_f32_32x32x16_bf16 v[16:31], v[164:167], v[144:147], v[16:31]
	v_mfma_f32_32x32x16_bf16 v[0:15], v[164:167], v[148:151], v[0:15]
	ds_read_b128 v[184:187], v193 offset:4096
	ds_read_b128 v[188:191], v193 offset:6144
	s_waitcnt lgkmcnt(2)
	v_mfma_f32_32x32x16_bf16 v[112:127], v[176:179], v[168:171], v[112:127]
	v_mfma_f32_32x32x16_bf16 v[96:111], v[176:179], v[172:175], v[96:111]
	v_mfma_f32_32x32x16_bf16 v[80:95], v[180:183], v[168:171], v[80:95]
	v_mfma_f32_32x32x16_bf16 v[64:79], v[180:183], v[172:175], v[64:79]
	s_sub_u32 s33, s33, 1
	s_cmp_lg_u32 s33, 0
	s_cbranch_scc1 .Lp5m_kloop
	s_waitcnt vmcnt(0) lgkmcnt(0)
	s_barrier
	ds_read_b128 v[144:147], v194 offset:24576
	ds_read_b128 v[148:151], v194 offset:26624
	ds_read_b128 v[152:155], v192 offset:24576
	ds_read_b128 v[156:159], v192 offset:26624
	ds_read_b128 v[160:163], v192 offset:28672
	ds_read_b128 v[164:167], v192 offset:30720
	v_mfma_f32_32x32x16_bf16 v[48:63], v[184:187], v[168:171], v[48:63]
	v_mfma_f32_32x32x16_bf16 v[32:47], v[184:187], v[172:175], v[32:47]
	v_mfma_f32_32x32x16_bf16 v[16:31], v[188:191], v[168:171], v[16:31]
	v_mfma_f32_32x32x16_bf16 v[0:15], v[188:191], v[172:175], v[0:15]
	s_add_u32 m0, s22, 0xc000
	s_nop 0
	global_load_lds_dwordx4 v196, s[98:99]
	s_add_u32 m0, s22, 0x0
	s_nop 0
	global_load_lds_dwordx4 v196, s[100:101]
	s_add_u32 m0, s22, 0xc400
	s_nop 0
	global_load_lds_dwordx4 v197, s[98:99]
	s_add_u32 m0, s22, 0x400
	s_nop 0
	global_load_lds_dwordx4 v197, s[100:101]
	s_waitcnt lgkmcnt(2)
	v_mfma_f32_32x32x16_bf16 v[112:127], v[152:155], v[144:147], v[112:127]
	v_mfma_f32_32x32x16_bf16 v[96:111], v[152:155], v[148:151], v[96:111]
	v_mfma_f32_32x32x16_bf16 v[80:95], v[156:159], v[144:147], v[80:95]
	v_mfma_f32_32x32x16_bf16 v[64:79], v[156:159], v[148:151], v[64:79]
	ds_read_b128 v[168:171], v195 offset:24576
	ds_read_b128 v[172:175], v195 offset:26624
	ds_read_b128 v[176:179], v193 offset:24576
	ds_read_b128 v[180:183], v193 offset:26624
	s_add_u32 m0, s22, 0xc800
	s_nop 0
	global_load_lds_dwordx4 v198, s[98:99]
	s_add_u32 m0, s22, 0x800
	s_nop 0
	global_load_lds_dwordx4 v198, s[100:101]
	s_add_u32 m0, s22, 0xcc00
	s_nop 0
	global_load_lds_dwordx4 v199, s[98:99]
	s_add_u32 m0, s22, 0xc00
	s_nop 0
	global_load_lds_dwordx4 v199, s[100:101]
	s_waitcnt lgkmcnt(4)
	v_mfma_f32_32x32x16_bf16 v[48:63], v[160:163], v[144:147], v[48:63]
	v_mfma_f32_32x32x16_bf16 v[32:47], v[160:163], v[148:151], v[32:47]
	v_mfma_f32_32x32x16_bf16 v[16:31], v[164:167], v[144:147], v[16:31]
	v_mfma_f32_32x32x16_bf16 v[0:15], v[164:167], v[148:151], v[0:15]
	ds_read_b128 v[184:187], v193 offset:28672
	ds_read_b128 v[188:191], v193 offset:30720
	v_xad_u32 v246, s32, v241, v200
	v_xad_u32 v247, s32, v245, v201
	s_add_u32 m0, s23, 0xc000
	s_nop 0
	global_load_lds_dwordx4 v246, s[94:95]
	s_add_u32 m0, s23, 0xffffffc0
	s_nop 0
	global_load_lds_dwordx4 v246, s[94:95] offset:64
	s_add_u32 m0, s23, 0xc400
	s_nop 0
	global_load_lds_dwordx4 v247, s[94:95]
	s_add_u32 m0, s23, 0x3c0
	s_nop 0
	global_load_lds_dwordx4 v247, s[94:95] offset:64
	s_add_u32 s32, s32, 0x80
	s_add_u32 s98, s98, 128
	s_addc_u32 s99, s99, 0
	s_add_u32 s100, s100, 128
	s_addc_u32 s101, s101, 0
	s_waitcnt lgkmcnt(2)
	v_mfma_f32_32x32x16_bf16 v[112:127], v[176:179], v[168:171], v[112:127]
	v_mfma_f32_32x32x16_bf16 v[96:111], v[176:179], v[172:175], v[96:111]
	v_mfma_f32_32x32x16_bf16 v[80:95], v[180:183], v[168:171], v[80:95]
	v_mfma_f32_32x32x16_bf16 v[64:79], v[180:183], v[172:175], v[64:79]
	s_waitcnt vmcnt(0) lgkmcnt(0)
	s_barrier
	ds_read_b128 v[144:147], v194 offset:49152
	ds_read_b128 v[148:151], v194 offset:51200
	ds_read_b128 v[152:155], v192 offset:49152
	ds_read_b128 v[156:159], v192 offset:51200
	ds_read_b128 v[160:163], v192 offset:53248
	ds_read_b128 v[164:167], v192 offset:55296
	v_mfma_f32_32x32x16_bf16 v[48:63], v[184:187], v[168:171], v[48:63]
	v_mfma_f32_32x32x16_bf16 v[32:47], v[184:187], v[172:175], v[32:47]
	v_mfma_f32_32x32x16_bf16 v[16:31], v[188:191], v[168:171], v[16:31]
	v_mfma_f32_32x32x16_bf16 v[0:15], v[188:191], v[172:175], v[0:15]
	s_waitcnt lgkmcnt(2)
	v_mfma_f32_32x32x16_bf16 v[112:127], v[152:155], v[144:147], v[112:127]
	v_mfma_f32_32x32x16_bf16 v[96:111], v[152:155], v[148:151], v[96:111]
	v_mfma_f32_32x32x16_bf16 v[80:95], v[156:159], v[144:147], v[80:95]
	v_mfma_f32_32x32x16_bf16 v[64:79], v[156:159], v[148:151], v[64:79]
	ds_read_b128 v[168:171], v195 offset:49152
	ds_read_b128 v[172:175], v195 offset:51200
	ds_read_b128 v[176:179], v193 offset:49152
	ds_read_b128 v[180:183], v193 offset:51200
	s_waitcnt lgkmcnt(4)
	v_mfma_f32_32x32x16_bf16 v[48:63], v[160:163], v[144:147], v[48:63]
	v_mfma_f32_32x32x16_bf16 v[32:47], v[160:163], v[148:151], v[32:47]
	v_mfma_f32_32x32x16_bf16 v[16:31], v[164:167], v[144:147], v[16:31]
	v_mfma_f32_32x32x16_bf16 v[0:15], v[164:167], v[148:151], v[0:15]
	ds_read_b128 v[184:187], v193 offset:53248
	ds_read_b128 v[188:191], v193 offset:55296
	s_waitcnt lgkmcnt(2)
	v_mfma_f32_32x32x16_bf16 v[112:127], v[176:179], v[168:171], v[112:127]
	v_mfma_f32_32x32x16_bf16 v[96:111], v[176:179], v[172:175], v[96:111]
	v_mfma_f32_32x32x16_bf16 v[80:95], v[180:183], v[168:171], v[80:95]
	v_mfma_f32_32x32x16_bf16 v[64:79], v[180:183], v[172:175], v[64:79]
	s_waitcnt vmcnt(0) lgkmcnt(0)
	s_barrier
	ds_read_b128 v[144:147], v194 offset:0
	ds_read_b128 v[148:151], v194 offset:2048
	ds_read_b128 v[152:155], v192 offset:0
	ds_read_b128 v[156:159], v192 offset:2048
	ds_read_b128 v[160:163], v192 offset:4096
	ds_read_b128 v[164:167], v192 offset:6144
	v_mfma_f32_32x32x16_bf16 v[48:63], v[184:187], v[168:171], v[48:63]
	v_mfma_f32_32x32x16_bf16 v[32:47], v[184:187], v[172:175], v[32:47]
	v_mfma_f32_32x32x16_bf16 v[16:31], v[188:191], v[168:171], v[16:31]
	v_mfma_f32_32x32x16_bf16 v[0:15], v[188:191], v[172:175], v[0:15]
	s_waitcnt lgkmcnt(2)
	v_mfma_f32_32x32x16_bf16 v[112:127], v[152:155], v[144:147], v[112:127]
	v_mfma_f32_32x32x16_bf16 v[96:111], v[152:155], v[148:151], v[96:111]
	v_mfma_f32_32x32x16_bf16 v[80:95], v[156:159], v[144:147], v[80:95]
	v_mfma_f32_32x32x16_bf16 v[64:79], v[156:159], v[148:151], v[64:79]
	ds_read_b128 v[168:171], v195 offset:0
	ds_read_b128 v[172:175], v195 offset:2048
	ds_read_b128 v[176:179], v193 offset:0
	ds_read_b128 v[180:183], v193 offset:2048
	s_waitcnt lgkmcnt(4)
	v_mfma_f32_32x32x16_bf16 v[48:63], v[160:163], v[144:147], v[48:63]
	v_mfma_f32_32x32x16_bf16 v[32:47], v[160:163], v[148:151], v[32:47]
	v_mfma_f32_32x32x16_bf16 v[16:31], v[164:167], v[144:147], v[16:31]
	v_mfma_f32_32x32x16_bf16 v[0:15], v[164:167], v[148:151], v[0:15]
	ds_read_b128 v[184:187], v193 offset:4096
	ds_read_b128 v[188:191], v193 offset:6144
	s_waitcnt lgkmcnt(2)
	v_mfma_f32_32x32x16_bf16 v[112:127], v[176:179], v[168:171], v[112:127]
	v_mfma_f32_32x32x16_bf16 v[96:111], v[176:179], v[172:175], v[96:111]
	v_mfma_f32_32x32x16_bf16 v[80:95], v[180:183], v[168:171], v[80:95]
	v_mfma_f32_32x32x16_bf16 v[64:79], v[180:183], v[172:175], v[64:79]
	s_waitcnt lgkmcnt(0)
	v_mfma_f32_32x32x16_bf16 v[48:63], v[184:187], v[168:171], v[48:63]
	v_mfma_f32_32x32x16_bf16 v[32:47], v[184:187], v[172:175], v[32:47]
	v_mfma_f32_32x32x16_bf16 v[16:31], v[188:191], v[168:171], v[16:31]
	v_mfma_f32_32x32x16_bf16 v[0:15], v[188:191], v[172:175], v[0:15]
	s_load_dwordx16 s[60:75], s[0:1], 0x0
	v_add_u32_e32 v128, 0xffffe000, v132
	v_lshlrev_b64 v[134:135], 2, v[130:131]
	v_lshlrev_b64 v[132:133], 13, v[128:129]
	v_cmp_gt_i32_e32 vcc, 32, v138
	s_waitcnt lgkmcnt(0)
	v_lshl_add_u64 v[136:137], s[60:61], 0, v[134:135]
	v_lshl_add_u64 v[132:133], s[62:63], 0, v[132:133]
	v_lshlrev_b64 v[130:131], 1, v[130:131]
	v_cndmask_b32_e32 v133, v133, v137, vcc
	v_cndmask_b32_e32 v132, v132, v136, vcc
	v_lshl_add_u64 v[136:137], s[8:9], 0, v[130:131]
	v_mov_b32_e32 v130, v204
	s_waitcnt vmcnt(0)
	s_barrier
	s_load_dwordx16 s[60:75], s[0:1], 0xc0
	s_lshl_b32 s40, s40, 7
	v_and_b32_e32 v131, 0x1fff80, v130
	v_and_b32_e32 v138, 0x5f, v130
	v_lshrrev_b32_e32 v130, 3, v130
	v_and_or_b32 v130, v130, 4, v131
	s_ashr_i32 s41, s40, 31
	v_lshl_or_b32 v130, v130, 11, v138
	s_lshl_b64 s[42:43], s[40:41], 2
	v_ashrrev_i32_e32 v131, 31, v130
	v_lshl_add_u64 v[132:133], v[132:133], 0, s[42:43]
	s_waitcnt lgkmcnt(0)
	s_add_u32 s22, s66, s42
	v_lshlrev_b64 v[140:141], 2, v[130:131]
	s_addc_u32 s23, s67, s43
	v_lshlrev_b32_e32 v128, 2, v138
	v_lshl_add_u64 v[138:139], v[132:133], 0, v[140:141]
	v_or_b32_e32 v188, 0x800, v130
	global_load_dword v209, v128, s[22:23]
	s_nop 0
	global_load_dword v128, v128, s[22:23] offset:128
	v_ashrrev_i32_e32 v189, 31, v188
	global_load_dword v142, v[138:139], off
	v_lshlrev_b64 v[202:203], 2, v[188:189]
	v_lshl_add_u64 v[144:145], v[132:133], 0, v[202:203]
	v_or_b32_e32 v184, 0x1000, v130
	global_load_dword v240, v[144:145], off
	v_ashrrev_i32_e32 v185, 31, v184
	v_lshlrev_b64 v[200:201], 2, v[184:185]
	v_lshl_add_u64 v[144:145], v[132:133], 0, v[200:201]
	v_or_b32_e32 v178, 0x1800, v130
	global_load_dword v239, v[144:145], off
	v_ashrrev_i32_e32 v179, 31, v178
	v_lshlrev_b64 v[198:199], 2, v[178:179]
	v_lshl_add_u64 v[144:145], v[132:133], 0, v[198:199]
	v_or_b32_e32 v174, 0x4000, v130
	global_load_dword v238, v[144:145], off
	v_ashrrev_i32_e32 v175, 31, v174
	v_lshlrev_b64 v[196:197], 2, v[174:175]
	v_lshl_add_u64 v[144:145], v[132:133], 0, v[196:197]
	v_or_b32_e32 v170, 0x4800, v130
	global_load_dword v237, v[144:145], off
	v_ashrrev_i32_e32 v171, 31, v170
	v_lshlrev_b64 v[194:195], 2, v[170:171]
	v_lshl_add_u64 v[144:145], v[132:133], 0, v[194:195]
	v_or_b32_e32 v166, 0x5000, v130
	global_load_dword v236, v[144:145], off
	v_ashrrev_i32_e32 v167, 31, v166
	v_lshlrev_b64 v[192:193], 2, v[166:167]
	v_lshl_add_u64 v[144:145], v[132:133], 0, v[192:193]
	v_or_b32_e32 v162, 0x5800, v130
	global_load_dword v235, v[144:145], off
	v_ashrrev_i32_e32 v163, 31, v162
	v_lshlrev_b64 v[190:191], 2, v[162:163]
	v_lshl_add_u64 v[144:145], v[132:133], 0, v[190:191]
	v_or_b32_e32 v158, 0x8000, v130
	global_load_dword v233, v[144:145], off
	v_ashrrev_i32_e32 v159, 31, v158
	v_lshlrev_b64 v[186:187], 2, v[158:159]
	v_lshl_add_u64 v[144:145], v[132:133], 0, v[186:187]
	v_or_b32_e32 v154, 0x8800, v130
	global_load_dword v232, v[144:145], off
	v_ashrrev_i32_e32 v155, 31, v154
	v_lshlrev_b64 v[180:181], 2, v[154:155]
	v_lshl_add_u64 v[144:145], v[132:133], 0, v[180:181]
	v_or_b32_e32 v152, 0x9000, v130
	global_load_dword v230, v[144:145], off
	v_ashrrev_i32_e32 v153, 31, v152
	v_lshlrev_b64 v[176:177], 2, v[152:153]
	v_lshl_add_u64 v[144:145], v[132:133], 0, v[176:177]
	v_or_b32_e32 v150, 0x9800, v130
	global_load_dword v229, v[144:145], off
	v_ashrrev_i32_e32 v151, 31, v150
	v_lshlrev_b64 v[172:173], 2, v[150:151]
	v_lshl_add_u64 v[144:145], v[132:133], 0, v[172:173]
	v_or_b32_e32 v148, 0xc000, v130
	global_load_dword v228, v[144:145], off
	v_ashrrev_i32_e32 v149, 31, v148
	v_or_b32_e32 v146, 0xc800, v130
	v_lshlrev_b64 v[168:169], 2, v[148:149]
	v_ashrrev_i32_e32 v147, 31, v146
	v_lshl_add_u64 v[144:145], v[132:133], 0, v[168:169]
	v_lshlrev_b64 v[164:165], 2, v[146:147]
	global_load_dword v227, v[144:145], off
	v_lshl_add_u64 v[144:145], v[132:133], 0, v[164:165]
	global_load_dword v226, v[144:145], off
	v_or_b32_e32 v144, 0xd000, v130
	v_ashrrev_i32_e32 v145, 31, v144
	v_lshlrev_b64 v[160:161], 2, v[144:145]
	v_lshl_add_u64 v[156:157], v[132:133], 0, v[160:161]
	global_load_dword v234, v[156:157], off
	v_or_b32_e32 v156, 0xd800, v130
	v_ashrrev_i32_e32 v157, 31, v156
	v_lshlrev_b64 v[182:183], 2, v[156:157]
	v_lshl_add_u64 v[210:211], v[132:133], 0, v[182:183]
	global_load_dword v231, v[210:211], off
	s_lshl_b64 s[22:23], s[40:41], 1
	v_lshl_add_u64 v[136:137], v[136:137], 0, s[22:23]
	s_movk_i32 s22, 0x2000
	v_add_co_u32_e32 v212, vcc, s22, v138
	s_movk_i32 s22, 0x4000
	s_nop 0
	v_addc_co_u32_e32 v213, vcc, 0, v139, vcc
	global_load_dword v210, v[138:139], off offset:128
	global_load_dword v211, v[212:213], off offset:128
	v_add_co_u32_e32 v212, vcc, s22, v138
	s_movk_i32 s22, 0x6000
	s_nop 0
	v_addc_co_u32_e32 v213, vcc, 0, v139, vcc
	v_add_co_u32_e32 v214, vcc, s22, v138
	s_mov_b32 s22, 0x10000
	s_nop 0
	v_addc_co_u32_e32 v215, vcc, 0, v139, vcc
	global_load_dword v212, v[212:213], off offset:128
	v_lshl_add_u64 v[134:135], s[92:93], 0, v[134:135]
	global_load_dword v213, v[214:215], off offset:128
	v_add_co_u32_e32 v214, vcc, s22, v138
	s_mov_b32 s22, 0x12000
	s_nop 0
	v_addc_co_u32_e32 v215, vcc, 0, v139, vcc
	v_add_co_u32_e32 v216, vcc, s22, v138
	s_mov_b32 s22, 0x14000
	s_nop 0
	v_addc_co_u32_e32 v217, vcc, 0, v139, vcc
	global_load_dword v214, v[214:215], off offset:128
	v_lshl_add_u64 v[134:135], v[134:135], 0, s[42:43]
	global_load_dword v215, v[216:217], off offset:128
	v_add_co_u32_e32 v216, vcc, s22, v138
	s_mov_b32 s22, 0x16000
	s_nop 0
	v_addc_co_u32_e32 v217, vcc, 0, v139, vcc
	v_add_co_u32_e32 v218, vcc, s22, v138
	s_mov_b32 s22, 0x20000
	s_nop 0
	v_addc_co_u32_e32 v219, vcc, 0, v139, vcc
	global_load_dword v216, v[216:217], off offset:128
	s_waitcnt vmcnt(22)
	v_add_f32_e32 v112, v112, v142
	global_load_dword v220, v[218:219], off offset:128
	v_add_co_u32_e32 v218, vcc, s22, v138
	s_mov_b32 s22, 0x22000
	s_nop 0
	v_addc_co_u32_e32 v219, vcc, 0, v139, vcc
	global_load_dword v221, v[218:219], off offset:128
	v_add_co_u32_e32 v218, vcc, s22, v138
	s_mov_b32 s22, 0x24000
	s_nop 0
	v_addc_co_u32_e32 v219, vcc, 0, v139, vcc
	global_load_dword v223, v[218:219], off offset:128
	v_add_co_u32_e32 v218, vcc, s22, v138
	s_mov_b32 s22, 0x26000
	s_nop 0
	v_addc_co_u32_e32 v219, vcc, 0, v139, vcc
	global_load_dword v224, v[218:219], off offset:128
	v_add_co_u32_e32 v218, vcc, s22, v138
	s_mov_b32 s22, 0x30000
	s_nop 0
	v_addc_co_u32_e32 v219, vcc, 0, v139, vcc
	global_load_dword v225, v[218:219], off offset:128
	v_add_co_u32_e32 v218, vcc, s22, v138
	s_mov_b32 s22, 0x32000
	s_nop 0
	v_addc_co_u32_e32 v219, vcc, 0, v139, vcc
	global_load_dword v222, v[218:219], off offset:128
	v_add_co_u32_e32 v218, vcc, s22, v138
	s_mov_b32 s22, 0x34000
	s_nop 0
	v_addc_co_u32_e32 v219, vcc, 0, v139, vcc
	v_add_co_u32_e32 v242, vcc, s22, v138
	s_mov_b32 s22, 0x36000
	s_nop 0
	v_addc_co_u32_e32 v243, vcc, 0, v139, vcc
	global_load_dword v218, v[218:219], off offset:128
	v_lshl_add_u64 v[140:141], v[134:135], 0, v[140:141]
	global_load_dword v217, v[242:243], off offset:128
	v_add_co_u32_e32 v242, vcc, s22, v138
	v_lshl_add_u64 v[142:143], v[130:131], 1, v[136:137]
	s_nop 0
	v_addc_co_u32_e32 v243, vcc, 0, v139, vcc
	global_load_dword v219, v[242:243], off offset:128
	s_waitcnt vmcnt(30)
	v_add_f32_e32 v131, v113, v240
	global_store_dword v[140:141], v112, off
	v_mul_f32_e32 v112, v209, v112
	v_cvt_pk_bf16_f32 v112, v112, s0
	global_store_short v[142:143], v112, off
	v_lshl_add_u64 v[112:113], v[134:135], 0, v[202:203]
	global_store_dword v[112:113], v131, off
	v_mul_f32_e32 v112, v209, v131
	v_cvt_pk_bf16_f32 v131, v112, s0
	v_lshl_add_u64 v[112:113], v[188:189], 1, v[136:137]
	global_store_short v[112:113], v131, off
	s_waitcnt vmcnt(33)
	v_add_f32_e32 v114, v114, v239
	v_lshl_add_u64 v[112:113], v[134:135], 0, v[200:201]
	global_store_dword v[112:113], v114, off
	v_mul_f32_e32 v112, v209, v114
	v_cvt_pk_bf16_f32 v114, v112, s0
	v_lshl_add_u64 v[112:113], v[184:185], 1, v[136:137]
	global_store_short v[112:113], v114, off
	s_waitcnt vmcnt(34)
	v_add_f32_e32 v114, v115, v238
	v_lshl_add_u64 v[112:113], v[134:135], 0, v[198:199]
	global_store_dword v[112:113], v114, off
	v_mul_f32_e32 v112, v209, v114
	v_cvt_pk_bf16_f32 v114, v112, s0
	v_lshl_add_u64 v[112:113], v[178:179], 1, v[136:137]
	global_store_short v[112:113], v114, off
	s_waitcnt vmcnt(35)
	v_add_f32_e32 v114, v116, v237
	v_lshl_add_u64 v[112:113], v[134:135], 0, v[196:197]
	global_store_dword v[112:113], v114, off
	v_mul_f32_e32 v112, v209, v114
	v_cvt_pk_bf16_f32 v114, v112, s0
	v_lshl_add_u64 v[112:113], v[174:175], 1, v[136:137]
	global_store_short v[112:113], v114, off
	s_waitcnt vmcnt(36)
	v_add_f32_e32 v114, v117, v236
	v_lshl_add_u64 v[112:113], v[134:135], 0, v[194:195]
	global_store_dword v[112:113], v114, off
	v_mul_f32_e32 v112, v209, v114
	v_cvt_pk_bf16_f32 v114, v112, s0
	v_lshl_add_u64 v[112:113], v[170:171], 1, v[136:137]
	global_store_short v[112:113], v114, off
	s_waitcnt vmcnt(37)
	v_add_f32_e32 v114, v118, v235
	v_lshl_add_u64 v[112:113], v[134:135], 0, v[192:193]
	global_store_dword v[112:113], v114, off
	v_mul_f32_e32 v112, v209, v114
	v_cvt_pk_bf16_f32 v114, v112, s0
	v_lshl_add_u64 v[112:113], v[166:167], 1, v[136:137]
	global_store_short v[112:113], v114, off
	s_waitcnt vmcnt(38)
	v_add_f32_e32 v114, v119, v233
	v_lshl_add_u64 v[112:113], v[134:135], 0, v[190:191]
	global_store_dword v[112:113], v114, off
	v_mul_f32_e32 v112, v209, v114
	v_cvt_pk_bf16_f32 v114, v112, s0
	v_lshl_add_u64 v[112:113], v[162:163], 1, v[136:137]
	global_store_short v[112:113], v114, off
	s_waitcnt vmcnt(39)
	v_add_f32_e32 v114, v120, v232
	v_lshl_add_u64 v[112:113], v[134:135], 0, v[186:187]
	global_store_dword v[112:113], v114, off
	v_mul_f32_e32 v112, v209, v114
	v_cvt_pk_bf16_f32 v114, v112, s0
	v_lshl_add_u64 v[112:113], v[158:159], 1, v[136:137]
	global_store_short v[112:113], v114, off
	s_waitcnt vmcnt(40)
	v_add_f32_e32 v114, v121, v230
	v_lshl_add_u64 v[112:113], v[134:135], 0, v[180:181]
	global_store_dword v[112:113], v114, off
	v_mul_f32_e32 v112, v209, v114
	v_cvt_pk_bf16_f32 v114, v112, s0
	v_lshl_add_u64 v[112:113], v[154:155], 1, v[136:137]
	global_store_short v[112:113], v114, off
	s_waitcnt vmcnt(41)
	v_add_f32_e32 v114, v122, v229
	v_lshl_add_u64 v[112:113], v[134:135], 0, v[176:177]
	global_store_dword v[112:113], v114, off
	v_mul_f32_e32 v112, v209, v114
	v_cvt_pk_bf16_f32 v114, v112, s0
	v_lshl_add_u64 v[112:113], v[152:153], 1, v[136:137]
	global_store_short v[112:113], v114, off
	s_waitcnt vmcnt(42)
	v_add_f32_e32 v114, v123, v228
	v_lshl_add_u64 v[112:113], v[134:135], 0, v[172:173]
	global_store_dword v[112:113], v114, off
	v_mul_f32_e32 v112, v209, v114
	v_cvt_pk_bf16_f32 v114, v112, s0
	v_lshl_add_u64 v[112:113], v[150:151], 1, v[136:137]
	global_store_short v[112:113], v114, off
	s_waitcnt vmcnt(43)
	v_add_f32_e32 v114, v124, v227
	v_lshl_add_u64 v[112:113], v[134:135], 0, v[168:169]
	global_store_dword v[112:113], v114, off
	v_mul_f32_e32 v112, v209, v114
	v_cvt_pk_bf16_f32 v114, v112, s0
	v_lshl_add_u64 v[112:113], v[148:149], 1, v[136:137]
	global_store_short v[112:113], v114, off
	s_waitcnt vmcnt(44)
	v_add_f32_e32 v114, v125, v226
	v_lshl_add_u64 v[112:113], v[134:135], 0, v[164:165]
	global_store_dword v[112:113], v114, off
	v_mul_f32_e32 v112, v209, v114
	v_cvt_pk_bf16_f32 v114, v112, s0
	v_lshl_add_u64 v[112:113], v[146:147], 1, v[136:137]
	global_store_short v[112:113], v114, off
	s_waitcnt vmcnt(45)
	v_add_f32_e32 v114, v126, v234
	v_lshl_add_u64 v[112:113], v[134:135], 0, v[160:161]
	global_store_dword v[112:113], v114, off
	v_mul_f32_e32 v112, v209, v114
	v_cvt_pk_bf16_f32 v114, v112, s0
	v_lshl_add_u64 v[112:113], v[144:145], 1, v[136:137]
	global_store_short v[112:113], v114, off
	s_waitcnt vmcnt(46)
	v_add_f32_e32 v114, v127, v231
	v_lshl_add_u64 v[112:113], v[134:135], 0, v[182:183]
	global_store_dword v[112:113], v114, off
	v_mul_f32_e32 v112, v209, v114
	v_cvt_pk_bf16_f32 v114, v112, s0
	v_lshl_add_u64 v[112:113], v[156:157], 1, v[136:137]
	s_mov_b32 s22, 0x40000
	global_store_short v[112:113], v114, off
	v_add_co_u32_e32 v112, vcc, s22, v138
	s_mov_b32 s22, 0x42000
	s_nop 0
	v_addc_co_u32_e32 v113, vcc, 0, v139, vcc
	global_load_dword v148, v[112:113], off
	v_add_co_u32_e32 v112, vcc, s22, v138
	s_mov_b32 s22, 0x44000
	s_nop 0
	v_addc_co_u32_e32 v113, vcc, 0, v139, vcc
	v_add_co_u32_e32 v114, vcc, s22, v138
	s_mov_b32 s22, 0x46000
	s_nop 0
	v_addc_co_u32_e32 v115, vcc, 0, v139, vcc
	v_add_co_u32_e32 v116, vcc, s22, v138
	s_mov_b32 s22, 0x50000
	s_nop 0
	v_addc_co_u32_e32 v117, vcc, 0, v139, vcc
	v_add_co_u32_e32 v118, vcc, s22, v138
	s_mov_b32 s22, 0x52000
	s_nop 0
	v_addc_co_u32_e32 v119, vcc, 0, v139, vcc
	v_add_co_u32_e32 v120, vcc, s22, v138
	s_mov_b32 s22, 0x54000
	s_nop 0
	v_addc_co_u32_e32 v121, vcc, 0, v139, vcc
	v_add_co_u32_e32 v122, vcc, s22, v138
	s_mov_b32 s22, 0x56000
	s_nop 0
	v_addc_co_u32_e32 v123, vcc, 0, v139, vcc
	v_add_co_u32_e32 v124, vcc, s22, v138
	s_mov_b32 s22, 0x60000
	s_nop 0
	v_addc_co_u32_e32 v125, vcc, 0, v139, vcc
	v_add_co_u32_e32 v126, vcc, s22, v138
	s_mov_b32 s22, 0x62000
	s_nop 0
	v_addc_co_u32_e32 v127, vcc, 0, v139, vcc
	v_add_co_u32_e32 v144, vcc, s22, v138
	s_mov_b32 s22, 0x64000
	s_nop 0
	v_addc_co_u32_e32 v145, vcc, 0, v139, vcc
	v_add_co_u32_e32 v146, vcc, s22, v138
	s_mov_b32 s22, 0x66000
	s_nop 0
	v_addc_co_u32_e32 v147, vcc, 0, v139, vcc
	v_add_co_u32_e32 v150, vcc, s22, v138
	s_mov_b32 s22, 0x70000
	s_nop 0
	v_addc_co_u32_e32 v151, vcc, 0, v139, vcc
	v_add_co_u32_e32 v152, vcc, s22, v138
	s_mov_b32 s22, 0x72000
	s_nop 0
	v_addc_co_u32_e32 v153, vcc, 0, v139, vcc
	v_add_co_u32_e32 v154, vcc, s22, v138
	s_mov_b32 s22, 0x74000
	s_nop 0
	v_addc_co_u32_e32 v155, vcc, 0, v139, vcc
	v_add_co_u32_e32 v156, vcc, s22, v138
	s_mov_b32 s22, 0x76000
	s_nop 0
	v_addc_co_u32_e32 v157, vcc, 0, v139, vcc
	v_add_co_u32_e32 v158, vcc, s22, v138
	s_waitcnt vmcnt(48)
	v_add_f32_e32 v96, v96, v210
	v_addc_co_u32_e32 v159, vcc, 0, v139, vcc
	global_load_dword v149, v[112:113], off
	global_load_dword v160, v[114:115], off
	global_load_dword v161, v[116:117], off
	global_load_dword v162, v[118:119], off
	global_load_dword v163, v[120:121], off
	global_load_dword v164, v[122:123], off
	global_load_dword v165, v[124:125], off
	global_load_dword v166, v[126:127], off
	global_load_dword v167, v[144:145], off
	global_load_dword v168, v[146:147], off
	global_load_dword v169, v[150:151], off
	global_load_dword v170, v[152:153], off
	global_load_dword v171, v[154:155], off
	global_load_dword v172, v[156:157], off
	global_load_dword v173, v[158:159], off
	s_waitcnt vmcnt(62)
	v_add_f32_e32 v131, v97, v211
	global_store_dword v[140:141], v96, off offset:128
	v_mul_f32_e32 v96, v128, v96
	v_cvt_pk_bf16_f32 v96, v96, s0
	global_store_short v[142:143], v96, off offset:64
	v_or_b32_e32 v96, 0x820, v130
	v_ashrrev_i32_e32 v97, 31, v96
	v_lshl_add_u64 v[140:141], v[96:97], 2, v[134:135]
	global_store_dword v[140:141], v131, off
	v_mul_f32_e32 v131, v128, v131
	v_cvt_pk_bf16_f32 v131, v131, s0
	v_lshl_add_u64 v[96:97], v[96:97], 1, v[136:137]
	global_store_short v[96:97], v131, off
	v_or_b32_e32 v96, 0x1020, v130
	v_ashrrev_i32_e32 v97, 31, v96
	s_waitcnt vmcnt(62)
	v_add_f32_e32 v98, v98, v212
	v_lshl_add_u64 v[140:141], v[96:97], 2, v[134:135]
	global_store_dword v[140:141], v98, off
	v_mul_f32_e32 v98, v128, v98
	v_cvt_pk_bf16_f32 v98, v98, s0
	v_lshl_add_u64 v[96:97], v[96:97], 1, v[136:137]
	global_store_short v[96:97], v98, off
	v_or_b32_e32 v96, 0x1820, v130
	v_ashrrev_i32_e32 v97, 31, v96
	v_add_f32_e32 v131, v99, v213
	v_lshl_add_u64 v[98:99], v[96:97], 2, v[134:135]
	global_store_dword v[98:99], v131, off
	v_mul_f32_e32 v98, v128, v131
	v_cvt_pk_bf16_f32 v98, v98, s0
	v_lshl_add_u64 v[96:97], v[96:97], 1, v[136:137]
	global_store_short v[96:97], v98, off
	v_or_b32_e32 v96, 0x4020, v130
	v_ashrrev_i32_e32 v97, 31, v96
	v_add_f32_e32 v100, v100, v214
	v_lshl_add_u64 v[98:99], v[96:97], 2, v[134:135]
	global_store_dword v[98:99], v100, off
	v_mul_f32_e32 v98, v128, v100
	v_cvt_pk_bf16_f32 v98, v98, s0
	v_lshl_add_u64 v[96:97], v[96:97], 1, v[136:137]
	global_store_short v[96:97], v98, off
	v_or_b32_e32 v96, 0x4820, v130
	v_ashrrev_i32_e32 v97, 31, v96
	v_add_f32_e32 v100, v101, v215
	v_lshl_add_u64 v[98:99], v[96:97], 2, v[134:135]
	global_store_dword v[98:99], v100, off
	v_mul_f32_e32 v98, v128, v100
	v_cvt_pk_bf16_f32 v98, v98, s0
	v_lshl_add_u64 v[96:97], v[96:97], 1, v[136:137]
	global_store_short v[96:97], v98, off
	v_or_b32_e32 v96, 0x5020, v130
	v_ashrrev_i32_e32 v97, 31, v96
	s_waitcnt vmcnt(62)
	v_add_f32_e32 v100, v102, v216
	v_lshl_add_u64 v[98:99], v[96:97], 2, v[134:135]
	global_store_dword v[98:99], v100, off
	v_mul_f32_e32 v98, v128, v100
	v_cvt_pk_bf16_f32 v98, v98, s0
	v_lshl_add_u64 v[96:97], v[96:97], 1, v[136:137]
	global_store_short v[96:97], v98, off
	v_or_b32_e32 v96, 0x5820, v130
	v_ashrrev_i32_e32 v97, 31, v96
	v_add_f32_e32 v100, v103, v220
	v_lshl_add_u64 v[98:99], v[96:97], 2, v[134:135]
	global_store_dword v[98:99], v100, off
	v_mul_f32_e32 v98, v128, v100
	v_cvt_pk_bf16_f32 v98, v98, s0
	v_lshl_add_u64 v[96:97], v[96:97], 1, v[136:137]
	global_store_short v[96:97], v98, off
	v_or_b32_e32 v96, 0x8020, v130
	v_ashrrev_i32_e32 v97, 31, v96
	v_add_f32_e32 v100, v104, v221
	v_lshl_add_u64 v[98:99], v[96:97], 2, v[134:135]
	global_store_dword v[98:99], v100, off
	v_mul_f32_e32 v98, v128, v100
	v_cvt_pk_bf16_f32 v98, v98, s0
	v_lshl_add_u64 v[96:97], v[96:97], 1, v[136:137]
	global_store_short v[96:97], v98, off
	v_or_b32_e32 v96, 0x8820, v130
	v_ashrrev_i32_e32 v97, 31, v96
	v_add_f32_e32 v100, v105, v223
	v_lshl_add_u64 v[98:99], v[96:97], 2, v[134:135]
	global_store_dword v[98:99], v100, off
	v_mul_f32_e32 v98, v128, v100
	v_cvt_pk_bf16_f32 v98, v98, s0
	v_lshl_add_u64 v[96:97], v[96:97], 1, v[136:137]
	global_store_short v[96:97], v98, off
	v_or_b32_e32 v96, 0x9020, v130
	v_ashrrev_i32_e32 v97, 31, v96
	v_add_f32_e32 v100, v106, v224
	v_lshl_add_u64 v[98:99], v[96:97], 2, v[134:135]
	global_store_dword v[98:99], v100, off
	v_mul_f32_e32 v98, v128, v100
	v_cvt_pk_bf16_f32 v98, v98, s0
	v_lshl_add_u64 v[96:97], v[96:97], 1, v[136:137]
	global_store_short v[96:97], v98, off
	v_or_b32_e32 v96, 0x9820, v130
	v_ashrrev_i32_e32 v97, 31, v96
	v_add_f32_e32 v100, v107, v225
	v_lshl_add_u64 v[98:99], v[96:97], 2, v[134:135]
	global_store_dword v[98:99], v100, off
	v_mul_f32_e32 v98, v128, v100
	v_cvt_pk_bf16_f32 v98, v98, s0
	v_lshl_add_u64 v[96:97], v[96:97], 1, v[136:137]
	global_store_short v[96:97], v98, off
	v_or_b32_e32 v96, 0xc020, v130
	v_ashrrev_i32_e32 v97, 31, v96
	v_add_f32_e32 v100, v108, v222
	v_lshl_add_u64 v[98:99], v[96:97], 2, v[134:135]
	global_store_dword v[98:99], v100, off
	v_mul_f32_e32 v98, v128, v100
	v_cvt_pk_bf16_f32 v98, v98, s0
	v_lshl_add_u64 v[96:97], v[96:97], 1, v[136:137]
	global_store_short v[96:97], v98, off
	v_or_b32_e32 v96, 0xc820, v130
	v_ashrrev_i32_e32 v97, 31, v96
	v_add_f32_e32 v100, v109, v218
	v_lshl_add_u64 v[98:99], v[96:97], 2, v[134:135]
	global_store_dword v[98:99], v100, off
	v_mul_f32_e32 v98, v128, v100
	v_cvt_pk_bf16_f32 v98, v98, s0
	v_lshl_add_u64 v[96:97], v[96:97], 1, v[136:137]
	global_store_short v[96:97], v98, off
	v_or_b32_e32 v96, 0xd020, v130
	v_ashrrev_i32_e32 v97, 31, v96
	s_waitcnt vmcnt(62)
	v_add_f32_e32 v100, v110, v217
	v_lshl_add_u64 v[98:99], v[96:97], 2, v[134:135]
	global_store_dword v[98:99], v100, off
	v_mul_f32_e32 v98, v128, v100
	v_cvt_pk_bf16_f32 v98, v98, s0
	v_lshl_add_u64 v[96:97], v[96:97], 1, v[136:137]
	global_store_short v[96:97], v98, off
	v_or_b32_e32 v96, 0xd820, v130
	v_ashrrev_i32_e32 v97, 31, v96
	v_add_f32_e32 v100, v111, v219
	v_lshl_add_u64 v[98:99], v[96:97], 2, v[134:135]
	global_store_dword v[98:99], v100, off
	v_mul_f32_e32 v98, v128, v100
	v_cvt_pk_bf16_f32 v98, v98, s0
	v_lshl_add_u64 v[96:97], v[96:97], 1, v[136:137]
	global_store_short v[96:97], v98, off
	v_or_b32_e32 v96, 0x10000, v130
	v_ashrrev_i32_e32 v97, 31, v96
	v_lshlrev_b64 v[140:141], 2, v[96:97]
	v_lshl_add_u64 v[98:99], v[132:133], 0, v[140:141]
	global_load_dword v131, v[98:99], off offset:128
	s_nop 0
	global_load_dword v112, v[112:113], off offset:128
	s_nop 0
	global_load_dword v111, v[114:115], off offset:128
	global_load_dword v110, v[116:117], off offset:128
	global_load_dword v109, v[118:119], off offset:128
	global_load_dword v108, v[120:121], off offset:128
	global_load_dword v107, v[122:123], off offset:128
	global_load_dword v106, v[124:125], off offset:128
	global_load_dword v105, v[126:127], off offset:128
	global_load_dword v104, v[144:145], off offset:128
	global_load_dword v103, v[146:147], off offset:128
	global_load_dword v102, v[150:151], off offset:128
	global_load_dword v101, v[152:153], off offset:128
	global_load_dword v100, v[154:155], off offset:128
	global_load_dword v99, v[156:157], off offset:128
	global_load_dword v98, v[158:159], off offset:128
	s_waitcnt vmcnt(62)
	v_add_f32_e32 v80, v80, v148
	v_lshl_add_u64 v[114:115], v[134:135], 0, v[140:141]
	global_store_dword v[114:115], v80, off
	v_mul_f32_e32 v80, v209, v80
	v_cvt_pk_bf16_f32 v80, v80, s0
	v_lshl_add_u64 v[96:97], v[96:97], 1, v[136:137]
	global_store_short v[96:97], v80, off
	v_or_b32_e32 v80, 0x10800, v130
	v_add_f32_e32 v113, v81, v149
	v_ashrrev_i32_e32 v81, 31, v80
	v_lshl_add_u64 v[96:97], v[80:81], 2, v[134:135]
	global_store_dword v[96:97], v113, off
	v_mul_f32_e32 v96, v209, v113
	v_cvt_pk_bf16_f32 v96, v96, s0
	v_lshl_add_u64 v[80:81], v[80:81], 1, v[136:137]
	global_store_short v[80:81], v96, off
	v_or_b32_e32 v80, 0x11000, v130
	v_ashrrev_i32_e32 v81, 31, v80
	s_waitcnt vmcnt(62)
	v_add_f32_e32 v82, v82, v160
	v_lshl_add_u64 v[96:97], v[80:81], 2, v[134:135]
	global_store_dword v[96:97], v82, off
	v_mul_f32_e32 v82, v209, v82
	v_cvt_pk_bf16_f32 v82, v82, s0
	v_lshl_add_u64 v[80:81], v[80:81], 1, v[136:137]
	global_store_short v[80:81], v82, off
	v_or_b32_e32 v80, 0x11800, v130
	v_ashrrev_i32_e32 v81, 31, v80
	v_add_f32_e32 v96, v83, v161
	v_lshl_add_u64 v[82:83], v[80:81], 2, v[134:135]
	global_store_dword v[82:83], v96, off
	v_mul_f32_e32 v82, v209, v96
	v_cvt_pk_bf16_f32 v82, v82, s0
	v_lshl_add_u64 v[80:81], v[80:81], 1, v[136:137]
	global_store_short v[80:81], v82, off
	v_or_b32_e32 v80, 0x14000, v130
	v_ashrrev_i32_e32 v81, 31, v80
	v_add_f32_e32 v84, v84, v162
	v_lshl_add_u64 v[82:83], v[80:81], 2, v[134:135]
	global_store_dword v[82:83], v84, off
	v_mul_f32_e32 v82, v209, v84
	v_cvt_pk_bf16_f32 v82, v82, s0
	v_lshl_add_u64 v[80:81], v[80:81], 1, v[136:137]
	global_store_short v[80:81], v82, off
	v_or_b32_e32 v80, 0x14800, v130
	v_ashrrev_i32_e32 v81, 31, v80
	v_add_f32_e32 v84, v85, v163
	v_lshl_add_u64 v[82:83], v[80:81], 2, v[134:135]
	global_store_dword v[82:83], v84, off
	v_mul_f32_e32 v82, v209, v84
	v_cvt_pk_bf16_f32 v82, v82, s0
	v_lshl_add_u64 v[80:81], v[80:81], 1, v[136:137]
	global_store_short v[80:81], v82, off
	v_or_b32_e32 v80, 0x15000, v130
	v_ashrrev_i32_e32 v81, 31, v80
	s_waitcnt vmcnt(62)
	v_add_f32_e32 v84, v86, v164
	v_lshl_add_u64 v[82:83], v[80:81], 2, v[134:135]
	global_store_dword v[82:83], v84, off
	v_mul_f32_e32 v82, v209, v84
	v_cvt_pk_bf16_f32 v82, v82, s0
	v_lshl_add_u64 v[80:81], v[80:81], 1, v[136:137]
	global_store_short v[80:81], v82, off
	v_or_b32_e32 v80, 0x15800, v130
	v_ashrrev_i32_e32 v81, 31, v80
	v_add_f32_e32 v84, v87, v165
	v_lshl_add_u64 v[82:83], v[80:81], 2, v[134:135]
	global_store_dword v[82:83], v84, off
	v_mul_f32_e32 v82, v209, v84
	v_cvt_pk_bf16_f32 v82, v82, s0
	v_lshl_add_u64 v[80:81], v[80:81], 1, v[136:137]
	global_store_short v[80:81], v82, off
	v_or_b32_e32 v80, 0x18000, v130
	v_ashrrev_i32_e32 v81, 31, v80
	v_add_f32_e32 v84, v88, v166
	v_lshl_add_u64 v[82:83], v[80:81], 2, v[134:135]
	global_store_dword v[82:83], v84, off
	v_mul_f32_e32 v82, v209, v84
	v_cvt_pk_bf16_f32 v82, v82, s0
	v_lshl_add_u64 v[80:81], v[80:81], 1, v[136:137]
	global_store_short v[80:81], v82, off
	v_or_b32_e32 v80, 0x18800, v130
	v_ashrrev_i32_e32 v81, 31, v80
	v_add_f32_e32 v84, v89, v167
	v_lshl_add_u64 v[82:83], v[80:81], 2, v[134:135]
	global_store_dword v[82:83], v84, off
	v_mul_f32_e32 v82, v209, v84
	v_cvt_pk_bf16_f32 v82, v82, s0
	v_lshl_add_u64 v[80:81], v[80:81], 1, v[136:137]
	global_store_short v[80:81], v82, off
	v_or_b32_e32 v80, 0x19000, v130
	v_ashrrev_i32_e32 v81, 31, v80
	v_add_f32_e32 v84, v90, v168
	v_lshl_add_u64 v[82:83], v[80:81], 2, v[134:135]
	global_store_dword v[82:83], v84, off
	v_mul_f32_e32 v82, v209, v84
	v_cvt_pk_bf16_f32 v82, v82, s0
	v_lshl_add_u64 v[80:81], v[80:81], 1, v[136:137]
	global_store_short v[80:81], v82, off
	v_or_b32_e32 v80, 0x19800, v130
	v_ashrrev_i32_e32 v81, 31, v80
	v_add_f32_e32 v84, v91, v169
	v_lshl_add_u64 v[82:83], v[80:81], 2, v[134:135]
	global_store_dword v[82:83], v84, off
	v_mul_f32_e32 v82, v209, v84
	v_cvt_pk_bf16_f32 v82, v82, s0
	v_lshl_add_u64 v[80:81], v[80:81], 1, v[136:137]
	global_store_short v[80:81], v82, off
	v_or_b32_e32 v80, 0x1c000, v130
	v_ashrrev_i32_e32 v81, 31, v80
	v_add_f32_e32 v84, v92, v170
	v_lshl_add_u64 v[82:83], v[80:81], 2, v[134:135]
	global_store_dword v[82:83], v84, off
	v_mul_f32_e32 v82, v209, v84
	v_cvt_pk_bf16_f32 v82, v82, s0
	v_lshl_add_u64 v[80:81], v[80:81], 1, v[136:137]
	global_store_short v[80:81], v82, off
	v_or_b32_e32 v80, 0x1c800, v130
	v_ashrrev_i32_e32 v81, 31, v80
	v_add_f32_e32 v84, v93, v171
	v_lshl_add_u64 v[82:83], v[80:81], 2, v[134:135]
	global_store_dword v[82:83], v84, off
	v_mul_f32_e32 v82, v209, v84
	v_cvt_pk_bf16_f32 v82, v82, s0
	v_lshl_add_u64 v[80:81], v[80:81], 1, v[136:137]
	global_store_short v[80:81], v82, off
	v_or_b32_e32 v80, 0x1d000, v130
	v_ashrrev_i32_e32 v81, 31, v80
	s_waitcnt vmcnt(62)
	v_add_f32_e32 v84, v94, v172
	v_lshl_add_u64 v[82:83], v[80:81], 2, v[134:135]
	global_store_dword v[82:83], v84, off
	v_mul_f32_e32 v82, v209, v84
	v_cvt_pk_bf16_f32 v82, v82, s0
	v_lshl_add_u64 v[80:81], v[80:81], 1, v[136:137]
	global_store_short v[80:81], v82, off
	v_or_b32_e32 v80, 0x1d800, v130
	v_ashrrev_i32_e32 v81, 31, v80
	v_add_f32_e32 v84, v95, v173
	v_lshl_add_u64 v[82:83], v[80:81], 2, v[134:135]
	global_store_dword v[82:83], v84, off
	v_mul_f32_e32 v82, v209, v84
	v_cvt_pk_bf16_f32 v82, v82, s0
	v_lshl_add_u64 v[80:81], v[80:81], 1, v[136:137]
	global_store_short v[80:81], v82, off
	v_add_co_u32_e32 v80, vcc, s50, v138
	s_mov_b32 s22, 0xb4000
	s_nop 0
	v_addc_co_u32_e32 v81, vcc, 0, v139, vcc
	global_load_dword v142, v[80:81], off
	v_add_co_u32_e32 v80, vcc, s2, v138
	v_or_b32_e32 v126, 0x10020, v130
	s_nop 0
	v_addc_co_u32_e32 v81, vcc, 0, v139, vcc
	v_add_co_u32_e32 v82, vcc, s36, v138
	v_ashrrev_i32_e32 v127, 31, v126
	s_nop 0
	v_addc_co_u32_e32 v83, vcc, 0, v139, vcc
	v_add_co_u32_e32 v84, vcc, s37, v138
	s_waitcnt vmcnt(48)
	v_add_f32_e32 v64, v64, v131
	v_addc_co_u32_e32 v85, vcc, 0, v139, vcc
	v_add_co_u32_e32 v86, vcc, s38, v138
	v_lshl_add_u64 v[140:141], v[126:127], 2, v[134:135]
	s_nop 0
	v_addc_co_u32_e32 v87, vcc, 0, v139, vcc
	v_add_co_u32_e32 v88, vcc, s39, v138
	global_load_dword v143, v[80:81], off
	global_load_dword v144, v[82:83], off
	global_load_dword v145, v[84:85], off
	global_load_dword v146, v[86:87], off
	v_addc_co_u32_e32 v89, vcc, 0, v139, vcc
	v_add_co_u32_e32 v90, vcc, s96, v138
	global_load_dword v147, v[88:89], off
	s_nop 0
	v_addc_co_u32_e32 v91, vcc, 0, v139, vcc
	v_add_co_u32_e32 v92, vcc, s97, v138
	global_load_dword v148, v[90:91], off
	s_nop 0
	v_addc_co_u32_e32 v93, vcc, 0, v139, vcc
	v_add_co_u32_e32 v94, vcc, s3, v138
	global_load_dword v149, v[92:93], off
	s_nop 0
	v_addc_co_u32_e32 v95, vcc, 0, v139, vcc
	v_add_co_u32_e32 v96, vcc, s4, v138
	global_load_dword v150, v[94:95], off
	s_nop 0
	v_addc_co_u32_e32 v97, vcc, 0, v139, vcc
	v_add_co_u32_e32 v114, vcc, s5, v138
	global_load_dword v151, v[96:97], off
	s_nop 0
	v_addc_co_u32_e32 v115, vcc, 0, v139, vcc
	v_add_co_u32_e32 v116, vcc, s45, v138
	global_load_dword v152, v[114:115], off
	s_nop 0
	v_addc_co_u32_e32 v117, vcc, 0, v139, vcc
	v_add_co_u32_e32 v118, vcc, s54, v138
	global_load_dword v153, v[116:117], off
	s_nop 0
	v_addc_co_u32_e32 v119, vcc, 0, v139, vcc
	v_add_co_u32_e32 v120, vcc, s55, v138
	global_load_dword v154, v[118:119], off
	s_nop 0
	v_addc_co_u32_e32 v121, vcc, 0, v139, vcc
	v_add_co_u32_e32 v122, vcc, s22, v138
	s_mov_b32 s22, 0xb6000
	s_nop 0
	v_addc_co_u32_e32 v123, vcc, 0, v139, vcc
	v_add_co_u32_e32 v124, vcc, s22, v138
	global_load_dword v155, v[120:121], off
	global_load_dword v156, v[122:123], off
	v_addc_co_u32_e32 v125, vcc, 0, v139, vcc
	global_load_dword v157, v[124:125], off
	v_lshl_add_u64 v[126:127], v[126:127], 1, v[136:137]
	global_store_dword v[140:141], v64, off
	v_mul_f32_e32 v64, v128, v64
	v_cvt_pk_bf16_f32 v64, v64, s0
	global_store_short v[126:127], v64, off
	v_or_b32_e32 v64, 0x10820, v130
	s_waitcnt vmcnt(62)
	v_add_f32_e32 v126, v65, v112
	v_ashrrev_i32_e32 v65, 31, v64
	v_lshl_add_u64 v[112:113], v[64:65], 2, v[134:135]
	global_store_dword v[112:113], v126, off
	v_mul_f32_e32 v112, v128, v126
	v_cvt_pk_bf16_f32 v112, v112, s0
	v_lshl_add_u64 v[64:65], v[64:65], 1, v[136:137]
	global_store_short v[64:65], v112, off
	v_or_b32_e32 v64, 0x11020, v130
	v_ashrrev_i32_e32 v65, 31, v64
	v_add_f32_e32 v66, v66, v111
	v_lshl_add_u64 v[112:113], v[64:65], 2, v[134:135]
	global_store_dword v[112:113], v66, off
	v_mul_f32_e32 v66, v128, v66
	v_cvt_pk_bf16_f32 v66, v66, s0
	v_lshl_add_u64 v[64:65], v[64:65], 1, v[136:137]
	global_store_short v[64:65], v66, off
	v_or_b32_e32 v64, 0x11820, v130
	v_ashrrev_i32_e32 v65, 31, v64
	v_add_f32_e32 v110, v67, v110
	v_lshl_add_u64 v[66:67], v[64:65], 2, v[134:135]
	global_store_dword v[66:67], v110, off
	v_mul_f32_e32 v66, v128, v110
	v_cvt_pk_bf16_f32 v66, v66, s0
	v_lshl_add_u64 v[64:65], v[64:65], 1, v[136:137]
	global_store_short v[64:65], v66, off
	v_or_b32_e32 v64, 0x14020, v130
	v_ashrrev_i32_e32 v65, 31, v64
	s_waitcnt vmcnt(62)
	v_add_f32_e32 v68, v68, v109
	v_lshl_add_u64 v[66:67], v[64:65], 2, v[134:135]
	global_store_dword v[66:67], v68, off
	v_mul_f32_e32 v66, v128, v68
	v_cvt_pk_bf16_f32 v66, v66, s0
	v_lshl_add_u64 v[64:65], v[64:65], 1, v[136:137]
	global_store_short v[64:65], v66, off
	v_or_b32_e32 v64, 0x14820, v130
	v_ashrrev_i32_e32 v65, 31, v64
	v_add_f32_e32 v68, v69, v108
	v_lshl_add_u64 v[66:67], v[64:65], 2, v[134:135]
	global_store_dword v[66:67], v68, off
	v_mul_f32_e32 v66, v128, v68
	v_cvt_pk_bf16_f32 v66, v66, s0
	v_lshl_add_u64 v[64:65], v[64:65], 1, v[136:137]
	global_store_short v[64:65], v66, off
	v_or_b32_e32 v64, 0x15020, v130
	v_ashrrev_i32_e32 v65, 31, v64
	v_add_f32_e32 v68, v70, v107
	v_lshl_add_u64 v[66:67], v[64:65], 2, v[134:135]
	global_store_dword v[66:67], v68, off
	v_mul_f32_e32 v66, v128, v68
	v_cvt_pk_bf16_f32 v66, v66, s0
	v_lshl_add_u64 v[64:65], v[64:65], 1, v[136:137]
	global_store_short v[64:65], v66, off
	v_or_b32_e32 v64, 0x15820, v130
	v_ashrrev_i32_e32 v65, 31, v64
	v_add_f32_e32 v68, v71, v106
	v_lshl_add_u64 v[66:67], v[64:65], 2, v[134:135]
	global_store_dword v[66:67], v68, off
	v_mul_f32_e32 v66, v128, v68
	v_cvt_pk_bf16_f32 v66, v66, s0
	v_lshl_add_u64 v[64:65], v[64:65], 1, v[136:137]
	global_store_short v[64:65], v66, off
	v_or_b32_e32 v64, 0x18020, v130
	v_ashrrev_i32_e32 v65, 31, v64
	v_add_f32_e32 v68, v72, v105
	v_lshl_add_u64 v[66:67], v[64:65], 2, v[134:135]
	global_store_dword v[66:67], v68, off
	v_mul_f32_e32 v66, v128, v68
	v_cvt_pk_bf16_f32 v66, v66, s0
	v_lshl_add_u64 v[64:65], v[64:65], 1, v[136:137]
	global_store_short v[64:65], v66, off
	v_or_b32_e32 v64, 0x18820, v130
	v_ashrrev_i32_e32 v65, 31, v64
	v_add_f32_e32 v68, v73, v104
	v_lshl_add_u64 v[66:67], v[64:65], 2, v[134:135]
	global_store_dword v[66:67], v68, off
	v_mul_f32_e32 v66, v128, v68
	v_cvt_pk_bf16_f32 v66, v66, s0
	v_lshl_add_u64 v[64:65], v[64:65], 1, v[136:137]
	global_store_short v[64:65], v66, off
	v_or_b32_e32 v64, 0x19020, v130
	v_ashrrev_i32_e32 v65, 31, v64
	s_waitcnt vmcnt(62)
	v_add_f32_e32 v68, v74, v103
	v_lshl_add_u64 v[66:67], v[64:65], 2, v[134:135]
	global_store_dword v[66:67], v68, off
	v_mul_f32_e32 v66, v128, v68
	v_cvt_pk_bf16_f32 v66, v66, s0
	v_lshl_add_u64 v[64:65], v[64:65], 1, v[136:137]
	global_store_short v[64:65], v66, off
	v_or_b32_e32 v64, 0x19820, v130
	v_ashrrev_i32_e32 v65, 31, v64
	v_add_f32_e32 v68, v75, v102
	v_lshl_add_u64 v[66:67], v[64:65], 2, v[134:135]
	global_store_dword v[66:67], v68, off
	v_mul_f32_e32 v66, v128, v68
	v_cvt_pk_bf16_f32 v66, v66, s0
	v_lshl_add_u64 v[64:65], v[64:65], 1, v[136:137]
	global_store_short v[64:65], v66, off
	v_or_b32_e32 v64, 0x1c020, v130
	v_ashrrev_i32_e32 v65, 31, v64
	v_add_f32_e32 v68, v76, v101
	v_lshl_add_u64 v[66:67], v[64:65], 2, v[134:135]
	global_store_dword v[66:67], v68, off
	v_mul_f32_e32 v66, v128, v68
	v_cvt_pk_bf16_f32 v66, v66, s0
	v_lshl_add_u64 v[64:65], v[64:65], 1, v[136:137]
	global_store_short v[64:65], v66, off
	v_or_b32_e32 v64, 0x1c820, v130
	v_ashrrev_i32_e32 v65, 31, v64
	v_add_f32_e32 v68, v77, v100
	v_lshl_add_u64 v[66:67], v[64:65], 2, v[134:135]
	global_store_dword v[66:67], v68, off
	v_mul_f32_e32 v66, v128, v68
	v_cvt_pk_bf16_f32 v66, v66, s0
	v_lshl_add_u64 v[64:65], v[64:65], 1, v[136:137]
	global_store_short v[64:65], v66, off
	v_or_b32_e32 v64, 0x1d020, v130
	v_ashrrev_i32_e32 v65, 31, v64
	v_add_f32_e32 v68, v78, v99
	v_lshl_add_u64 v[66:67], v[64:65], 2, v[134:135]
	global_store_dword v[66:67], v68, off
	v_mul_f32_e32 v66, v128, v68
	v_cvt_pk_bf16_f32 v66, v66, s0
	v_lshl_add_u64 v[64:65], v[64:65], 1, v[136:137]
	global_store_short v[64:65], v66, off
	v_or_b32_e32 v64, 0x1d820, v130
	v_ashrrev_i32_e32 v65, 31, v64
	v_add_f32_e32 v68, v79, v98
	v_lshl_add_u64 v[66:67], v[64:65], 2, v[134:135]
	global_store_dword v[66:67], v68, off
	v_mul_f32_e32 v66, v128, v68
	v_cvt_pk_bf16_f32 v66, v66, s0
	v_lshl_add_u64 v[64:65], v[64:65], 1, v[136:137]
	global_store_short v[64:65], v66, off
	v_or_b32_e32 v64, 0x20000, v130
	v_ashrrev_i32_e32 v65, 31, v64
	v_lshlrev_b64 v[66:67], 2, v[64:65]
	v_lshl_add_u64 v[68:69], v[132:133], 0, v[66:67]
	s_waitcnt vmcnt(47)
	v_add_f32_e32 v48, v48, v142
	v_lshl_add_u64 v[66:67], v[134:135], 0, v[66:67]
	global_load_dword v102, v[68:69], off offset:128
	global_load_dword v101, v[80:81], off offset:128
	global_load_dword v100, v[82:83], off offset:128
	global_load_dword v99, v[84:85], off offset:128
	global_load_dword v98, v[86:87], off offset:128
	s_nop 0
	global_load_dword v88, v[88:89], off offset:128
	s_nop 0
	global_load_dword v87, v[90:91], off offset:128
	global_load_dword v86, v[92:93], off offset:128
	global_load_dword v85, v[94:95], off offset:128
	global_load_dword v84, v[96:97], off offset:128
	global_load_dword v83, v[114:115], off offset:128
	global_load_dword v82, v[116:117], off offset:128
	global_load_dword v81, v[118:119], off offset:128
	global_load_dword v80, v[120:121], off offset:128
	global_load_dword v79, v[122:123], off offset:128
	global_load_dword v78, v[124:125], off offset:128
	v_lshl_add_u64 v[64:65], v[64:65], 1, v[136:137]
	global_store_dword v[66:67], v48, off
	v_mul_f32_e32 v48, v209, v48
	v_cvt_pk_bf16_f32 v48, v48, s0
	global_store_short v[64:65], v48, off
	v_or_b32_e32 v48, 0x20800, v130
	s_waitcnt vmcnt(62)
	v_add_f32_e32 v66, v49, v143
	v_ashrrev_i32_e32 v49, 31, v48
	v_lshl_add_u64 v[64:65], v[48:49], 2, v[134:135]
	global_store_dword v[64:65], v66, off
	v_mul_f32_e32 v64, v209, v66
	v_cvt_pk_bf16_f32 v64, v64, s0
	v_lshl_add_u64 v[48:49], v[48:49], 1, v[136:137]
	global_store_short v[48:49], v64, off
	v_or_b32_e32 v48, 0x21000, v130
	v_ashrrev_i32_e32 v49, 31, v48
	v_add_f32_e32 v50, v50, v144
	v_lshl_add_u64 v[64:65], v[48:49], 2, v[134:135]
	global_store_dword v[64:65], v50, off
	v_mul_f32_e32 v50, v209, v50
	v_cvt_pk_bf16_f32 v50, v50, s0
	v_lshl_add_u64 v[48:49], v[48:49], 1, v[136:137]
	global_store_short v[48:49], v50, off
	v_or_b32_e32 v48, 0x21800, v130
	v_ashrrev_i32_e32 v49, 31, v48
	v_add_f32_e32 v64, v51, v145
	v_lshl_add_u64 v[50:51], v[48:49], 2, v[134:135]
	global_store_dword v[50:51], v64, off
	v_mul_f32_e32 v50, v209, v64
	v_cvt_pk_bf16_f32 v50, v50, s0
	v_lshl_add_u64 v[48:49], v[48:49], 1, v[136:137]
	global_store_short v[48:49], v50, off
	v_or_b32_e32 v48, 0x24000, v130
	v_ashrrev_i32_e32 v49, 31, v48
	s_waitcnt vmcnt(62)
	v_add_f32_e32 v52, v52, v146
	v_lshl_add_u64 v[50:51], v[48:49], 2, v[134:135]
	global_store_dword v[50:51], v52, off
	v_mul_f32_e32 v50, v209, v52
	v_cvt_pk_bf16_f32 v50, v50, s0
	v_lshl_add_u64 v[48:49], v[48:49], 1, v[136:137]
	global_store_short v[48:49], v50, off
	v_or_b32_e32 v48, 0x24800, v130
	v_ashrrev_i32_e32 v49, 31, v48
	v_add_f32_e32 v52, v53, v147
	v_lshl_add_u64 v[50:51], v[48:49], 2, v[134:135]
	global_store_dword v[50:51], v52, off
	v_mul_f32_e32 v50, v209, v52
	v_cvt_pk_bf16_f32 v50, v50, s0
	v_lshl_add_u64 v[48:49], v[48:49], 1, v[136:137]
	global_store_short v[48:49], v50, off
	v_or_b32_e32 v48, 0x25000, v130
	v_ashrrev_i32_e32 v49, 31, v48
	v_add_f32_e32 v52, v54, v148
	v_lshl_add_u64 v[50:51], v[48:49], 2, v[134:135]
	global_store_dword v[50:51], v52, off
	v_mul_f32_e32 v50, v209, v52
	v_cvt_pk_bf16_f32 v50, v50, s0
	v_lshl_add_u64 v[48:49], v[48:49], 1, v[136:137]
	global_store_short v[48:49], v50, off
	v_or_b32_e32 v48, 0x25800, v130
	v_ashrrev_i32_e32 v49, 31, v48
	v_add_f32_e32 v52, v55, v149
	v_lshl_add_u64 v[50:51], v[48:49], 2, v[134:135]
	global_store_dword v[50:51], v52, off
	v_mul_f32_e32 v50, v209, v52
	v_cvt_pk_bf16_f32 v50, v50, s0
	v_lshl_add_u64 v[48:49], v[48:49], 1, v[136:137]
	global_store_short v[48:49], v50, off
	v_or_b32_e32 v48, 0x28000, v130
	v_ashrrev_i32_e32 v49, 31, v48
	v_add_f32_e32 v52, v56, v150
	v_lshl_add_u64 v[50:51], v[48:49], 2, v[134:135]
	global_store_dword v[50:51], v52, off
	v_mul_f32_e32 v50, v209, v52
	v_cvt_pk_bf16_f32 v50, v50, s0
	v_lshl_add_u64 v[48:49], v[48:49], 1, v[136:137]
	global_store_short v[48:49], v50, off
	v_or_b32_e32 v48, 0x28800, v130
	v_ashrrev_i32_e32 v49, 31, v48
	v_add_f32_e32 v52, v57, v151
	v_lshl_add_u64 v[50:51], v[48:49], 2, v[134:135]
	global_store_dword v[50:51], v52, off
	v_mul_f32_e32 v50, v209, v52
	v_cvt_pk_bf16_f32 v50, v50, s0
	v_lshl_add_u64 v[48:49], v[48:49], 1, v[136:137]
	global_store_short v[48:49], v50, off
	v_or_b32_e32 v48, 0x29000, v130
	v_ashrrev_i32_e32 v49, 31, v48
	s_waitcnt vmcnt(62)
	v_add_f32_e32 v52, v58, v152
	v_lshl_add_u64 v[50:51], v[48:49], 2, v[134:135]
	global_store_dword v[50:51], v52, off
	v_mul_f32_e32 v50, v209, v52
	v_cvt_pk_bf16_f32 v50, v50, s0
	v_lshl_add_u64 v[48:49], v[48:49], 1, v[136:137]
	global_store_short v[48:49], v50, off
	v_or_b32_e32 v48, 0x29800, v130
	v_ashrrev_i32_e32 v49, 31, v48
	v_add_f32_e32 v52, v59, v153
	v_lshl_add_u64 v[50:51], v[48:49], 2, v[134:135]
	global_store_dword v[50:51], v52, off
	v_mul_f32_e32 v50, v209, v52
	v_cvt_pk_bf16_f32 v50, v50, s0
	v_lshl_add_u64 v[48:49], v[48:49], 1, v[136:137]
	global_store_short v[48:49], v50, off
	v_or_b32_e32 v48, 0x2c000, v130
	v_ashrrev_i32_e32 v49, 31, v48
	v_add_f32_e32 v52, v60, v154
	v_lshl_add_u64 v[50:51], v[48:49], 2, v[134:135]
	global_store_dword v[50:51], v52, off
	v_mul_f32_e32 v50, v209, v52
	v_cvt_pk_bf16_f32 v50, v50, s0
	v_lshl_add_u64 v[48:49], v[48:49], 1, v[136:137]
	global_store_short v[48:49], v50, off
	v_or_b32_e32 v48, 0x2c800, v130
	v_ashrrev_i32_e32 v49, 31, v48
	v_add_f32_e32 v52, v61, v155
	v_lshl_add_u64 v[50:51], v[48:49], 2, v[134:135]
	global_store_dword v[50:51], v52, off
	v_mul_f32_e32 v50, v209, v52
	v_cvt_pk_bf16_f32 v50, v50, s0
	v_lshl_add_u64 v[48:49], v[48:49], 1, v[136:137]
	global_store_short v[48:49], v50, off
	v_or_b32_e32 v48, 0x2d000, v130
	v_ashrrev_i32_e32 v49, 31, v48
	v_add_f32_e32 v52, v62, v156
	v_lshl_add_u64 v[50:51], v[48:49], 2, v[134:135]
	global_store_dword v[50:51], v52, off
	v_mul_f32_e32 v50, v209, v52
	v_cvt_pk_bf16_f32 v50, v50, s0
	v_lshl_add_u64 v[48:49], v[48:49], 1, v[136:137]
	global_store_short v[48:49], v50, off
	v_or_b32_e32 v48, 0x2d800, v130
	v_ashrrev_i32_e32 v49, 31, v48
	v_add_f32_e32 v52, v63, v157
	v_lshl_add_u64 v[50:51], v[48:49], 2, v[134:135]
	global_store_dword v[50:51], v52, off
	v_mul_f32_e32 v50, v209, v52
	v_cvt_pk_bf16_f32 v50, v50, s0
	v_lshl_add_u64 v[48:49], v[48:49], 1, v[136:137]
	s_mov_b32 s22, 0xc0000
	global_store_short v[48:49], v50, off
	v_add_co_u32_e32 v48, vcc, s22, v138
	s_mov_b32 s22, 0xc2000
	s_nop 0
	v_addc_co_u32_e32 v49, vcc, 0, v139, vcc
	global_load_dword v89, v[48:49], off
	v_add_co_u32_e32 v48, vcc, s22, v138
	v_or_b32_e32 v110, 0x20020, v130
	s_nop 0
	v_addc_co_u32_e32 v49, vcc, 0, v139, vcc
	v_add_co_u32_e32 v50, vcc, s76, v138
	v_ashrrev_i32_e32 v111, 31, v110
	s_nop 0
	v_addc_co_u32_e32 v51, vcc, 0, v139, vcc
	v_add_co_u32_e32 v52, vcc, s77, v138
	s_waitcnt vmcnt(48)
	v_add_f32_e32 v32, v32, v102
	v_addc_co_u32_e32 v53, vcc, 0, v139, vcc
	v_add_co_u32_e32 v54, vcc, s78, v138
	v_lshl_add_u64 v[112:113], v[110:111], 2, v[134:135]
	s_nop 0
	v_addc_co_u32_e32 v55, vcc, 0, v139, vcc
	v_add_co_u32_e32 v56, vcc, s79, v138
	global_load_dword v90, v[48:49], off
	global_load_dword v91, v[50:51], off
	global_load_dword v92, v[52:53], off
	global_load_dword v93, v[54:55], off
	v_addc_co_u32_e32 v57, vcc, 0, v139, vcc
	v_add_co_u32_e32 v58, vcc, s80, v138
	global_load_dword v94, v[56:57], off
	s_nop 0
	v_addc_co_u32_e32 v59, vcc, 0, v139, vcc
	v_add_co_u32_e32 v60, vcc, s81, v138
	global_load_dword v95, v[58:59], off
	s_nop 0
	v_addc_co_u32_e32 v61, vcc, 0, v139, vcc
	v_add_co_u32_e32 v62, vcc, s82, v138
	global_load_dword v96, v[60:61], off
	s_nop 0
	v_addc_co_u32_e32 v63, vcc, 0, v139, vcc
	v_add_co_u32_e32 v64, vcc, s83, v138
	global_load_dword v97, v[62:63], off
	s_nop 0
	v_addc_co_u32_e32 v65, vcc, 0, v139, vcc
	v_add_co_u32_e32 v66, vcc, s84, v138
	global_load_dword v103, v[64:65], off
	s_nop 0
	v_addc_co_u32_e32 v67, vcc, 0, v139, vcc
	v_add_co_u32_e32 v68, vcc, s85, v138
	global_load_dword v104, v[66:67], off
	s_nop 0
	v_addc_co_u32_e32 v69, vcc, 0, v139, vcc
	v_add_co_u32_e32 v70, vcc, s86, v138
	global_load_dword v105, v[68:69], off
	s_nop 0
	v_addc_co_u32_e32 v71, vcc, 0, v139, vcc
	v_add_co_u32_e32 v72, vcc, s87, v138
	global_load_dword v106, v[70:71], off
	s_nop 0
	v_addc_co_u32_e32 v73, vcc, 0, v139, vcc
	v_add_co_u32_e32 v74, vcc, s88, v138
	global_load_dword v107, v[72:73], off
	s_nop 0
	v_addc_co_u32_e32 v75, vcc, 0, v139, vcc
	v_add_co_u32_e32 v76, vcc, s89, v138
	global_load_dword v108, v[74:75], off
	s_nop 0
	v_addc_co_u32_e32 v77, vcc, 0, v139, vcc
	global_load_dword v109, v[76:77], off
	v_lshl_add_u64 v[110:111], v[110:111], 1, v[136:137]
	global_store_dword v[112:113], v32, off
	v_mul_f32_e32 v32, v128, v32
	v_cvt_pk_bf16_f32 v32, v32, s0
	global_store_short v[110:111], v32, off
	v_or_b32_e32 v32, 0x20820, v130
	s_waitcnt vmcnt(62)
	v_add_f32_e32 v101, v33, v101
	v_ashrrev_i32_e32 v33, 31, v32
	v_lshl_add_u64 v[110:111], v[32:33], 2, v[134:135]
	global_store_dword v[110:111], v101, off
	v_mul_f32_e32 v101, v128, v101
	v_cvt_pk_bf16_f32 v101, v101, s0
	v_lshl_add_u64 v[32:33], v[32:33], 1, v[136:137]
	global_store_short v[32:33], v101, off
	v_or_b32_e32 v32, 0x21020, v130
	v_ashrrev_i32_e32 v33, 31, v32
	v_add_f32_e32 v34, v34, v100
	v_lshl_add_u64 v[100:101], v[32:33], 2, v[134:135]
	global_store_dword v[100:101], v34, off
	v_mul_f32_e32 v34, v128, v34
	v_cvt_pk_bf16_f32 v34, v34, s0
	v_lshl_add_u64 v[32:33], v[32:33], 1, v[136:137]
	global_store_short v[32:33], v34, off
	v_or_b32_e32 v32, 0x21820, v130
	v_ashrrev_i32_e32 v33, 31, v32
	v_add_f32_e32 v99, v35, v99
	v_lshl_add_u64 v[34:35], v[32:33], 2, v[134:135]
	global_store_dword v[34:35], v99, off
	v_mul_f32_e32 v34, v128, v99
	v_cvt_pk_bf16_f32 v34, v34, s0
	v_lshl_add_u64 v[32:33], v[32:33], 1, v[136:137]
	global_store_short v[32:33], v34, off
	v_or_b32_e32 v32, 0x24020, v130
	v_ashrrev_i32_e32 v33, 31, v32
	s_waitcnt vmcnt(62)
	v_add_f32_e32 v36, v36, v98
	v_lshl_add_u64 v[34:35], v[32:33], 2, v[134:135]
	global_store_dword v[34:35], v36, off
	v_mul_f32_e32 v34, v128, v36
	v_cvt_pk_bf16_f32 v34, v34, s0
	v_lshl_add_u64 v[32:33], v[32:33], 1, v[136:137]
	global_store_short v[32:33], v34, off
	v_or_b32_e32 v32, 0x24820, v130
	v_ashrrev_i32_e32 v33, 31, v32
	v_add_f32_e32 v36, v37, v88
	v_lshl_add_u64 v[34:35], v[32:33], 2, v[134:135]
	global_store_dword v[34:35], v36, off
	v_mul_f32_e32 v34, v128, v36
	v_cvt_pk_bf16_f32 v34, v34, s0
	v_lshl_add_u64 v[32:33], v[32:33], 1, v[136:137]
	global_store_short v[32:33], v34, off
	v_or_b32_e32 v32, 0x25020, v130
	v_ashrrev_i32_e32 v33, 31, v32
	v_add_f32_e32 v36, v38, v87
	v_lshl_add_u64 v[34:35], v[32:33], 2, v[134:135]
	global_store_dword v[34:35], v36, off
	v_mul_f32_e32 v34, v128, v36
	v_cvt_pk_bf16_f32 v34, v34, s0
	v_lshl_add_u64 v[32:33], v[32:33], 1, v[136:137]
	global_store_short v[32:33], v34, off
	v_or_b32_e32 v32, 0x25820, v130
	v_ashrrev_i32_e32 v33, 31, v32
	v_add_f32_e32 v36, v39, v86
	v_lshl_add_u64 v[34:35], v[32:33], 2, v[134:135]
	global_store_dword v[34:35], v36, off
	v_mul_f32_e32 v34, v128, v36
	v_cvt_pk_bf16_f32 v34, v34, s0
	v_lshl_add_u64 v[32:33], v[32:33], 1, v[136:137]
	global_store_short v[32:33], v34, off
	v_or_b32_e32 v32, 0x28020, v130
	v_ashrrev_i32_e32 v33, 31, v32
	v_add_f32_e32 v36, v40, v85
	v_lshl_add_u64 v[34:35], v[32:33], 2, v[134:135]
	global_store_dword v[34:35], v36, off
	v_mul_f32_e32 v34, v128, v36
	v_cvt_pk_bf16_f32 v34, v34, s0
	v_lshl_add_u64 v[32:33], v[32:33], 1, v[136:137]
	global_store_short v[32:33], v34, off
	v_or_b32_e32 v32, 0x28820, v130
	v_ashrrev_i32_e32 v33, 31, v32
	v_add_f32_e32 v36, v41, v84
	v_lshl_add_u64 v[34:35], v[32:33], 2, v[134:135]
	global_store_dword v[34:35], v36, off
	v_mul_f32_e32 v34, v128, v36
	v_cvt_pk_bf16_f32 v34, v34, s0
	v_lshl_add_u64 v[32:33], v[32:33], 1, v[136:137]
	global_store_short v[32:33], v34, off
	v_or_b32_e32 v32, 0x29020, v130
	v_ashrrev_i32_e32 v33, 31, v32
	s_waitcnt vmcnt(62)
	v_add_f32_e32 v36, v42, v83
	v_lshl_add_u64 v[34:35], v[32:33], 2, v[134:135]
	global_store_dword v[34:35], v36, off
	v_mul_f32_e32 v34, v128, v36
	v_cvt_pk_bf16_f32 v34, v34, s0
	v_lshl_add_u64 v[32:33], v[32:33], 1, v[136:137]
	global_store_short v[32:33], v34, off
	v_or_b32_e32 v32, 0x29820, v130
	v_ashrrev_i32_e32 v33, 31, v32
	v_add_f32_e32 v36, v43, v82
	v_lshl_add_u64 v[34:35], v[32:33], 2, v[134:135]
	global_store_dword v[34:35], v36, off
	v_mul_f32_e32 v34, v128, v36
	v_cvt_pk_bf16_f32 v34, v34, s0
	v_lshl_add_u64 v[32:33], v[32:33], 1, v[136:137]
	global_store_short v[32:33], v34, off
	v_or_b32_e32 v32, 0x2c020, v130
	v_ashrrev_i32_e32 v33, 31, v32
	v_add_f32_e32 v36, v44, v81
	v_lshl_add_u64 v[34:35], v[32:33], 2, v[134:135]
	global_store_dword v[34:35], v36, off
	v_mul_f32_e32 v34, v128, v36
	v_cvt_pk_bf16_f32 v34, v34, s0
	v_lshl_add_u64 v[32:33], v[32:33], 1, v[136:137]
	global_store_short v[32:33], v34, off
	v_or_b32_e32 v32, 0x2c820, v130
	v_ashrrev_i32_e32 v33, 31, v32
	v_add_f32_e32 v36, v45, v80
	v_lshl_add_u64 v[34:35], v[32:33], 2, v[134:135]
	global_store_dword v[34:35], v36, off
	v_mul_f32_e32 v34, v128, v36
	v_cvt_pk_bf16_f32 v34, v34, s0
	v_lshl_add_u64 v[32:33], v[32:33], 1, v[136:137]
	global_store_short v[32:33], v34, off
	v_or_b32_e32 v32, 0x2d020, v130
	v_ashrrev_i32_e32 v33, 31, v32
	v_add_f32_e32 v36, v46, v79
	v_lshl_add_u64 v[34:35], v[32:33], 2, v[134:135]
	global_store_dword v[34:35], v36, off
	v_mul_f32_e32 v34, v128, v36
	v_cvt_pk_bf16_f32 v34, v34, s0
	v_lshl_add_u64 v[32:33], v[32:33], 1, v[136:137]
	global_store_short v[32:33], v34, off
	v_or_b32_e32 v32, 0x2d820, v130
	v_ashrrev_i32_e32 v33, 31, v32
	v_add_f32_e32 v36, v47, v78
	v_lshl_add_u64 v[34:35], v[32:33], 2, v[134:135]
	global_store_dword v[34:35], v36, off
	v_mul_f32_e32 v34, v128, v36
	v_cvt_pk_bf16_f32 v34, v34, s0
	v_lshl_add_u64 v[32:33], v[32:33], 1, v[136:137]
	global_store_short v[32:33], v34, off
	v_or_b32_e32 v32, 0x30000, v130
	v_ashrrev_i32_e32 v33, 31, v32
	v_lshlrev_b64 v[34:35], 2, v[32:33]
	v_lshl_add_u64 v[36:37], v[132:133], 0, v[34:35]
	s_waitcnt vmcnt(47)
	v_add_f32_e32 v16, v16, v89
	v_lshl_add_u64 v[34:35], v[134:135], 0, v[34:35]
	global_load_dword v36, v[36:37], off offset:128
	s_nop 0
	global_load_dword v37, v[48:49], off offset:128
	global_load_dword v38, v[50:51], off offset:128
	global_load_dword v39, v[52:53], off offset:128
	global_load_dword v40, v[54:55], off offset:128
	global_load_dword v41, v[56:57], off offset:128
	global_load_dword v42, v[58:59], off offset:128
	global_load_dword v43, v[60:61], off offset:128
	global_load_dword v44, v[62:63], off offset:128
	global_load_dword v45, v[64:65], off offset:128
	global_load_dword v46, v[66:67], off offset:128
	global_load_dword v47, v[68:69], off offset:128
	global_load_dword v48, v[70:71], off offset:128
	global_load_dword v49, v[72:73], off offset:128
	global_load_dword v50, v[74:75], off offset:128
	global_load_dword v51, v[76:77], off offset:128
	v_lshl_add_u64 v[32:33], v[32:33], 1, v[136:137]
	global_store_dword v[34:35], v16, off
	v_mul_f32_e32 v16, v209, v16
	v_cvt_pk_bf16_f32 v16, v16, s0
	global_store_short v[32:33], v16, off
	v_or_b32_e32 v16, 0x30800, v130
	s_waitcnt vmcnt(62)
	v_add_f32_e32 v34, v17, v90
	v_ashrrev_i32_e32 v17, 31, v16
	v_lshl_add_u64 v[32:33], v[16:17], 2, v[134:135]
	global_store_dword v[32:33], v34, off
	v_mul_f32_e32 v32, v209, v34
	v_cvt_pk_bf16_f32 v32, v32, s0
	v_lshl_add_u64 v[16:17], v[16:17], 1, v[136:137]
	global_store_short v[16:17], v32, off
	v_or_b32_e32 v16, 0x31000, v130
	v_ashrrev_i32_e32 v17, 31, v16
	v_add_f32_e32 v18, v18, v91
	v_lshl_add_u64 v[32:33], v[16:17], 2, v[134:135]
	global_store_dword v[32:33], v18, off
	v_mul_f32_e32 v18, v209, v18
	v_cvt_pk_bf16_f32 v18, v18, s0
	v_lshl_add_u64 v[16:17], v[16:17], 1, v[136:137]
	global_store_short v[16:17], v18, off
	v_or_b32_e32 v16, 0x31800, v130
	v_ashrrev_i32_e32 v17, 31, v16
	v_add_f32_e32 v32, v19, v92
	v_lshl_add_u64 v[18:19], v[16:17], 2, v[134:135]
	global_store_dword v[18:19], v32, off
	v_mul_f32_e32 v18, v209, v32
	v_cvt_pk_bf16_f32 v18, v18, s0
	v_lshl_add_u64 v[16:17], v[16:17], 1, v[136:137]
	global_store_short v[16:17], v18, off
	v_or_b32_e32 v16, 0x34000, v130
	v_ashrrev_i32_e32 v17, 31, v16
	s_waitcnt vmcnt(62)
	v_add_f32_e32 v20, v20, v93
	v_lshl_add_u64 v[18:19], v[16:17], 2, v[134:135]
	global_store_dword v[18:19], v20, off
	v_mul_f32_e32 v18, v209, v20
	v_cvt_pk_bf16_f32 v18, v18, s0
	v_lshl_add_u64 v[16:17], v[16:17], 1, v[136:137]
	global_store_short v[16:17], v18, off
	v_or_b32_e32 v16, 0x34800, v130
	v_ashrrev_i32_e32 v17, 31, v16
	v_add_f32_e32 v20, v21, v94
	v_lshl_add_u64 v[18:19], v[16:17], 2, v[134:135]
	global_store_dword v[18:19], v20, off
	v_mul_f32_e32 v18, v209, v20
	v_cvt_pk_bf16_f32 v18, v18, s0
	v_lshl_add_u64 v[16:17], v[16:17], 1, v[136:137]
	global_store_short v[16:17], v18, off
	v_or_b32_e32 v16, 0x35000, v130
	v_ashrrev_i32_e32 v17, 31, v16
	v_add_f32_e32 v20, v22, v95
	v_lshl_add_u64 v[18:19], v[16:17], 2, v[134:135]
	global_store_dword v[18:19], v20, off
	v_mul_f32_e32 v18, v209, v20
	v_cvt_pk_bf16_f32 v18, v18, s0
	v_lshl_add_u64 v[16:17], v[16:17], 1, v[136:137]
	global_store_short v[16:17], v18, off
	v_or_b32_e32 v16, 0x35800, v130
	v_ashrrev_i32_e32 v17, 31, v16
	v_add_f32_e32 v20, v23, v96
	v_lshl_add_u64 v[18:19], v[16:17], 2, v[134:135]
	global_store_dword v[18:19], v20, off
	v_mul_f32_e32 v18, v209, v20
	v_cvt_pk_bf16_f32 v18, v18, s0
	v_lshl_add_u64 v[16:17], v[16:17], 1, v[136:137]
	global_store_short v[16:17], v18, off
	v_or_b32_e32 v16, 0x38000, v130
	v_ashrrev_i32_e32 v17, 31, v16
	v_add_f32_e32 v20, v24, v97
	v_lshl_add_u64 v[18:19], v[16:17], 2, v[134:135]
	global_store_dword v[18:19], v20, off
	v_mul_f32_e32 v18, v209, v20
	v_cvt_pk_bf16_f32 v18, v18, s0
	v_lshl_add_u64 v[16:17], v[16:17], 1, v[136:137]
	global_store_short v[16:17], v18, off
	v_or_b32_e32 v16, 0x38800, v130
	v_ashrrev_i32_e32 v17, 31, v16
	v_add_f32_e32 v20, v25, v103
	v_lshl_add_u64 v[18:19], v[16:17], 2, v[134:135]
	global_store_dword v[18:19], v20, off
	v_mul_f32_e32 v18, v209, v20
	v_cvt_pk_bf16_f32 v18, v18, s0
	v_lshl_add_u64 v[16:17], v[16:17], 1, v[136:137]
	global_store_short v[16:17], v18, off
	v_or_b32_e32 v16, 0x39000, v130
	v_ashrrev_i32_e32 v17, 31, v16
	s_waitcnt vmcnt(62)
	v_add_f32_e32 v20, v26, v104
	v_lshl_add_u64 v[18:19], v[16:17], 2, v[134:135]
	global_store_dword v[18:19], v20, off
	v_mul_f32_e32 v18, v209, v20
	v_cvt_pk_bf16_f32 v18, v18, s0
	v_lshl_add_u64 v[16:17], v[16:17], 1, v[136:137]
	global_store_short v[16:17], v18, off
	v_or_b32_e32 v16, 0x39800, v130
	v_ashrrev_i32_e32 v17, 31, v16
	v_add_f32_e32 v20, v27, v105
	v_lshl_add_u64 v[18:19], v[16:17], 2, v[134:135]
	global_store_dword v[18:19], v20, off
	v_mul_f32_e32 v18, v209, v20
	v_cvt_pk_bf16_f32 v18, v18, s0
	v_lshl_add_u64 v[16:17], v[16:17], 1, v[136:137]
	global_store_short v[16:17], v18, off
	v_or_b32_e32 v16, 0x3c000, v130
	v_ashrrev_i32_e32 v17, 31, v16
	v_add_f32_e32 v20, v28, v106
	v_lshl_add_u64 v[18:19], v[16:17], 2, v[134:135]
	global_store_dword v[18:19], v20, off
	v_mul_f32_e32 v18, v209, v20
	v_cvt_pk_bf16_f32 v18, v18, s0
	v_lshl_add_u64 v[16:17], v[16:17], 1, v[136:137]
	global_store_short v[16:17], v18, off
	v_or_b32_e32 v16, 0x3c800, v130
	v_ashrrev_i32_e32 v17, 31, v16
	v_add_f32_e32 v20, v29, v107
	v_lshl_add_u64 v[18:19], v[16:17], 2, v[134:135]
	global_store_dword v[18:19], v20, off
	v_mul_f32_e32 v18, v209, v20
	v_cvt_pk_bf16_f32 v18, v18, s0
	v_lshl_add_u64 v[16:17], v[16:17], 1, v[136:137]
	global_store_short v[16:17], v18, off
	v_or_b32_e32 v16, 0x3d000, v130
	v_ashrrev_i32_e32 v17, 31, v16
	v_add_f32_e32 v20, v30, v108
	v_lshl_add_u64 v[18:19], v[16:17], 2, v[134:135]
	global_store_dword v[18:19], v20, off
	v_mul_f32_e32 v18, v209, v20
	v_cvt_pk_bf16_f32 v18, v18, s0
	v_lshl_add_u64 v[16:17], v[16:17], 1, v[136:137]
	global_store_short v[16:17], v18, off
	v_or_b32_e32 v16, 0x3d800, v130
	v_ashrrev_i32_e32 v17, 31, v16
	v_add_f32_e32 v20, v31, v109
	v_lshl_add_u64 v[18:19], v[16:17], 2, v[134:135]
	global_store_dword v[18:19], v20, off
	v_mul_f32_e32 v18, v209, v20
	v_cvt_pk_bf16_f32 v18, v18, s0
	v_lshl_add_u64 v[16:17], v[16:17], 1, v[136:137]
	global_store_short v[16:17], v18, off
	v_or_b32_e32 v16, 0x30020, v130
	v_ashrrev_i32_e32 v17, 31, v16
	s_waitcnt vmcnt(47)
	v_add_f32_e32 v0, v0, v36
	v_lshl_add_u64 v[18:19], v[16:17], 2, v[134:135]
	global_store_dword v[18:19], v0, off
	v_mul_f32_e32 v0, v128, v0
	v_cvt_pk_bf16_f32 v0, v0, s0
	v_lshl_add_u64 v[16:17], v[16:17], 1, v[136:137]
	global_store_short v[16:17], v0, off
	v_or_b32_e32 v0, 0x30820, v130
	s_waitcnt vmcnt(48)
	v_add_f32_e32 v18, v1, v37
	v_ashrrev_i32_e32 v1, 31, v0
	v_lshl_add_u64 v[16:17], v[0:1], 2, v[134:135]
	global_store_dword v[16:17], v18, off
	v_mul_f32_e32 v16, v128, v18
	v_cvt_pk_bf16_f32 v16, v16, s0
	v_lshl_add_u64 v[0:1], v[0:1], 1, v[136:137]
	global_store_short v[0:1], v16, off
	v_or_b32_e32 v0, 0x31020, v130
	v_ashrrev_i32_e32 v1, 31, v0
	s_waitcnt vmcnt(49)
	v_add_f32_e32 v2, v2, v38
	v_lshl_add_u64 v[16:17], v[0:1], 2, v[134:135]
	global_store_dword v[16:17], v2, off
	v_mul_f32_e32 v2, v128, v2
	v_cvt_pk_bf16_f32 v2, v2, s0
	v_lshl_add_u64 v[0:1], v[0:1], 1, v[136:137]
	global_store_short v[0:1], v2, off
	v_or_b32_e32 v0, 0x31820, v130
	v_ashrrev_i32_e32 v1, 31, v0
	s_waitcnt vmcnt(50)
	v_add_f32_e32 v16, v3, v39
	v_lshl_add_u64 v[2:3], v[0:1], 2, v[134:135]
	global_store_dword v[2:3], v16, off
	v_mul_f32_e32 v2, v128, v16
	v_cvt_pk_bf16_f32 v2, v2, s0
	v_lshl_add_u64 v[0:1], v[0:1], 1, v[136:137]
	global_store_short v[0:1], v2, off
	v_or_b32_e32 v0, 0x34020, v130
	v_ashrrev_i32_e32 v1, 31, v0
	s_waitcnt vmcnt(51)
	v_add_f32_e32 v4, v4, v40
	v_lshl_add_u64 v[2:3], v[0:1], 2, v[134:135]
	global_store_dword v[2:3], v4, off
	v_mul_f32_e32 v2, v128, v4
	v_cvt_pk_bf16_f32 v2, v2, s0
	v_lshl_add_u64 v[0:1], v[0:1], 1, v[136:137]
	global_store_short v[0:1], v2, off
	v_or_b32_e32 v0, 0x34820, v130
	v_ashrrev_i32_e32 v1, 31, v0
	s_waitcnt vmcnt(52)
	v_add_f32_e32 v4, v5, v41
	v_lshl_add_u64 v[2:3], v[0:1], 2, v[134:135]
	global_store_dword v[2:3], v4, off
	v_mul_f32_e32 v2, v128, v4
	v_cvt_pk_bf16_f32 v2, v2, s0
	v_lshl_add_u64 v[0:1], v[0:1], 1, v[136:137]
	global_store_short v[0:1], v2, off
	v_or_b32_e32 v0, 0x35020, v130
	v_ashrrev_i32_e32 v1, 31, v0
	s_waitcnt vmcnt(53)
	v_add_f32_e32 v4, v6, v42
	v_lshl_add_u64 v[2:3], v[0:1], 2, v[134:135]
	global_store_dword v[2:3], v4, off
	v_mul_f32_e32 v2, v128, v4
	v_cvt_pk_bf16_f32 v2, v2, s0
	v_lshl_add_u64 v[0:1], v[0:1], 1, v[136:137]
	global_store_short v[0:1], v2, off
	v_or_b32_e32 v0, 0x35820, v130
	v_ashrrev_i32_e32 v1, 31, v0
	s_waitcnt vmcnt(54)
	v_add_f32_e32 v4, v7, v43
	v_lshl_add_u64 v[2:3], v[0:1], 2, v[134:135]
	global_store_dword v[2:3], v4, off
	v_mul_f32_e32 v2, v128, v4
	v_cvt_pk_bf16_f32 v2, v2, s0
	v_lshl_add_u64 v[0:1], v[0:1], 1, v[136:137]
	global_store_short v[0:1], v2, off
	v_or_b32_e32 v0, 0x38020, v130
	v_ashrrev_i32_e32 v1, 31, v0
	s_waitcnt vmcnt(55)
	v_add_f32_e32 v4, v8, v44
	v_lshl_add_u64 v[2:3], v[0:1], 2, v[134:135]
	global_store_dword v[2:3], v4, off
	v_mul_f32_e32 v2, v128, v4
	v_cvt_pk_bf16_f32 v2, v2, s0
	v_lshl_add_u64 v[0:1], v[0:1], 1, v[136:137]
	global_store_short v[0:1], v2, off
	v_or_b32_e32 v0, 0x38820, v130
	v_ashrrev_i32_e32 v1, 31, v0
	s_waitcnt vmcnt(56)
	v_add_f32_e32 v4, v9, v45
	v_lshl_add_u64 v[2:3], v[0:1], 2, v[134:135]
	global_store_dword v[2:3], v4, off
	v_mul_f32_e32 v2, v128, v4
	v_cvt_pk_bf16_f32 v2, v2, s0
	v_lshl_add_u64 v[0:1], v[0:1], 1, v[136:137]
	global_store_short v[0:1], v2, off
	v_or_b32_e32 v0, 0x39020, v130
	v_ashrrev_i32_e32 v1, 31, v0
	s_waitcnt vmcnt(57)
	v_add_f32_e32 v4, v10, v46
	v_lshl_add_u64 v[2:3], v[0:1], 2, v[134:135]
	global_store_dword v[2:3], v4, off
	v_mul_f32_e32 v2, v128, v4
	v_cvt_pk_bf16_f32 v2, v2, s0
	v_lshl_add_u64 v[0:1], v[0:1], 1, v[136:137]
	global_store_short v[0:1], v2, off
	v_or_b32_e32 v0, 0x39820, v130
	v_ashrrev_i32_e32 v1, 31, v0
	s_waitcnt vmcnt(58)
	v_add_f32_e32 v4, v11, v47
	v_lshl_add_u64 v[2:3], v[0:1], 2, v[134:135]
	global_store_dword v[2:3], v4, off
	v_mul_f32_e32 v2, v128, v4
	v_cvt_pk_bf16_f32 v2, v2, s0
	v_lshl_add_u64 v[0:1], v[0:1], 1, v[136:137]
	global_store_short v[0:1], v2, off
	v_or_b32_e32 v0, 0x3c020, v130
	v_ashrrev_i32_e32 v1, 31, v0
	s_waitcnt vmcnt(59)
	v_add_f32_e32 v4, v12, v48
	v_lshl_add_u64 v[2:3], v[0:1], 2, v[134:135]
	global_store_dword v[2:3], v4, off
	v_mul_f32_e32 v2, v128, v4
	v_cvt_pk_bf16_f32 v2, v2, s0
	v_lshl_add_u64 v[0:1], v[0:1], 1, v[136:137]
	global_store_short v[0:1], v2, off
	v_or_b32_e32 v0, 0x3c820, v130
	v_ashrrev_i32_e32 v1, 31, v0
	s_waitcnt vmcnt(60)
	v_add_f32_e32 v4, v13, v49
	v_lshl_add_u64 v[2:3], v[0:1], 2, v[134:135]
	global_store_dword v[2:3], v4, off
	v_mul_f32_e32 v2, v128, v4
	v_cvt_pk_bf16_f32 v2, v2, s0
	v_lshl_add_u64 v[0:1], v[0:1], 1, v[136:137]
	global_store_short v[0:1], v2, off
	v_or_b32_e32 v0, 0x3d020, v130
	v_ashrrev_i32_e32 v1, 31, v0
	s_waitcnt vmcnt(61)
	v_add_f32_e32 v4, v14, v50
	v_lshl_add_u64 v[2:3], v[0:1], 2, v[134:135]
	global_store_dword v[2:3], v4, off
	v_mul_f32_e32 v2, v128, v4
	v_cvt_pk_bf16_f32 v2, v2, s0
	v_lshl_add_u64 v[0:1], v[0:1], 1, v[136:137]
	global_store_short v[0:1], v2, off
	v_or_b32_e32 v0, 0x3d820, v130
	v_ashrrev_i32_e32 v1, 31, v0
	s_waitcnt vmcnt(62)
	v_add_f32_e32 v4, v15, v51
	v_lshl_add_u64 v[2:3], v[0:1], 2, v[134:135]
	global_store_dword v[2:3], v4, off
	v_mul_f32_e32 v2, v128, v4
	v_cvt_pk_bf16_f32 v2, v2, s0
	v_lshl_add_u64 v[0:1], v[0:1], 1, v[136:137]
	global_store_short v[0:1], v2, off
	v_add_u32_e32 v206, s46, v206
	v_add_u32_e32 v208, s46, v208
	v_cmp_le_i32_e64 s[40:41], s51, v206
	s_and_b64 vcc, exec, s[40:41]
	s_cbranch_vccz .LBB0_707

.LBB0_715:
	s_add_i32 s16, s22, s33
	s_cmpk_gt_i32 s16, 0x7f
	s_mov_b64 s[30:31], -1
	s_cbranch_scc1 .LBB0_714
	s_ashr_i32 s30, s16, 31
	s_lshr_b32 s30, s30, 25
	s_add_i32 s30, s16, s30
	s_ashr_i32 s61, s30, 7
	s_and_b32 s30, s30, 0xffffff80
	s_lshl_b32 s31, s61, 3
	s_sub_i32 s30, s16, s30
	s_sub_i32 s34, 8, s31
	s_cmpk_gt_i32 s16, 0x7f
	s_cselect_b32 s16, s34, 8
	s_abs_i32 s34, s16
	v_cvt_f32_u32_e32 v0, s34
	s_sub_i32 s41, 0, s34
	s_abs_i32 s35, s30
	s_xor_b32 s40, s30, s16
	v_rcp_iflag_f32_e32 v0, v0
	s_ashr_i32 s40, s40, 31
	v_mov_b32_e32 v10, v204
	v_mul_f32_e32 v0, 0x4f7ffffe, v0
	v_cvt_u32_f32_e32 v0, v0
	v_ashrrev_i32_e32 v1, 6, v10
	v_lshlrev_b32_e32 v3, 9, v10
	v_and_b32_e32 v3, 0x7800, v3
	v_readfirstlane_b32 s42, v0
	s_mul_i32 s41, s41, s42
	s_mul_hi_u32 s41, s42, s41
	s_add_i32 s42, s42, s41
	s_mul_hi_u32 s41, s35, s42
	s_mul_i32 s42, s41, s34
	s_sub_i32 s35, s35, s42
	s_add_i32 s43, s41, 1
	s_sub_i32 s42, s35, s34
	s_cmp_ge_u32 s35, s34
	s_cselect_b32 s41, s43, s41
	s_cselect_b32 s35, s42, s35
	s_add_i32 s42, s41, 1
	s_cmp_ge_u32 s35, s34
	s_cselect_b32 s34, s42, s41
	s_xor_b32 s34, s34, s40
	s_sub_i32 s34, s34, s40
	s_mul_i32 s62, s16, s34
	s_sub_i32 s55, s30, s62
	s_add_i32 s55, s55, s31
	s_lshl_b32 s16, s55, 6
	s_add_i32 s40, s16, 0x2000
	s_ashr_i32 s41, s40, 31
	v_bfe_u32 v0, v10, 4, 2
	s_lshl_b64 s[30:31], s[40:41], 11
	s_lshl_b64 s[40:41], s[40:41], 12
	v_bitop3_b32 v0, v0, v10, 3 bitop3:0x78
	s_add_u32 s40, s50, s40
	v_lshlrev_b32_e32 v2, 3, v0
	v_lshlrev_b32_e32 v0, 15, v1
	v_lshlrev_b32_e32 v4, 16, v1
	v_lshlrev_b32_e32 v1, 10, v1
	s_addc_u32 s41, s51, s41
	s_ashr_i32 s35, s34, 31
	v_or3_b32 v0, v3, v0, v2
	v_add_u32_e32 v40, 32, v1
	s_lshl_b64 s[42:43], s[34:35], 19
	v_or3_b32 v2, v3, v4, v2
	v_add_u32_e32 v41, v40, v1
	v_ashrrev_i32_e32 v1, 31, v0
	s_add_u32 s44, s47, s42
	v_add_u32_e32 v8, 0x1000, v41
	v_lshlrev_b64 v[0:1], 1, v[0:1]
	v_ashrrev_i32_e32 v3, 31, v2
	v_readfirstlane_b32 s35, v40
	s_addc_u32 s45, s49, s43
	v_lshl_add_u64 v[4:5], s[40:41], 0, v[0:1]
	v_lshlrev_b64 v[2:3], 1, v[2:3]
	s_mov_b32 m0, s35
	v_readfirstlane_b32 s35, v8
	v_add_u32_e32 v11, 0x1400, v41
	v_lshl_add_u64 v[6:7], s[44:45], 0, v[2:3]
	s_mov_b32 m0, s35
	v_readfirstlane_b32 s35, v11
	v_add_u32_e32 v11, 0x3000, v40
	v_lshl_add_u64 v[8:9], v[6:7], 0, s[6:7]
	s_mov_b32 m0, s35
	v_readfirstlane_b32 s35, v11
	v_add_u32_e32 v11, 0x4000, v41
	v_lshl_add_u64 v[8:9], v[4:5], 0, 64
	s_mov_b32 m0, s35
	v_readfirstlane_b32 s35, v11
	v_add_u32_e32 v11, 0x4400, v41
	v_lshl_add_u64 v[8:9], v[6:7], 0, 64
	s_mov_b32 m0, s35
	v_readfirstlane_b32 s35, v11
	v_lshl_add_u64 v[8:9], v[6:7], 0, s[8:9]
	s_mov_b32 m0, s35
	v_lshl_add_u64 v[4:5], v[4:5], 0, s[10:11]
	v_add_u32_e32 v8, 0x6000, v40
	s_add_u32 s40, s94, s42
	v_readfirstlane_b32 s35, v8
	v_add_u32_e32 v8, 0x7000, v41
	s_mov_b32 m0, s35
	v_readfirstlane_b32 s35, v8
	v_lshl_add_u64 v[4:5], v[6:7], 0, s[10:11]
	s_mov_b32 m0, s35
	s_addc_u32 s41, s95, s43
	v_lshl_add_u64 v[4:5], v[6:7], 0, s[12:13]
	v_add_u32_e32 v6, 0x7400, v41
	v_lshl_add_u64 v[32:33], s[40:41], 0, v[2:3]
	v_readfirstlane_b32 s35, v6
	s_mov_b32 m0, s35
	s_sub_i32 s40, s48, s62
	s_mulk_i32 s61, 0x78
	s_sub_i32 s40, s40, s61
	s_lshl_b32 s40, s40, 6
	v_and_b32_e32 v4, 31, v10
	v_lshrrev_b32_e32 v6, 2, v10
	s_addk_i32 s40, 0x2000
	v_and_or_b32 v4, v6, s54, v4
	s_ashr_i32 s41, s40, 31
	v_bfe_u32 v5, v10, 5, 1
	v_lshlrev_b32_e32 v42, 6, v4
	v_lshlrev_b32_e32 v4, 6, v10
	s_lshl_b64 s[40:41], s[40:41], 12
	v_bfe_u32 v7, v10, 2, 2
	v_and_b32_e32 v43, 0x17c0, v4
	v_bitop3_b32 v4, v5, v6, 3 bitop3:0x78
	s_add_u32 s40, s94, s40
	v_lshlrev_b32_e32 v44, 4, v4
	v_bitop3_b32 v4, v5, v7, 2 bitop3:0x36
	s_addc_u32 s41, s95, s41
	v_mov_b32_e32 v16, 0
	s_mov_b32 s60, 0
	s_mov_b32 s35, 1
	v_lshlrev_b32_e32 v45, 4, v4
	v_lshl_add_u64 v[34:35], s[40:41], 0, v[0:1]
	s_mov_b64 s[40:41], 0
	v_mov_b32_e32 v17, v16
	v_mov_b32_e32 v18, v16
	v_mov_b32_e32 v19, v16
	v_mov_b32_e32 v20, v16
	v_mov_b32_e32 v21, v16
	v_mov_b32_e32 v22, v16
	v_mov_b32_e32 v23, v16
	v_mov_b32_e32 v24, v16
	v_mov_b32_e32 v25, v16
	v_mov_b32_e32 v26, v16
	v_mov_b32_e32 v27, v16
	v_mov_b32_e32 v28, v16
	v_mov_b32_e32 v29, v16
	v_mov_b32_e32 v30, v16
	v_mov_b32_e32 v31, v16
	v_mov_b32_e32 v0, v16
	v_mov_b32_e32 v1, v16
	v_mov_b32_e32 v2, v16
	v_mov_b32_e32 v3, v16
	v_mov_b32_e32 v4, v16
	v_mov_b32_e32 v5, v16
	v_mov_b32_e32 v6, v16
	v_mov_b32_e32 v7, v16
	v_mov_b32_e32 v8, v16
	v_mov_b32_e32 v9, v16
	v_mov_b32_e32 v10, v16
	v_mov_b32_e32 v11, v16
	v_mov_b32_e32 v12, v16
	v_mov_b32_e32 v13, v16
	v_mov_b32_e32 v14, v16
	v_mov_b32_e32 v15, v16
	v_add3_u32 v184, v42, v44, 32
	v_add3_u32 v185, v42, v45, 32
	v_add_u32_e32 v186, 0x1020, v43
	v_add_u32_e32 v187, v186, v45
	v_add_u32_e32 v186, v186, v44
	v_subrev_u32_e32 v188, s94, v34
	v_subrev_u32_e32 v189, s94, v32
	v_add_u32_e32 v188, 0x15c88000, v188
	v_add_u32_e32 v189, 0x18a88000, v189
	v_add_u32_e32 v190, 0x10000, v189
	v_readfirstlane_b32 s80, v40
	v_readfirstlane_b32 s81, v41
	s_add_u32 s81, s81, 0x1000
	s_mov_b64 s[76:77], s[94:95]
	s_add_u32 s78, s94, 64
	s_addc_u32 s79, s95, 0
	v_bfe_u32 v191, v204, 2, 4
	v_lshlrev_b32_e32 v191, 7, v191
	s_mov_b32 s83, 0
	s_movk_i32 s84, 0x800
	v_xad_u32 v192, s83, v191, v189
	v_xad_u32 v193, s84, v191, v190
	s_add_u32 m0, s80, 0x0
	s_nop 0
	global_load_lds_dwordx4 v188, s[76:77]
	s_add_u32 m0, s80, 0x3000
	s_nop 0
	global_load_lds_dwordx4 v188, s[78:79]
	s_add_u32 m0, s81, 0x0
	s_nop 0
	global_load_lds_dwordx4 v192, s[94:95]
	s_add_u32 m0, s81, 0x2fc0
	s_nop 0
	global_load_lds_dwordx4 v192, s[94:95] offset:64
	s_add_u32 m0, s81, 0x400
	s_nop 0
	global_load_lds_dwordx4 v193, s[94:95]
	s_add_u32 m0, s81, 0x33c0
	s_nop 0
	global_load_lds_dwordx4 v193, s[94:95] offset:64
	s_add_u32 s83, s83, 0x80
	s_xor_b32 s84, s83, 0x800
	s_add_u32 s76, s76, 128
	s_addc_u32 s77, s77, 0
	s_add_u32 s78, s78, 128
	s_addc_u32 s79, s79, 0
	v_xad_u32 v192, s83, v191, v189
	v_xad_u32 v193, s84, v191, v190
	s_add_u32 m0, s80, 0x6000
	s_nop 0
	global_load_lds_dwordx4 v188, s[76:77]
	s_add_u32 m0, s80, 0x9000
	s_nop 0
	global_load_lds_dwordx4 v188, s[78:79]
	s_add_u32 m0, s81, 0x6000
	s_nop 0
	global_load_lds_dwordx4 v192, s[94:95]
	s_add_u32 m0, s81, 0x8fc0
	s_nop 0
	global_load_lds_dwordx4 v192, s[94:95] offset:64
	s_add_u32 m0, s81, 0x6400
	s_nop 0
	global_load_lds_dwordx4 v193, s[94:95]
	s_add_u32 m0, s81, 0x93c0
	s_nop 0
	global_load_lds_dwordx4 v193, s[94:95] offset:64
	s_add_u32 s83, s83, 0x80
	s_xor_b32 s84, s83, 0x800
	s_add_u32 s76, s76, 128
	s_addc_u32 s77, s77, 0
	s_add_u32 s78, s78, 128
	s_addc_u32 s79, s79, 0
	v_xad_u32 v192, s83, v191, v189
	v_xad_u32 v193, s84, v191, v190
	s_add_u32 m0, s80, 0xc000
	s_nop 0
	global_load_lds_dwordx4 v188, s[76:77]
	s_add_u32 m0, s80, 0xf000
	s_nop 0
	global_load_lds_dwordx4 v188, s[78:79]
	s_add_u32 m0, s81, 0xc000
	s_nop 0
	global_load_lds_dwordx4 v192, s[94:95]
	s_add_u32 m0, s81, 0xefc0
	s_nop 0
	global_load_lds_dwordx4 v192, s[94:95] offset:64
	s_add_u32 m0, s81, 0xc400
	s_nop 0
	global_load_lds_dwordx4 v193, s[94:95]
	s_add_u32 m0, s81, 0xf3c0
	s_nop 0
	global_load_lds_dwordx4 v193, s[94:95] offset:64
	s_add_u32 s83, s83, 0x80
	s_xor_b32 s84, s83, 0x800
	s_add_u32 s76, s76, 128
	s_addc_u32 s77, s77, 0
	s_add_u32 s78, s78, 128
	s_addc_u32 s79, s79, 0
	s_waitcnt vmcnt(13)
	s_barrier
	ds_read_b128 v[160:163], v186 offset:0
	ds_read_b128 v[164:167], v186 offset:2048
	ds_read_b128 v[168:171], v184 offset:0
	s_waitcnt lgkmcnt(0)
	v_mfma_f32_32x32x16_bf16 v[16:31], v[168:171], v[160:163], v[16:31]
	v_mfma_f32_32x32x16_bf16 v[0:15], v[168:171], v[164:167], v[0:15]
	ds_read_b128 v[172:175], v187 offset:0
	ds_read_b128 v[176:179], v187 offset:2048
	ds_read_b128 v[180:183], v185 offset:0
	s_waitcnt vmcnt(12) lgkmcnt(0)
	s_barrier
	ds_read_b128 v[160:163], v186 offset:12288
	ds_read_b128 v[164:167], v186 offset:14336
	ds_read_b128 v[168:171], v184 offset:12288
	v_mfma_f32_32x32x16_bf16 v[16:31], v[180:183], v[172:175], v[16:31]
	v_mfma_f32_32x32x16_bf16 v[0:15], v[180:183], v[176:179], v[0:15]
	s_waitcnt lgkmcnt(0)
	v_mfma_f32_32x32x16_bf16 v[16:31], v[168:171], v[160:163], v[16:31]
	v_mfma_f32_32x32x16_bf16 v[0:15], v[168:171], v[164:167], v[0:15]
	ds_read_b128 v[172:175], v187 offset:12288
	ds_read_b128 v[176:179], v187 offset:14336
	ds_read_b128 v[180:183], v185 offset:12288
	s_waitcnt vmcnt(7) lgkmcnt(0)
	s_barrier
	ds_read_b128 v[160:163], v186 offset:24576
	ds_read_b128 v[164:167], v186 offset:26624
	ds_read_b128 v[168:171], v184 offset:24576
	v_mfma_f32_32x32x16_bf16 v[16:31], v[180:183], v[172:175], v[16:31]
	v_mfma_f32_32x32x16_bf16 v[0:15], v[180:183], v[176:179], v[0:15]
	s_add_u32 m0, s80, 0x0
	s_nop 0
	global_load_lds_dwordx4 v188, s[76:77]
	s_add_u32 m0, s80, 0x3000
	s_nop 0
	global_load_lds_dwordx4 v188, s[78:79]
	s_waitcnt lgkmcnt(0)
	v_mfma_f32_32x32x16_bf16 v[16:31], v[168:171], v[160:163], v[16:31]
	v_mfma_f32_32x32x16_bf16 v[0:15], v[168:171], v[164:167], v[0:15]
	ds_read_b128 v[172:175], v187 offset:24576
	ds_read_b128 v[176:179], v187 offset:26624
	ds_read_b128 v[180:183], v185 offset:24576
	v_xad_u32 v192, s83, v191, v189
	v_xad_u32 v193, s84, v191, v190
	s_add_u32 m0, s81, 0x0
	s_nop 0
	global_load_lds_dwordx4 v192, s[94:95]
	s_add_u32 m0, s81, 0x2fc0
	s_nop 0
	global_load_lds_dwordx4 v192, s[94:95] offset:64
	s_add_u32 m0, s81, 0x400
	s_nop 0
	global_load_lds_dwordx4 v193, s[94:95]
	s_add_u32 m0, s81, 0x33c0
	s_nop 0
	global_load_lds_dwordx4 v193, s[94:95] offset:64
	s_add_u32 s83, s83, 0x80
	s_xor_b32 s84, s83, 0x800
	s_add_u32 s76, s76, 128
	s_addc_u32 s77, s77, 0
	s_add_u32 s78, s78, 128
	s_addc_u32 s79, s79, 0
	s_waitcnt vmcnt(12) lgkmcnt(0)
	s_barrier
	ds_read_b128 v[160:163], v186 offset:36864
	ds_read_b128 v[164:167], v186 offset:38912
	ds_read_b128 v[168:171], v184 offset:36864
	v_mfma_f32_32x32x16_bf16 v[16:31], v[180:183], v[172:175], v[16:31]
	v_mfma_f32_32x32x16_bf16 v[0:15], v[180:183], v[176:179], v[0:15]
	s_waitcnt lgkmcnt(0)
	v_mfma_f32_32x32x16_bf16 v[16:31], v[168:171], v[160:163], v[16:31]
	v_mfma_f32_32x32x16_bf16 v[0:15], v[168:171], v[164:167], v[0:15]
	ds_read_b128 v[172:175], v187 offset:36864
	ds_read_b128 v[176:179], v187 offset:38912
	ds_read_b128 v[180:183], v185 offset:36864
	s_waitcnt vmcnt(7) lgkmcnt(0)
	s_barrier
	ds_read_b128 v[160:163], v186 offset:49152
	ds_read_b128 v[164:167], v186 offset:51200
	ds_read_b128 v[168:171], v184 offset:49152
	v_mfma_f32_32x32x16_bf16 v[16:31], v[180:183], v[172:175], v[16:31]
	v_mfma_f32_32x32x16_bf16 v[0:15], v[180:183], v[176:179], v[0:15]
	s_add_u32 m0, s80, 0x6000
	s_nop 0
	global_load_lds_dwordx4 v188, s[76:77]
	s_add_u32 m0, s80, 0x9000
	s_nop 0
	global_load_lds_dwordx4 v188, s[78:79]
	s_waitcnt lgkmcnt(0)
	v_mfma_f32_32x32x16_bf16 v[16:31], v[168:171], v[160:163], v[16:31]
	v_mfma_f32_32x32x16_bf16 v[0:15], v[168:171], v[164:167], v[0:15]
	ds_read_b128 v[172:175], v187 offset:49152
	ds_read_b128 v[176:179], v187 offset:51200
	ds_read_b128 v[180:183], v185 offset:49152
	v_xad_u32 v192, s83, v191, v189
	v_xad_u32 v193, s84, v191, v190
	s_add_u32 m0, s81, 0x6000
	s_nop 0
	global_load_lds_dwordx4 v192, s[94:95]
	s_add_u32 m0, s81, 0x8fc0
	s_nop 0
	global_load_lds_dwordx4 v192, s[94:95] offset:64
	s_add_u32 m0, s81, 0x6400
	s_nop 0
	global_load_lds_dwordx4 v193, s[94:95]
	s_add_u32 m0, s81, 0x93c0
	s_nop 0
	global_load_lds_dwordx4 v193, s[94:95] offset:64
	s_add_u32 s83, s83, 0x80
	s_xor_b32 s84, s83, 0x800
	s_add_u32 s76, s76, 128
	s_addc_u32 s77, s77, 0
	s_add_u32 s78, s78, 128
	s_addc_u32 s79, s79, 0
	s_waitcnt vmcnt(12) lgkmcnt(0)
	s_barrier
	ds_read_b128 v[160:163], v186 offset:61440
	ds_read_b128 v[164:167], v186 offset:63488
	ds_read_b128 v[168:171], v184 offset:61440
	v_mfma_f32_32x32x16_bf16 v[16:31], v[180:183], v[172:175], v[16:31]
	v_mfma_f32_32x32x16_bf16 v[0:15], v[180:183], v[176:179], v[0:15]
	s_waitcnt lgkmcnt(0)
	v_mfma_f32_32x32x16_bf16 v[16:31], v[168:171], v[160:163], v[16:31]
	v_mfma_f32_32x32x16_bf16 v[0:15], v[168:171], v[164:167], v[0:15]
	ds_read_b128 v[172:175], v187 offset:61440
	ds_read_b128 v[176:179], v187 offset:63488
	ds_read_b128 v[180:183], v185 offset:61440
	s_mov_b32 s82, 9
.Lp5s_kloop:
	s_waitcnt vmcnt(6) lgkmcnt(0)
	s_barrier
	ds_read_b128 v[160:163], v186 offset:0
	ds_read_b128 v[164:167], v186 offset:2048
	ds_read_b128 v[168:171], v184 offset:0
	v_mfma_f32_32x32x16_bf16 v[16:31], v[180:183], v[172:175], v[16:31]
	v_mfma_f32_32x32x16_bf16 v[0:15], v[180:183], v[176:179], v[0:15]
	s_add_u32 m0, s80, 0xc000
	s_nop 0
	global_load_lds_dwordx4 v188, s[76:77]
	s_add_u32 m0, s80, 0xf000
	s_nop 0
	global_load_lds_dwordx4 v188, s[78:79]
	s_waitcnt lgkmcnt(0)
	v_mfma_f32_32x32x16_bf16 v[16:31], v[168:171], v[160:163], v[16:31]
	v_mfma_f32_32x32x16_bf16 v[0:15], v[168:171], v[164:167], v[0:15]
	ds_read_b128 v[172:175], v187 offset:0
	ds_read_b128 v[176:179], v187 offset:2048
	ds_read_b128 v[180:183], v185 offset:0
	v_xad_u32 v192, s83, v191, v189
	v_xad_u32 v193, s84, v191, v190
	s_add_u32 m0, s81, 0xc000
	s_nop 0
	global_load_lds_dwordx4 v192, s[94:95]
	s_add_u32 m0, s81, 0xefc0
	s_nop 0
	global_load_lds_dwordx4 v192, s[94:95] offset:64
	s_add_u32 m0, s81, 0xc400
	s_nop 0
	global_load_lds_dwordx4 v193, s[94:95]
	s_add_u32 m0, s81, 0xf3c0
	s_nop 0
	global_load_lds_dwordx4 v193, s[94:95] offset:64
	s_add_u32 s83, s83, 0x80
	s_xor_b32 s84, s83, 0x800
	s_add_u32 s76, s76, 128
	s_addc_u32 s77, s77, 0
	s_add_u32 s78, s78, 128
	s_addc_u32 s79, s79, 0
	s_waitcnt lgkmcnt(0)
	s_barrier
	ds_read_b128 v[160:163], v186 offset:12288
	ds_read_b128 v[164:167], v186 offset:14336
	ds_read_b128 v[168:171], v184 offset:12288
	v_mfma_f32_32x32x16_bf16 v[16:31], v[180:183], v[172:175], v[16:31]
	v_mfma_f32_32x32x16_bf16 v[0:15], v[180:183], v[176:179], v[0:15]
	s_waitcnt lgkmcnt(0)
	v_mfma_f32_32x32x16_bf16 v[16:31], v[168:171], v[160:163], v[16:31]
	v_mfma_f32_32x32x16_bf16 v[0:15], v[168:171], v[164:167], v[0:15]
	ds_read_b128 v[172:175], v187 offset:12288
	ds_read_b128 v[176:179], v187 offset:14336
	ds_read_b128 v[180:183], v185 offset:12288
	s_waitcnt vmcnt(6) lgkmcnt(0)
	s_barrier
	ds_read_b128 v[160:163], v186 offset:24576
	ds_read_b128 v[164:167], v186 offset:26624
	ds_read_b128 v[168:171], v184 offset:24576
	v_mfma_f32_32x32x16_bf16 v[16:31], v[180:183], v[172:175], v[16:31]
	v_mfma_f32_32x32x16_bf16 v[0:15], v[180:183], v[176:179], v[0:15]
	s_add_u32 m0, s80, 0x0
	s_nop 0
	global_load_lds_dwordx4 v188, s[76:77]
	s_add_u32 m0, s80, 0x3000
	s_nop 0
	global_load_lds_dwordx4 v188, s[78:79]
	s_waitcnt lgkmcnt(0)
	v_mfma_f32_32x32x16_bf16 v[16:31], v[168:171], v[160:163], v[16:31]
	v_mfma_f32_32x32x16_bf16 v[0:15], v[168:171], v[164:167], v[0:15]
	ds_read_b128 v[172:175], v187 offset:24576
	ds_read_b128 v[176:179], v187 offset:26624
	ds_read_b128 v[180:183], v185 offset:24576
	v_xad_u32 v192, s83, v191, v189
	v_xad_u32 v193, s84, v191, v190
	s_add_u32 m0, s81, 0x0
	s_nop 0
	global_load_lds_dwordx4 v192, s[94:95]
	s_add_u32 m0, s81, 0x2fc0
	s_nop 0
	global_load_lds_dwordx4 v192, s[94:95] offset:64
	s_add_u32 m0, s81, 0x400
	s_nop 0
	global_load_lds_dwordx4 v193, s[94:95]
	s_add_u32 m0, s81, 0x33c0
	s_nop 0
	global_load_lds_dwordx4 v193, s[94:95] offset:64
	s_add_u32 s83, s83, 0x80
	s_xor_b32 s84, s83, 0x800
	s_add_u32 s76, s76, 128
	s_addc_u32 s77, s77, 0
	s_add_u32 s78, s78, 128
	s_addc_u32 s79, s79, 0
	s_waitcnt lgkmcnt(0)
	s_barrier
	ds_read_b128 v[160:163], v186 offset:36864
	ds_read_b128 v[164:167], v186 offset:38912
	ds_read_b128 v[168:171], v184 offset:36864
	v_mfma_f32_32x32x16_bf16 v[16:31], v[180:183], v[172:175], v[16:31]
	v_mfma_f32_32x32x16_bf16 v[0:15], v[180:183], v[176:179], v[0:15]
	s_waitcnt lgkmcnt(0)
	v_mfma_f32_32x32x16_bf16 v[16:31], v[168:171], v[160:163], v[16:31]
	v_mfma_f32_32x32x16_bf16 v[0:15], v[168:171], v[164:167], v[0:15]
	ds_read_b128 v[172:175], v187 offset:36864
	ds_read_b128 v[176:179], v187 offset:38912
	ds_read_b128 v[180:183], v185 offset:36864
	s_waitcnt vmcnt(6) lgkmcnt(0)
	s_barrier
	ds_read_b128 v[160:163], v186 offset:49152
	ds_read_b128 v[164:167], v186 offset:51200
	ds_read_b128 v[168:171], v184 offset:49152
	v_mfma_f32_32x32x16_bf16 v[16:31], v[180:183], v[172:175], v[16:31]
	v_mfma_f32_32x32x16_bf16 v[0:15], v[180:183], v[176:179], v[0:15]
	s_add_u32 m0, s80, 0x6000
	s_nop 0
	global_load_lds_dwordx4 v188, s[76:77]
	s_add_u32 m0, s80, 0x9000
	s_nop 0
	global_load_lds_dwordx4 v188, s[78:79]
	s_waitcnt lgkmcnt(0)
	v_mfma_f32_32x32x16_bf16 v[16:31], v[168:171], v[160:163], v[16:31]
	v_mfma_f32_32x32x16_bf16 v[0:15], v[168:171], v[164:167], v[0:15]
	ds_read_b128 v[172:175], v187 offset:49152
	ds_read_b128 v[176:179], v187 offset:51200
	ds_read_b128 v[180:183], v185 offset:49152
	v_xad_u32 v192, s83, v191, v189
	v_xad_u32 v193, s84, v191, v190
	s_add_u32 m0, s81, 0x6000
	s_nop 0
	global_load_lds_dwordx4 v192, s[94:95]
	s_add_u32 m0, s81, 0x8fc0
	s_nop 0
	global_load_lds_dwordx4 v192, s[94:95] offset:64
	s_add_u32 m0, s81, 0x6400
	s_nop 0
	global_load_lds_dwordx4 v193, s[94:95]
	s_add_u32 m0, s81, 0x93c0
	s_nop 0
	global_load_lds_dwordx4 v193, s[94:95] offset:64
	s_add_u32 s83, s83, 0x80
	s_xor_b32 s84, s83, 0x800
	s_add_u32 s76, s76, 128
	s_addc_u32 s77, s77, 0
	s_add_u32 s78, s78, 128
	s_addc_u32 s79, s79, 0
	s_waitcnt lgkmcnt(0)
	s_barrier
	ds_read_b128 v[160:163], v186 offset:61440
	ds_read_b128 v[164:167], v186 offset:63488
	ds_read_b128 v[168:171], v184 offset:61440
	v_mfma_f32_32x32x16_bf16 v[16:31], v[180:183], v[172:175], v[16:31]
	v_mfma_f32_32x32x16_bf16 v[0:15], v[180:183], v[176:179], v[0:15]
	s_waitcnt lgkmcnt(0)
	v_mfma_f32_32x32x16_bf16 v[16:31], v[168:171], v[160:163], v[16:31]
	v_mfma_f32_32x32x16_bf16 v[0:15], v[168:171], v[164:167], v[0:15]
	ds_read_b128 v[172:175], v187 offset:61440
	ds_read_b128 v[176:179], v187 offset:63488
	ds_read_b128 v[180:183], v185 offset:61440
	s_sub_u32 s82, s82, 1
	s_cmp_lg_u32 s82, 0
	s_cbranch_scc1 .Lp5s_kloop
	s_waitcnt vmcnt(6) lgkmcnt(0)
	s_barrier
	ds_read_b128 v[160:163], v186 offset:0
	ds_read_b128 v[164:167], v186 offset:2048
	ds_read_b128 v[168:171], v184 offset:0
	v_mfma_f32_32x32x16_bf16 v[16:31], v[180:183], v[172:175], v[16:31]
	v_mfma_f32_32x32x16_bf16 v[0:15], v[180:183], v[176:179], v[0:15]
	s_waitcnt lgkmcnt(0)
	v_mfma_f32_32x32x16_bf16 v[16:31], v[168:171], v[160:163], v[16:31]
	v_mfma_f32_32x32x16_bf16 v[0:15], v[168:171], v[164:167], v[0:15]
	ds_read_b128 v[172:175], v187 offset:0
	ds_read_b128 v[176:179], v187 offset:2048
	ds_read_b128 v[180:183], v185 offset:0
	s_waitcnt lgkmcnt(0)
	s_barrier
	ds_read_b128 v[160:163], v186 offset:12288
	ds_read_b128 v[164:167], v186 offset:14336
	ds_read_b128 v[168:171], v184 offset:12288
	v_mfma_f32_32x32x16_bf16 v[16:31], v[180:183], v[172:175], v[16:31]
	v_mfma_f32_32x32x16_bf16 v[0:15], v[180:183], v[176:179], v[0:15]
	s_waitcnt lgkmcnt(0)
	v_mfma_f32_32x32x16_bf16 v[16:31], v[168:171], v[160:163], v[16:31]
	v_mfma_f32_32x32x16_bf16 v[0:15], v[168:171], v[164:167], v[0:15]
	ds_read_b128 v[172:175], v187 offset:12288
	ds_read_b128 v[176:179], v187 offset:14336
	ds_read_b128 v[180:183], v185 offset:12288
	s_waitcnt vmcnt(0) lgkmcnt(0)
	s_barrier
	ds_read_b128 v[160:163], v186 offset:24576
	ds_read_b128 v[164:167], v186 offset:26624
	ds_read_b128 v[168:171], v184 offset:24576
	v_mfma_f32_32x32x16_bf16 v[16:31], v[180:183], v[172:175], v[16:31]
	v_mfma_f32_32x32x16_bf16 v[0:15], v[180:183], v[176:179], v[0:15]
	s_waitcnt lgkmcnt(0)
	v_mfma_f32_32x32x16_bf16 v[16:31], v[168:171], v[160:163], v[16:31]
	v_mfma_f32_32x32x16_bf16 v[0:15], v[168:171], v[164:167], v[0:15]
	ds_read_b128 v[172:175], v187 offset:24576
	ds_read_b128 v[176:179], v187 offset:26624
	ds_read_b128 v[180:183], v185 offset:24576
	s_waitcnt lgkmcnt(0)
	s_barrier
	ds_read_b128 v[160:163], v186 offset:36864
	ds_read_b128 v[164:167], v186 offset:38912
	ds_read_b128 v[168:171], v184 offset:36864
	v_mfma_f32_32x32x16_bf16 v[16:31], v[180:183], v[172:175], v[16:31]
	v_mfma_f32_32x32x16_bf16 v[0:15], v[180:183], v[176:179], v[0:15]
	s_waitcnt lgkmcnt(0)
	v_mfma_f32_32x32x16_bf16 v[16:31], v[168:171], v[160:163], v[16:31]
	v_mfma_f32_32x32x16_bf16 v[0:15], v[168:171], v[164:167], v[0:15]
	ds_read_b128 v[172:175], v187 offset:36864
	ds_read_b128 v[176:179], v187 offset:38912
	ds_read_b128 v[180:183], v185 offset:36864
	s_waitcnt lgkmcnt(0)
	v_mfma_f32_32x32x16_bf16 v[16:31], v[180:183], v[172:175], v[16:31]
	v_mfma_f32_32x32x16_bf16 v[0:15], v[180:183], v[176:179], v[0:15]
	s_branch .LBB0_713

.LBB0_787:
	v_add_u32_e32 v0, v76, v77
	v_cmp_lt_i32_e32 vcc, s47, v0
	s_cbranch_vccnz .LBB0_786
	v_readfirstlane_b32 s38, v0
	s_ashr_i32 s39, s38, 31
	s_lshr_b32 s39, s39, 25
	s_add_i32 s39, s38, s39
	s_ashr_i32 s44, s39, 7
	s_lshl_b32 s40, s44, 3
	s_and_b32 s39, s39, 0xffffff80
	s_sub_i32 s41, 0x44, s40
	s_cmpk_gt_i32 s38, 0x3ff
	s_cselect_b32 s41, s41, 8
	s_abs_i32 s38, s41
	v_cvt_f32_u32_e32 v1, s38
	v_subrev_u32_e32 v0, s39, v0
	s_sub_i32 s39, 0, s38
	v_sub_u32_e32 v2, 0, v0
	v_rcp_iflag_f32_e32 v1, v1
	v_max_i32_e32 v2, v0, v2
	v_xor_b32_e32 v3, s41, v0
	v_ashrrev_i32_e32 v3, 31, v3
	v_mul_f32_e32 v1, 0x4f7ffffe, v1
	v_cvt_u32_f32_e32 v1, v1
	v_mov_b32_e32 v8, v204
	v_add_u32_e32 v0, s40, v0
	v_mul_lo_u32 v4, s39, v1
	v_mul_hi_u32 v4, v1, v4
	v_add_u32_e32 v1, v1, v4
	v_mul_hi_u32 v1, v2, v1
	v_mul_lo_u32 v4, v1, s38
	v_sub_u32_e32 v2, v2, v4
	v_add_u32_e32 v4, 1, v1
	v_subrev_u32_e32 v5, s38, v2
	v_cmp_le_u32_e32 vcc, s38, v2
	s_mulk_i32 s44, 0x78
	v_and_b32_e32 v9, 31, v8
	v_cndmask_b32_e32 v1, v1, v4, vcc
	v_cndmask_b32_e32 v2, v2, v5, vcc
	v_add_u32_e32 v4, 1, v1
	v_cmp_le_u32_e32 vcc, s38, v2
	v_bfe_u32 v2, v8, 4, 2
	v_bitop3_b32 v2, v2, v8, 3 bitop3:0x78
	v_cndmask_b32_e32 v1, v1, v4, vcc
	v_xor_b32_e32 v1, v1, v3
	v_sub_u32_e32 v1, v1, v3
	v_ashrrev_i32_e32 v3, 6, v8
	v_readfirstlane_b32 s38, v1
	v_lshlrev_b32_e32 v5, 9, v8
	s_mul_i32 s45, s41, s38
	s_ashr_i32 s39, s38, 31
	v_lshlrev_b32_e32 v2, 3, v2
	v_lshlrev_b32_e32 v4, 16, v3
	v_and_b32_e32 v5, 0x7800, v5
	v_subrev_u32_e32 v0, s45, v0
	s_lshl_b64 s[40:41], s[38:39], 19
	v_or3_b32 v2, v5, v4, v2
	v_ashrrev_i32_e32 v1, 31, v0
	s_add_u32 s42, s48, s40
	v_lshl_add_u32 v64, v3, 11, 32
	v_ashrrev_i32_e32 v3, 31, v2
	v_lshlrev_b64 v[66:67], 18, v[0:1]
	v_lshlrev_b64 v[0:1], 19, v[0:1]
	s_addc_u32 s43, s49, s41
	v_lshlrev_b64 v[2:3], 1, v[2:3]
	v_lshl_add_u64 v[0:1], s[6:7], 0, v[0:1]
	v_lshl_add_u64 v[4:5], s[42:43], 0, v[2:3]
	v_readfirstlane_b32 s42, v64
	v_add_u32_e32 v11, 0x400, v64
	v_add_u32_e32 v10, 0x2000, v64
	v_lshl_add_u64 v[0:1], v[0:1], 0, v[2:3]
	s_mov_b32 m0, s42
	v_readfirstlane_b32 s42, v11
	v_lshl_add_u64 v[6:7], v[0:1], 0, s[10:11]
	s_mov_b32 m0, s42
	v_readfirstlane_b32 s42, v10
	v_add_u32_e32 v10, 0x2400, v64
	s_mov_b32 m0, s42
	v_readfirstlane_b32 s42, v10
	v_add_u32_e32 v10, 0x4000, v64
	v_lshl_add_u64 v[6:7], v[4:5], 0, s[10:11]
	s_mov_b32 m0, s42
	v_readfirstlane_b32 s42, v10
	v_add_u32_e32 v10, 0x4400, v64
	v_lshl_add_u64 v[6:7], v[0:1], 0, 64
	s_mov_b32 m0, s42
	v_readfirstlane_b32 s42, v10
	v_add_u32_e32 v10, 0x6000, v64
	v_lshl_add_u64 v[6:7], v[0:1], 0, s[12:13]
	s_mov_b32 m0, s42
	v_readfirstlane_b32 s42, v10
	v_add_u32_e32 v10, 0x6400, v64
	v_lshl_add_u64 v[6:7], v[4:5], 0, 64
	s_mov_b32 m0, s42
	v_readfirstlane_b32 s42, v10
	v_add_u32_e32 v10, 0x8000, v64
	v_lshl_add_u64 v[6:7], v[4:5], 0, s[12:13]
	s_mov_b32 m0, s42
	v_readfirstlane_b32 s42, v10
	v_lshl_add_u64 v[6:7], v[0:1], 0, s[14:15]
	s_mov_b32 m0, s42
	v_lshl_add_u64 v[0:1], v[0:1], 0, s[16:17]
	v_add_u32_e32 v6, 0x8400, v64
	s_add_u32 s40, s94, s40
	v_readfirstlane_b32 s42, v6
	v_add_u32_e32 v6, 0xa000, v64
	s_mov_b32 m0, s42
	v_readfirstlane_b32 s42, v6
	v_lshl_add_u64 v[0:1], v[4:5], 0, s[14:15]
	s_mov_b32 m0, s42
	s_addc_u32 s41, s95, s41
	v_lshl_add_u64 v[0:1], v[4:5], 0, s[16:17]
	v_add_u32_e32 v4, 0xa400, v64
	v_lshrrev_b32_e32 v5, 1, v8
	v_readfirstlane_b32 s42, v4
	s_mov_b32 m0, s42
	v_bfe_u32 v4, v8, 2, 2
	v_bfe_u32 v0, v8, 5, 1
	v_lshrrev_b32_e32 v1, 2, v8
	v_bitop3_b32 v1, v0, v1, 3 bitop3:0x78
	v_bitop3_b32 v0, v0, v4, 2 bitop3:0x36
	v_lshlrev_b32_e32 v82, 4, v0
	v_subrev_u32_e32 v0, s45, v78
	v_subrev_u32_e32 v0, s44, v0
	v_lshlrev_b32_e32 v81, 4, v1
	v_ashrrev_i32_e32 v1, 31, v0
	v_lshlrev_b64 v[0:1], 19, v[0:1]
	v_and_or_b32 v5, v5, s52, v9
	v_lshl_add_u64 v[0:1], s[94:95], 0, v[0:1]
	v_lshlrev_b32_e32 v79, 6, v5
	v_lshlrev_b32_e32 v5, 6, v8
	v_lshl_add_u64 v[70:71], v[0:1], 0, v[2:3]
	v_mov_b32_e32 v0, 0
	s_mov_b32 s54, 0
	s_mov_b32 s53, 1
	v_and_b32_e32 v80, 0x17c0, v5
	v_lshl_add_u64 v[68:69], s[40:41], 0, v[2:3]
	s_mov_b64 s[40:41], 0
	v_mov_b32_e32 v1, v0
	v_mov_b32_e32 v2, v0
	v_mov_b32_e32 v3, v0
	v_mov_b32_e32 v4, v0
	v_mov_b32_e32 v5, v0
	v_mov_b32_e32 v6, v0
	v_mov_b32_e32 v7, v0
	v_mov_b32_e32 v8, v0
	v_mov_b32_e32 v9, v0
	v_mov_b32_e32 v10, v0
	v_mov_b32_e32 v11, v0
	v_mov_b32_e32 v12, v0
	v_mov_b32_e32 v13, v0
	v_mov_b32_e32 v14, v0
	v_mov_b32_e32 v15, v0
	v_mov_b32_e32 v16, v0
	v_mov_b32_e32 v17, v0
	v_mov_b32_e32 v18, v0
	v_mov_b32_e32 v19, v0
	v_mov_b32_e32 v20, v0
	v_mov_b32_e32 v21, v0
	v_mov_b32_e32 v22, v0
	v_mov_b32_e32 v23, v0
	v_mov_b32_e32 v24, v0
	v_mov_b32_e32 v25, v0
	v_mov_b32_e32 v26, v0
	v_mov_b32_e32 v27, v0
	v_mov_b32_e32 v28, v0
	v_mov_b32_e32 v29, v0
	v_mov_b32_e32 v30, v0
	v_mov_b32_e32 v31, v0
	v_mov_b32_e32 v32, v0
	v_mov_b32_e32 v33, v0
	v_mov_b32_e32 v34, v0
	v_mov_b32_e32 v35, v0
	v_mov_b32_e32 v36, v0
	v_mov_b32_e32 v37, v0
	v_mov_b32_e32 v38, v0
	v_mov_b32_e32 v39, v0
	v_mov_b32_e32 v40, v0
	v_mov_b32_e32 v41, v0
	v_mov_b32_e32 v42, v0
	v_mov_b32_e32 v43, v0
	v_mov_b32_e32 v44, v0
	v_mov_b32_e32 v45, v0
	v_mov_b32_e32 v46, v0
	v_mov_b32_e32 v47, v0
	v_mov_b32_e32 v48, v0
	v_mov_b32_e32 v49, v0
	v_mov_b32_e32 v50, v0
	v_mov_b32_e32 v51, v0
	v_mov_b32_e32 v52, v0
	v_mov_b32_e32 v53, v0
	v_mov_b32_e32 v54, v0
	v_mov_b32_e32 v55, v0
	v_mov_b32_e32 v56, v0
	v_mov_b32_e32 v57, v0
	v_mov_b32_e32 v58, v0
	v_mov_b32_e32 v59, v0
	v_mov_b32_e32 v60, v0
	v_mov_b32_e32 v61, v0
	v_mov_b32_e32 v62, v0
	v_mov_b32_e32 v63, v0
	v_add3_u32 v140, v79, v81, 32
	v_add3_u32 v141, v79, v82, 32
	v_add_u32_e32 v142, 0x2020, v80
	v_add_u32_e32 v143, v142, v82
	v_add_u32_e32 v142, v142, v81
	v_subrev_u32_e32 v144, s94, v70
	v_subrev_u32_e32 v146, s94, v68
	v_add_u32_e32 v144, 0x13288000, v144
	v_add_u32_e32 v146, 0x19288000, v146
	v_add_u32_e32 v145, 0x10000, v144
	v_add_u32_e32 v147, 0x10000, v146
	v_readfirstlane_b32 s64, v64
	s_nop 0
	s_add_u32 s65, s64, 0x2000
	s_mov_b64 s[60:61], s[94:95]
	s_add_u32 s62, s94, 64
	s_addc_u32 s63, s95, 0
	v_bfe_u32 v148, v204, 2, 4
	v_lshlrev_b32_e32 v148, 7, v148
	s_mov_b32 s70, 0
	s_movk_i32 s71, 0x800
	v_xad_u32 v149, s70, v148, v146
	v_xad_u32 v150, s71, v148, v147
	s_add_u32 m0, s64, 0x0
	s_nop 0
	global_load_lds_dwordx4 v144, s[60:61]
	s_add_u32 m0, s64, 0x4000
	s_nop 0
	global_load_lds_dwordx4 v144, s[62:63]
	s_add_u32 m0, s64, 0x400
	s_nop 0
	global_load_lds_dwordx4 v145, s[60:61]
	s_add_u32 m0, s64, 0x4400
	s_nop 0
	global_load_lds_dwordx4 v145, s[62:63]
	s_add_u32 m0, s65, 0x0
	s_nop 0
	global_load_lds_dwordx4 v149, s[94:95]
	s_add_u32 m0, s65, 0x3fc0
	s_nop 0
	global_load_lds_dwordx4 v149, s[94:95] offset:64
	s_add_u32 m0, s65, 0x400
	s_nop 0
	global_load_lds_dwordx4 v150, s[94:95]
	s_add_u32 m0, s65, 0x43c0
	s_nop 0
	global_load_lds_dwordx4 v150, s[94:95] offset:64
	s_add_u32 s70, s70, 0x80
	s_xor_b32 s71, s70, 0x800
	s_add_u32 s60, s60, 128
	s_addc_u32 s61, s61, 0
	s_add_u32 s62, s62, 128
	s_addc_u32 s63, s63, 0
	v_xad_u32 v149, s70, v148, v146
	v_xad_u32 v150, s71, v148, v147
	s_add_u32 m0, s64, 0x8000
	s_nop 0
	global_load_lds_dwordx4 v144, s[60:61]
	s_add_u32 m0, s64, 0xc000
	s_nop 0
	global_load_lds_dwordx4 v144, s[62:63]
	s_add_u32 m0, s64, 0x8400
	s_nop 0
	global_load_lds_dwordx4 v145, s[60:61]
	s_add_u32 m0, s64, 0xc400
	s_nop 0
	global_load_lds_dwordx4 v145, s[62:63]
	s_add_u32 m0, s65, 0x8000
	s_nop 0
	global_load_lds_dwordx4 v149, s[94:95]
	s_add_u32 m0, s65, 0xbfc0
	s_nop 0
	global_load_lds_dwordx4 v149, s[94:95] offset:64
	s_add_u32 m0, s65, 0x8400
	s_nop 0
	global_load_lds_dwordx4 v150, s[94:95]
	s_add_u32 m0, s65, 0xc3c0
	s_nop 0
	global_load_lds_dwordx4 v150, s[94:95] offset:64
	s_add_u32 s70, s70, 0x80
	s_xor_b32 s71, s70, 0x800
	s_add_u32 s60, s60, 128
	s_addc_u32 s61, s61, 0
	s_add_u32 s62, s62, 128
	s_addc_u32 s63, s63, 0
	s_waitcnt vmcnt(9)
	s_barrier
	ds_read_b128 v[108:111], v142 offset:0
	ds_read_b128 v[112:115], v142 offset:2048
	ds_read_b128 v[116:119], v140 offset:0
	ds_read_b128 v[120:123], v140 offset:2048
	s_waitcnt lgkmcnt(0)
	v_mfma_f32_32x32x16_bf16 v[48:63], v[116:119], v[108:111], v[48:63]
	v_mfma_f32_32x32x16_bf16 v[32:47], v[116:119], v[112:115], v[32:47]
	v_mfma_f32_32x32x16_bf16 v[16:31], v[120:123], v[108:111], v[16:31]
	v_mfma_f32_32x32x16_bf16 v[0:15], v[120:123], v[112:115], v[0:15]
	ds_read_b128 v[124:127], v143 offset:0
	ds_read_b128 v[128:131], v143 offset:2048
	ds_read_b128 v[132:135], v141 offset:0
	ds_read_b128 v[136:139], v141 offset:2048
	s_waitcnt vmcnt(8) lgkmcnt(0)
	s_barrier
	ds_read_b128 v[108:111], v142 offset:16384
	ds_read_b128 v[112:115], v142 offset:18432
	ds_read_b128 v[116:119], v140 offset:16384
	ds_read_b128 v[120:123], v140 offset:18432
	v_mfma_f32_32x32x16_bf16 v[48:63], v[132:135], v[124:127], v[48:63]
	v_mfma_f32_32x32x16_bf16 v[32:47], v[132:135], v[128:131], v[32:47]
	v_mfma_f32_32x32x16_bf16 v[16:31], v[136:139], v[124:127], v[16:31]
	v_mfma_f32_32x32x16_bf16 v[0:15], v[136:139], v[128:131], v[0:15]
	s_waitcnt lgkmcnt(0)
	v_mfma_f32_32x32x16_bf16 v[48:63], v[116:119], v[108:111], v[48:63]
	v_mfma_f32_32x32x16_bf16 v[32:47], v[116:119], v[112:115], v[32:47]
	v_mfma_f32_32x32x16_bf16 v[16:31], v[120:123], v[108:111], v[16:31]
	v_mfma_f32_32x32x16_bf16 v[0:15], v[120:123], v[112:115], v[0:15]
	ds_read_b128 v[124:127], v143 offset:16384
	ds_read_b128 v[128:131], v143 offset:18432
	ds_read_b128 v[132:135], v141 offset:16384
	ds_read_b128 v[136:139], v141 offset:18432
	s_waitcnt vmcnt(1) lgkmcnt(0)
	s_barrier
	ds_read_b128 v[108:111], v142 offset:32768
	ds_read_b128 v[112:115], v142 offset:34816
	ds_read_b128 v[116:119], v140 offset:32768
	ds_read_b128 v[120:123], v140 offset:34816
	v_mfma_f32_32x32x16_bf16 v[48:63], v[132:135], v[124:127], v[48:63]
	v_mfma_f32_32x32x16_bf16 v[32:47], v[132:135], v[128:131], v[32:47]
	v_mfma_f32_32x32x16_bf16 v[16:31], v[136:139], v[124:127], v[16:31]
	v_mfma_f32_32x32x16_bf16 v[0:15], v[136:139], v[128:131], v[0:15]
	s_add_u32 m0, s64, 0x0
	s_nop 0
	global_load_lds_dwordx4 v144, s[60:61]
	s_add_u32 m0, s64, 0x4000
	s_nop 0
	global_load_lds_dwordx4 v144, s[62:63]
	s_add_u32 m0, s64, 0x400
	s_nop 0
	global_load_lds_dwordx4 v145, s[60:61]
	s_add_u32 m0, s64, 0x4400
	s_nop 0
	global_load_lds_dwordx4 v145, s[62:63]
	s_waitcnt lgkmcnt(0)
	v_mfma_f32_32x32x16_bf16 v[48:63], v[116:119], v[108:111], v[48:63]
	v_mfma_f32_32x32x16_bf16 v[32:47], v[116:119], v[112:115], v[32:47]
	v_mfma_f32_32x32x16_bf16 v[16:31], v[120:123], v[108:111], v[16:31]
	v_mfma_f32_32x32x16_bf16 v[0:15], v[120:123], v[112:115], v[0:15]
	ds_read_b128 v[124:127], v143 offset:32768
	ds_read_b128 v[128:131], v143 offset:34816
	ds_read_b128 v[132:135], v141 offset:32768
	ds_read_b128 v[136:139], v141 offset:34816
	v_xad_u32 v149, s70, v148, v146
	v_xad_u32 v150, s71, v148, v147
	s_add_u32 m0, s65, 0x0
	s_nop 0
	global_load_lds_dwordx4 v149, s[94:95]
	s_add_u32 m0, s65, 0x3fc0
	s_nop 0
	global_load_lds_dwordx4 v149, s[94:95] offset:64
	s_add_u32 m0, s65, 0x400
	s_nop 0
	global_load_lds_dwordx4 v150, s[94:95]
	s_add_u32 m0, s65, 0x43c0
	s_nop 0
	global_load_lds_dwordx4 v150, s[94:95] offset:64
	s_add_u32 s70, s70, 0x80
	s_xor_b32 s71, s70, 0x800
	s_add_u32 s60, s60, 128
	s_addc_u32 s61, s61, 0
	s_add_u32 s62, s62, 128
	s_addc_u32 s63, s63, 0
	s_waitcnt vmcnt(8) lgkmcnt(0)
	s_barrier
	ds_read_b128 v[108:111], v142 offset:49152
	ds_read_b128 v[112:115], v142 offset:51200
	ds_read_b128 v[116:119], v140 offset:49152
	ds_read_b128 v[120:123], v140 offset:51200
	v_mfma_f32_32x32x16_bf16 v[48:63], v[132:135], v[124:127], v[48:63]
	v_mfma_f32_32x32x16_bf16 v[32:47], v[132:135], v[128:131], v[32:47]
	v_mfma_f32_32x32x16_bf16 v[16:31], v[136:139], v[124:127], v[16:31]
	v_mfma_f32_32x32x16_bf16 v[0:15], v[136:139], v[128:131], v[0:15]
	s_waitcnt lgkmcnt(0)
	v_mfma_f32_32x32x16_bf16 v[48:63], v[116:119], v[108:111], v[48:63]
	v_mfma_f32_32x32x16_bf16 v[32:47], v[116:119], v[112:115], v[32:47]
	v_mfma_f32_32x32x16_bf16 v[16:31], v[120:123], v[108:111], v[16:31]
	v_mfma_f32_32x32x16_bf16 v[0:15], v[120:123], v[112:115], v[0:15]
	ds_read_b128 v[124:127], v143 offset:49152
	ds_read_b128 v[128:131], v143 offset:51200
	ds_read_b128 v[132:135], v141 offset:49152
	ds_read_b128 v[136:139], v141 offset:51200
	s_mov_b32 s69, 14
.Lp6_kloop:
	s_waitcnt vmcnt(0) lgkmcnt(0)
	s_barrier
	ds_read_b128 v[108:111], v142 offset:0
	ds_read_b128 v[112:115], v142 offset:2048
	ds_read_b128 v[116:119], v140 offset:0
	ds_read_b128 v[120:123], v140 offset:2048
	v_mfma_f32_32x32x16_bf16 v[48:63], v[132:135], v[124:127], v[48:63]
	v_mfma_f32_32x32x16_bf16 v[32:47], v[132:135], v[128:131], v[32:47]
	v_mfma_f32_32x32x16_bf16 v[16:31], v[136:139], v[124:127], v[16:31]
	v_mfma_f32_32x32x16_bf16 v[0:15], v[136:139], v[128:131], v[0:15]
	s_add_u32 m0, s64, 0x8000
	s_nop 0
	global_load_lds_dwordx4 v144, s[60:61]
	s_add_u32 m0, s64, 0xc000
	s_nop 0
	global_load_lds_dwordx4 v144, s[62:63]
	s_add_u32 m0, s64, 0x8400
	s_nop 0
	global_load_lds_dwordx4 v145, s[60:61]
	s_add_u32 m0, s64, 0xc400
	s_nop 0
	global_load_lds_dwordx4 v145, s[62:63]
	s_waitcnt lgkmcnt(0)
	v_mfma_f32_32x32x16_bf16 v[48:63], v[116:119], v[108:111], v[48:63]
	v_mfma_f32_32x32x16_bf16 v[32:47], v[116:119], v[112:115], v[32:47]
	v_mfma_f32_32x32x16_bf16 v[16:31], v[120:123], v[108:111], v[16:31]
	v_mfma_f32_32x32x16_bf16 v[0:15], v[120:123], v[112:115], v[0:15]
	ds_read_b128 v[124:127], v143 offset:0
	ds_read_b128 v[128:131], v143 offset:2048
	ds_read_b128 v[132:135], v141 offset:0
	ds_read_b128 v[136:139], v141 offset:2048
	v_xad_u32 v149, s70, v148, v146
	v_xad_u32 v150, s71, v148, v147
	s_add_u32 m0, s65, 0x8000
	s_nop 0
	global_load_lds_dwordx4 v149, s[94:95]
	s_add_u32 m0, s65, 0xbfc0
	s_nop 0
	global_load_lds_dwordx4 v149, s[94:95] offset:64
	s_add_u32 m0, s65, 0x8400
	s_nop 0
	global_load_lds_dwordx4 v150, s[94:95]
	s_add_u32 m0, s65, 0xc3c0
	s_nop 0
	global_load_lds_dwordx4 v150, s[94:95] offset:64
	s_add_u32 s70, s70, 0x80
	s_xor_b32 s71, s70, 0x800
	s_add_u32 s60, s60, 128
	s_addc_u32 s61, s61, 0
	s_add_u32 s62, s62, 128
	s_addc_u32 s63, s63, 0
	s_waitcnt lgkmcnt(0)
	s_barrier
	ds_read_b128 v[108:111], v142 offset:16384
	ds_read_b128 v[112:115], v142 offset:18432
	ds_read_b128 v[116:119], v140 offset:16384
	ds_read_b128 v[120:123], v140 offset:18432
	v_mfma_f32_32x32x16_bf16 v[48:63], v[132:135], v[124:127], v[48:63]
	v_mfma_f32_32x32x16_bf16 v[32:47], v[132:135], v[128:131], v[32:47]
	v_mfma_f32_32x32x16_bf16 v[16:31], v[136:139], v[124:127], v[16:31]
	v_mfma_f32_32x32x16_bf16 v[0:15], v[136:139], v[128:131], v[0:15]
	s_waitcnt lgkmcnt(0)
	v_mfma_f32_32x32x16_bf16 v[48:63], v[116:119], v[108:111], v[48:63]
	v_mfma_f32_32x32x16_bf16 v[32:47], v[116:119], v[112:115], v[32:47]
	v_mfma_f32_32x32x16_bf16 v[16:31], v[120:123], v[108:111], v[16:31]
	v_mfma_f32_32x32x16_bf16 v[0:15], v[120:123], v[112:115], v[0:15]
	ds_read_b128 v[124:127], v143 offset:16384
	ds_read_b128 v[128:131], v143 offset:18432
	ds_read_b128 v[132:135], v141 offset:16384
	ds_read_b128 v[136:139], v141 offset:18432
	s_waitcnt vmcnt(0) lgkmcnt(0)
	s_barrier
	ds_read_b128 v[108:111], v142 offset:32768
	ds_read_b128 v[112:115], v142 offset:34816
	ds_read_b128 v[116:119], v140 offset:32768
	ds_read_b128 v[120:123], v140 offset:34816
	v_mfma_f32_32x32x16_bf16 v[48:63], v[132:135], v[124:127], v[48:63]
	v_mfma_f32_32x32x16_bf16 v[32:47], v[132:135], v[128:131], v[32:47]
	v_mfma_f32_32x32x16_bf16 v[16:31], v[136:139], v[124:127], v[16:31]
	v_mfma_f32_32x32x16_bf16 v[0:15], v[136:139], v[128:131], v[0:15]
	s_add_u32 m0, s64, 0x0
	s_nop 0
	global_load_lds_dwordx4 v144, s[60:61]
	s_add_u32 m0, s64, 0x4000
	s_nop 0
	global_load_lds_dwordx4 v144, s[62:63]
	s_add_u32 m0, s64, 0x400
	s_nop 0
	global_load_lds_dwordx4 v145, s[60:61]
	s_add_u32 m0, s64, 0x4400
	s_nop 0
	global_load_lds_dwordx4 v145, s[62:63]
	s_waitcnt lgkmcnt(0)
	v_mfma_f32_32x32x16_bf16 v[48:63], v[116:119], v[108:111], v[48:63]
	v_mfma_f32_32x32x16_bf16 v[32:47], v[116:119], v[112:115], v[32:47]
	v_mfma_f32_32x32x16_bf16 v[16:31], v[120:123], v[108:111], v[16:31]
	v_mfma_f32_32x32x16_bf16 v[0:15], v[120:123], v[112:115], v[0:15]
	ds_read_b128 v[124:127], v143 offset:32768
	ds_read_b128 v[128:131], v143 offset:34816
	ds_read_b128 v[132:135], v141 offset:32768
	ds_read_b128 v[136:139], v141 offset:34816
	v_xad_u32 v149, s70, v148, v146
	v_xad_u32 v150, s71, v148, v147
	s_add_u32 m0, s65, 0x0
	s_nop 0
	global_load_lds_dwordx4 v149, s[94:95]
	s_add_u32 m0, s65, 0x3fc0
	s_nop 0
	global_load_lds_dwordx4 v149, s[94:95] offset:64
	s_add_u32 m0, s65, 0x400
	s_nop 0
	global_load_lds_dwordx4 v150, s[94:95]
	s_add_u32 m0, s65, 0x43c0
	s_nop 0
	global_load_lds_dwordx4 v150, s[94:95] offset:64
	s_add_u32 s70, s70, 0x80
	s_xor_b32 s71, s70, 0x800
	s_add_u32 s60, s60, 128
	s_addc_u32 s61, s61, 0
	s_add_u32 s62, s62, 128
	s_addc_u32 s63, s63, 0
	s_waitcnt lgkmcnt(0)
	s_barrier
	ds_read_b128 v[108:111], v142 offset:49152
	ds_read_b128 v[112:115], v142 offset:51200
	ds_read_b128 v[116:119], v140 offset:49152
	ds_read_b128 v[120:123], v140 offset:51200
	v_mfma_f32_32x32x16_bf16 v[48:63], v[132:135], v[124:127], v[48:63]
	v_mfma_f32_32x32x16_bf16 v[32:47], v[132:135], v[128:131], v[32:47]
	v_mfma_f32_32x32x16_bf16 v[16:31], v[136:139], v[124:127], v[16:31]
	v_mfma_f32_32x32x16_bf16 v[0:15], v[136:139], v[128:131], v[0:15]
	s_waitcnt lgkmcnt(0)
	v_mfma_f32_32x32x16_bf16 v[48:63], v[116:119], v[108:111], v[48:63]
	v_mfma_f32_32x32x16_bf16 v[32:47], v[116:119], v[112:115], v[32:47]
	v_mfma_f32_32x32x16_bf16 v[16:31], v[120:123], v[108:111], v[16:31]
	v_mfma_f32_32x32x16_bf16 v[0:15], v[120:123], v[112:115], v[0:15]
	ds_read_b128 v[124:127], v143 offset:49152
	ds_read_b128 v[128:131], v143 offset:51200
	ds_read_b128 v[132:135], v141 offset:49152
	ds_read_b128 v[136:139], v141 offset:51200
	s_sub_u32 s69, s69, 1
	s_cmp_lg_u32 s69, 0
	s_cbranch_scc1 .Lp6_kloop
	s_waitcnt vmcnt(0) lgkmcnt(0)
	s_barrier
	ds_read_b128 v[108:111], v142 offset:0
	ds_read_b128 v[112:115], v142 offset:2048
	ds_read_b128 v[116:119], v140 offset:0
	ds_read_b128 v[120:123], v140 offset:2048
	v_mfma_f32_32x32x16_bf16 v[48:63], v[132:135], v[124:127], v[48:63]
	v_mfma_f32_32x32x16_bf16 v[32:47], v[132:135], v[128:131], v[32:47]
	v_mfma_f32_32x32x16_bf16 v[16:31], v[136:139], v[124:127], v[16:31]
	v_mfma_f32_32x32x16_bf16 v[0:15], v[136:139], v[128:131], v[0:15]
	s_add_u32 m0, s64, 0x8000
	s_nop 0
	global_load_lds_dwordx4 v144, s[60:61]
	s_add_u32 m0, s64, 0xc000
	s_nop 0
	global_load_lds_dwordx4 v144, s[62:63]
	s_add_u32 m0, s64, 0x8400
	s_nop 0
	global_load_lds_dwordx4 v145, s[60:61]
	s_add_u32 m0, s64, 0xc400
	s_nop 0
	global_load_lds_dwordx4 v145, s[62:63]
	s_waitcnt lgkmcnt(0)
	v_mfma_f32_32x32x16_bf16 v[48:63], v[116:119], v[108:111], v[48:63]
	v_mfma_f32_32x32x16_bf16 v[32:47], v[116:119], v[112:115], v[32:47]
	v_mfma_f32_32x32x16_bf16 v[16:31], v[120:123], v[108:111], v[16:31]
	v_mfma_f32_32x32x16_bf16 v[0:15], v[120:123], v[112:115], v[0:15]
	ds_read_b128 v[124:127], v143 offset:0
	ds_read_b128 v[128:131], v143 offset:2048
	ds_read_b128 v[132:135], v141 offset:0
	ds_read_b128 v[136:139], v141 offset:2048
	v_xad_u32 v149, s70, v148, v146
	v_xad_u32 v150, s71, v148, v147
	s_add_u32 m0, s65, 0x8000
	s_nop 0
	global_load_lds_dwordx4 v149, s[94:95]
	s_add_u32 m0, s65, 0xbfc0
	s_nop 0
	global_load_lds_dwordx4 v149, s[94:95] offset:64
	s_add_u32 m0, s65, 0x8400
	s_nop 0
	global_load_lds_dwordx4 v150, s[94:95]
	s_add_u32 m0, s65, 0xc3c0
	s_nop 0
	global_load_lds_dwordx4 v150, s[94:95] offset:64
	s_add_u32 s70, s70, 0x80
	s_xor_b32 s71, s70, 0x800
	s_add_u32 s60, s60, 128
	s_addc_u32 s61, s61, 0
	s_add_u32 s62, s62, 128
	s_addc_u32 s63, s63, 0
	s_waitcnt lgkmcnt(0)
	s_barrier
	ds_read_b128 v[108:111], v142 offset:16384
	ds_read_b128 v[112:115], v142 offset:18432
	ds_read_b128 v[116:119], v140 offset:16384
	ds_read_b128 v[120:123], v140 offset:18432
	v_mfma_f32_32x32x16_bf16 v[48:63], v[132:135], v[124:127], v[48:63]
	v_mfma_f32_32x32x16_bf16 v[32:47], v[132:135], v[128:131], v[32:47]
	v_mfma_f32_32x32x16_bf16 v[16:31], v[136:139], v[124:127], v[16:31]
	v_mfma_f32_32x32x16_bf16 v[0:15], v[136:139], v[128:131], v[0:15]
	s_waitcnt lgkmcnt(0)
	v_mfma_f32_32x32x16_bf16 v[48:63], v[116:119], v[108:111], v[48:63]
	v_mfma_f32_32x32x16_bf16 v[32:47], v[116:119], v[112:115], v[32:47]
	v_mfma_f32_32x32x16_bf16 v[16:31], v[120:123], v[108:111], v[16:31]
	v_mfma_f32_32x32x16_bf16 v[0:15], v[120:123], v[112:115], v[0:15]
	ds_read_b128 v[124:127], v143 offset:16384
	ds_read_b128 v[128:131], v143 offset:18432
	ds_read_b128 v[132:135], v141 offset:16384
	ds_read_b128 v[136:139], v141 offset:18432
	s_waitcnt vmcnt(0) lgkmcnt(0)
	s_barrier
	ds_read_b128 v[108:111], v142 offset:32768
	ds_read_b128 v[112:115], v142 offset:34816
	ds_read_b128 v[116:119], v140 offset:32768
	ds_read_b128 v[120:123], v140 offset:34816
	v_mfma_f32_32x32x16_bf16 v[48:63], v[132:135], v[124:127], v[48:63]
	v_mfma_f32_32x32x16_bf16 v[32:47], v[132:135], v[128:131], v[32:47]
	v_mfma_f32_32x32x16_bf16 v[16:31], v[136:139], v[124:127], v[16:31]
	v_mfma_f32_32x32x16_bf16 v[0:15], v[136:139], v[128:131], v[0:15]
	s_waitcnt lgkmcnt(0)
	v_mfma_f32_32x32x16_bf16 v[48:63], v[116:119], v[108:111], v[48:63]
	v_mfma_f32_32x32x16_bf16 v[32:47], v[116:119], v[112:115], v[32:47]
	v_mfma_f32_32x32x16_bf16 v[16:31], v[120:123], v[108:111], v[16:31]
	v_mfma_f32_32x32x16_bf16 v[0:15], v[120:123], v[112:115], v[0:15]
	ds_read_b128 v[124:127], v143 offset:32768
	ds_read_b128 v[128:131], v143 offset:34816
	ds_read_b128 v[132:135], v141 offset:32768
	ds_read_b128 v[136:139], v141 offset:34816
	s_waitcnt lgkmcnt(0)
	s_barrier
	ds_read_b128 v[108:111], v142 offset:49152
	ds_read_b128 v[112:115], v142 offset:51200
	ds_read_b128 v[116:119], v140 offset:49152
	ds_read_b128 v[120:123], v140 offset:51200
	v_mfma_f32_32x32x16_bf16 v[48:63], v[132:135], v[124:127], v[48:63]
	v_mfma_f32_32x32x16_bf16 v[32:47], v[132:135], v[128:131], v[32:47]
	v_mfma_f32_32x32x16_bf16 v[16:31], v[136:139], v[124:127], v[16:31]
	v_mfma_f32_32x32x16_bf16 v[0:15], v[136:139], v[128:131], v[0:15]
	s_waitcnt lgkmcnt(0)
	v_mfma_f32_32x32x16_bf16 v[48:63], v[116:119], v[108:111], v[48:63]
	v_mfma_f32_32x32x16_bf16 v[32:47], v[116:119], v[112:115], v[32:47]
	v_mfma_f32_32x32x16_bf16 v[16:31], v[120:123], v[108:111], v[16:31]
	v_mfma_f32_32x32x16_bf16 v[0:15], v[120:123], v[112:115], v[0:15]
	ds_read_b128 v[124:127], v143 offset:49152
	ds_read_b128 v[128:131], v143 offset:51200
	ds_read_b128 v[132:135], v141 offset:49152
	ds_read_b128 v[136:139], v141 offset:51200
	s_waitcnt lgkmcnt(0)
	v_mfma_f32_32x32x16_bf16 v[48:63], v[132:135], v[124:127], v[48:63]
	v_mfma_f32_32x32x16_bf16 v[32:47], v[132:135], v[128:131], v[32:47]
	v_mfma_f32_32x32x16_bf16 v[16:31], v[136:139], v[124:127], v[16:31]
	v_mfma_f32_32x32x16_bf16 v[0:15], v[136:139], v[128:131], v[0:15]
